# k16 plus: in 6-DMA load phases issue the LDS-DMA loads before the 8 fragment ds_reads
# baseline (speedup 1.0000x reference)
;     __device__ bool next(int i, Unit& u) const { if (i >= 2) return false; const int x = c & 7, j = c >> 3; u.pm = 32 * i + 4 * x + (j & 3); u.pn = j >> 2; return true; }
; #define PG8_STAGE(bufoff, gbase, voff) do { _Pragma("unroll") for (int _i = 0; _i < 2; ++_i) \
;         __builtin_amdgcn_global_load_lds((const unsigned*)((const char*)(gbase) + (voff)[_i]), (LAS unsigned*)(lds + (bufoff) + ldsw + _i * 8192), 16, 0, 0); } while (0)
; #define PG8_LDA(dst, b, h) do { _Pragma("unroll") for (int m = 0; m < 4; ++m) _Pragma("unroll") for (int k = 0; k < 2; ++k) dst[m][k] = *(const LAS bf16x8*)(lds + PG8_SA(b, h) + aoff + m * 2048 + k * 1024); } while (0)
; #define PG8_LDB(dst, b, h) do { _Pragma("unroll") for (int n = 0; n < 2; ++n) _Pragma("unroll") for (int k = 0; k < 2; ++k) dst[n][k] = *(const LAS bf16x8*)(lds + PG8_SB(b, h) + boff + n * 2048 + k * 1024); } while (0)
; #define PG8_WAIT_V(n) asm volatile("s_waitcnt vmcnt(" #n ")" ::: "memory")
; #define PG8_WAIT_L(n) asm volatile("s_waitcnt lgkmcnt(" #n ")" ::: "memory")
; #define PG8_BAR __builtin_amdgcn_s_barrier()
; template <class Epi, class Sched, bool ALIGN_EPI = true>
; __device__ __forceinline__ void gemm_phase(LAS unsigned char* lds, const Gemm g, const Sched& S, const Epi& E) {
;     ...
;         const bool has_next = S.next(ui + 1, nxt);
;         const char* nA = has_next ? (const char*)g.A + ((size_t)nxt.pm * BM * g.lda + (size_t)nxt.pn * g.a_pn_off) * 2 : cA; const char* nB = has_next ? (const char*)g.Bt + (size_t)nxt.pn * BM * g.ldb * 2 : cB;
;         for (int t = 0; t < nt; t += 2) {
;             const bool last = (t == nt - 2);
;             const char* a1 = cA + (size_t)(t + 1) * kstep;
;             const char* a2 = last ? nA : cA + (size_t)(t + 2) * kstep; const char* b2 = last ? nB : cB + (size_t)(t + 2) * kstep;
;             const char* a3 = a2 + kstep; const char* b3 = b2 + kstep;
;             PG8_LDB(B0, 0, 0); PG8_LDB(B1, 0, 1); PG8_SCHED; PG8_LDA(At, 0, 0); PG8_STAGE(PG8_SA(1, 1), a1 + hA, voffA);
;             PG8_WAIT_V(8); PG8_WAIT_L(0); PG8_BAR; PG8_MMA(0, 0, At, B0); PG8_MMA(0, 1, At, B1); PG8_BAR; PG8_SCHED;
;             PG8_LDA(At, 0, 1); PG8_STAGE(PG8_SB(0, 0), b2, voffB); PG8_STAGE(PG8_SB(0, 1), b2 + hB, voffB); PG8_STAGE(PG8_SA(0, 0), a2, voffA);
;             PG8_WAIT_V(8); PG8_WAIT_L(0); PG8_BAR; PG8_MMA(1, 0, At, B0); PG8_MMA(1, 1, At, B1); PG8_BAR; PG8_SCHED;
.LBB0_76:
	s_ashr_i32 s15, s14, 31
	s_lshl_b64 s[18:19], s[14:15], 20
	s_add_u32 s38, s46, s18
	s_addc_u32 s39, s47, s19
	s_and_b64 s[18:19], s[4:5], exec
	s_cselect_b32 s15, s39, s7
	s_cselect_b32 s17, s38, s6
	s_ashr_i32 s13, s12, 31
	s_lshl_b64 s[18:19], s[12:13], 20
	s_add_u32 s40, s53, s18
	s_addc_u32 s41, s58, s19
	s_and_b64 s[18:19], s[4:5], exec
	s_cselect_b32 s13, s41, s43
	s_cselect_b32 s18, s40, s42
	s_add_u32 s6, s6, 0x80080
	s_addc_u32 s7, s7, 0
	s_add_u32 s19, s42, 0x100
	s_addc_u32 s24, s43, 0
	s_mov_b32 s25, -2
	s_add_u32 s26, s6, 0xfff80080
	s_addc_u32 s27, s7, -1
	s_add_i32 s30, 0, 0x10000
	s_cmp_eq_u32 s25, 28
	s_cselect_b32 s45, s15, s27
	s_cselect_b32 s44, s17, s26
	s_cselect_b32 s43, s13, s24
	s_cselect_b32 s42, s18, s19
	s_add_i32 s31, 0, 0x14000
	v_add_u32_e32 v144, s30, v166
	v_add_u32_e32 v156, s31, v166
	ds_read_b128 v[132:135], v144
	ds_read_b128 v[136:139], v144 offset:1024
	ds_read_b128 v[140:143], v144 offset:2048
	ds_read_b128 v[144:147], v144 offset:3072
	ds_read_b128 v[170:173], v156
	ds_read_b128 v[174:177], v156 offset:1024
	ds_read_b128 v[178:181], v156 offset:2048
	ds_read_b128 v[182:185], v156 offset:3072
	v_lshl_add_u64 v[156:157], s[6:7], 0, v[152:153]
	s_add_i32 m0, s60, 0xc000
	ds_read_b128 v[186:189], v168
	ds_read_b128 v[190:193], v168 offset:1024
	ds_read_b128 v[194:197], v168 offset:2048
	ds_read_b128 v[204:207], v168 offset:3072
	ds_read_b128 v[208:211], v168 offset:4096
	ds_read_b128 v[212:215], v168 offset:5120
	ds_read_b128 v[216:219], v168 offset:6144
	ds_read_b128 v[220:223], v168 offset:7168
	global_load_lds_dwordx4 v[156:157], off
	v_lshl_add_u64 v[156:157], s[6:7], 0, v[154:155]
	s_add_i32 m0, s60, 0xe000
	s_nop 0
	global_load_lds_dwordx4 v[156:157], off
	s_waitcnt vmcnt(8)
	s_waitcnt lgkmcnt(0)
	s_barrier
	s_setprio 1
	s_waitcnt lgkmcnt(0)
	v_mfma_f32_16x16x32_bf16 v[128:131], v[132:135], v[186:189], 0
	v_mfma_f32_16x16x32_bf16 v[128:131], v[136:139], v[190:193], v[128:131]
	v_mfma_f32_16x16x32_bf16 v[124:127], v[140:143], v[186:189], 0
	v_mfma_f32_16x16x32_bf16 v[124:127], v[144:147], v[190:193], v[124:127]
	v_mfma_f32_16x16x32_bf16 v[116:119], v[132:135], v[194:197], 0
	v_mfma_f32_16x16x32_bf16 v[116:119], v[136:139], v[204:207], v[116:119]
	v_mfma_f32_16x16x32_bf16 v[112:115], v[140:143], v[194:197], 0
	v_mfma_f32_16x16x32_bf16 v[112:115], v[144:147], v[204:207], v[112:115]
	v_mfma_f32_16x16x32_bf16 v[104:107], v[132:135], v[208:211], 0
	v_mfma_f32_16x16x32_bf16 v[104:107], v[136:139], v[212:215], v[104:107]
	v_mfma_f32_16x16x32_bf16 v[96:99], v[140:143], v[208:211], 0
	v_mfma_f32_16x16x32_bf16 v[96:99], v[144:147], v[212:215], v[96:99]
	v_mfma_f32_16x16x32_bf16 v[88:91], v[132:135], v[216:219], 0
	v_mfma_f32_16x16x32_bf16 v[88:91], v[136:139], v[220:223], v[88:91]
	v_mfma_f32_16x16x32_bf16 v[80:83], v[140:143], v[216:219], 0
	v_mfma_f32_16x16x32_bf16 v[80:83], v[144:147], v[220:223], v[80:83]
	s_setprio 0
	s_setprio 1
	v_mfma_f32_16x16x32_bf16 v[120:123], v[170:173], v[186:189], 0
	v_mfma_f32_16x16x32_bf16 v[120:123], v[174:177], v[190:193], v[120:123]
	v_mfma_f32_16x16x32_bf16 v[108:111], v[178:181], v[186:189], 0
	v_mfma_f32_16x16x32_bf16 v[108:111], v[182:185], v[190:193], v[108:111]
	v_mfma_f32_16x16x32_bf16 v[100:103], v[170:173], v[194:197], 0
	v_mfma_f32_16x16x32_bf16 v[100:103], v[174:177], v[204:207], v[100:103]
	v_mfma_f32_16x16x32_bf16 v[92:95], v[178:181], v[194:197], 0
	v_mfma_f32_16x16x32_bf16 v[92:95], v[182:185], v[204:207], v[92:95]
	v_mfma_f32_16x16x32_bf16 v[84:87], v[170:173], v[208:211], 0
	v_mfma_f32_16x16x32_bf16 v[84:87], v[174:177], v[212:215], v[84:87]
	v_mfma_f32_16x16x32_bf16 v[76:79], v[178:181], v[208:211], 0
	v_mfma_f32_16x16x32_bf16 v[76:79], v[182:185], v[212:215], v[76:79]
	v_mfma_f32_16x16x32_bf16 v[72:75], v[170:173], v[216:219], 0
	v_mfma_f32_16x16x32_bf16 v[72:75], v[174:177], v[220:223], v[72:75]
	s_setprio 2
	s_barrier
	v_mfma_f32_16x16x32_bf16 v[68:71], v[178:181], v[216:219], 0
	v_mfma_f32_16x16x32_bf16 v[68:71], v[182:185], v[220:223], v[68:71]
	s_setprio 0
	s_add_i32 s26, s30, s59
	v_lshl_add_u64 v[156:157], s[42:43], 0, v[2:3]
	s_mov_b32 m0, s26
	s_nop 0
	global_load_lds_dwordx4 v[156:157], off
	s_add_i32 m0, s26, 0x2000
	s_add_u32 s26, s42, 0x80000
	v_lshl_add_u64 v[164:165], s[42:43], 0, v[0:1]
	s_addc_u32 s27, s43, 0
	s_add_i32 s30, s31, s59
	global_load_lds_dwordx4 v[164:165], off
	v_lshl_add_u64 v[224:225], s[26:27], 0, v[2:3]
	s_mov_b32 m0, s30
	v_lshl_add_u64 v[226:227], s[44:45], 0, v[148:149]
	global_load_lds_dwordx4 v[224:225], off
	v_lshl_add_u64 v[224:225], s[26:27], 0, v[0:1]
	s_add_i32 m0, s30, 0x2000
	s_nop 0
	global_load_lds_dwordx4 v[224:225], off
	v_lshl_add_u64 v[224:225], s[44:45], 0, v[150:151]
	s_mov_b32 m0, s60
	s_nop 0
	global_load_lds_dwordx4 v[224:225], off
	s_mov_b32 m0, s61
	s_nop 0
	global_load_lds_dwordx4 v[226:227], off
	ds_read_b128 v[186:189], v168 offset:16384
	ds_read_b128 v[190:193], v168 offset:17408
	ds_read_b128 v[194:197], v168 offset:18432
	ds_read_b128 v[204:207], v168 offset:19456
	ds_read_b128 v[208:211], v168 offset:20480
	ds_read_b128 v[212:215], v168 offset:21504
	ds_read_b128 v[216:219], v168 offset:22528
	ds_read_b128 v[220:223], v168 offset:23552
	s_waitcnt vmcnt(8)
	s_waitcnt lgkmcnt(0)
	s_barrier
; #define PG8_STAGE(bufoff, gbase, voff) do { _Pragma("unroll") for (int _i = 0; _i < 2; ++_i) \
;         __builtin_amdgcn_global_load_lds((const unsigned*)((const char*)(gbase) + (voff)[_i]), (LAS unsigned*)(lds + (bufoff) + ldsw + _i * 8192), 16, 0, 0); } while (0)
; #define PG8_LDA(dst, b, h) do { _Pragma("unroll") for (int m = 0; m < 4; ++m) _Pragma("unroll") for (int k = 0; k < 2; ++k) dst[m][k] = *(const LAS bf16x8*)(lds + PG8_SA(b, h) + aoff + m * 2048 + k * 1024); } while (0)
; #define PG8_LDB(dst, b, h) do { _Pragma("unroll") for (int n = 0; n < 2; ++n) _Pragma("unroll") for (int k = 0; k < 2; ++k) dst[n][k] = *(const LAS bf16x8*)(lds + PG8_SB(b, h) + boff + n * 2048 + k * 1024); } while (0)
; #define PG8_MMA(ai, bj, At, Bt) do { __builtin_amdgcn_s_setprio(1); _Pragma("unroll") for (int m = 0; m < 4; ++m) _Pragma("unroll") for (int n = 0; n < 2; ++n) _Pragma("unroll") for (int k = 0; k < 2; ++k) \
;         acc[ai][bj][m][n] = __builtin_amdgcn_mfma_f32_16x16x32_bf16(Bt[n][k], At[m][k], acc[ai][bj][m][n], 0, 0, 0); __builtin_amdgcn_s_setprio(0); } while (0)
; #define PG8_WAIT_V(n) asm volatile("s_waitcnt vmcnt(" #n ")" ::: "memory")
; #define PG8_WAIT_L(n) asm volatile("s_waitcnt lgkmcnt(" #n ")" ::: "memory")
; #define PG8_BAR __builtin_amdgcn_s_barrier()
; #define PG8_SCHED __builtin_amdgcn_sched_barrier(0)
; template <class Epi, class Sched, bool ALIGN_EPI = true>
; __device__ __forceinline__ void gemm_phase(LAS unsigned char* lds, const Gemm g, const Sched& S, const Epi& E) {
;     ...
;             PG8_WAIT_V(8); PG8_WAIT_L(0); PG8_BAR; PG8_MMA(1, 0, At, B0); PG8_MMA(1, 1, At, B1); PG8_BAR; PG8_SCHED;
;             PG8_LDB(B0, 1, 0); PG8_LDB(B1, 1, 1); PG8_SCHED; PG8_LDA(At, 1, 0); PG8_STAGE(PG8_SA(0, 1), a2 + hA, voffA);
;             PG8_WAIT_V(8); PG8_WAIT_L(0); PG8_BAR; PG8_MMA(0, 0, At, B0); PG8_MMA(0, 1, At, B1); PG8_BAR; PG8_SCHED;
;             PG8_LDA(At, 1, 1); PG8_STAGE(PG8_SB(1, 0), b3, voffB); PG8_STAGE(PG8_SB(1, 1), b3 + hB, voffB); PG8_STAGE(PG8_SA(1, 0), a3, voffA);
;             PG8_WAIT_V(8); PG8_WAIT_L(0); PG8_BAR; PG8_MMA(1, 0, At, B0); PG8_MMA(1, 1, At, B1); PG8_BAR; PG8_SCHED;
	s_setprio 1
	s_waitcnt lgkmcnt(0)
	v_mfma_f32_16x16x32_bf16 v[64:67], v[132:135], v[186:189], 0
	v_mfma_f32_16x16x32_bf16 v[64:67], v[136:139], v[190:193], v[64:67]
	v_mfma_f32_16x16x32_bf16 v[60:63], v[140:143], v[186:189], 0
	v_mfma_f32_16x16x32_bf16 v[60:63], v[144:147], v[190:193], v[60:63]
	v_mfma_f32_16x16x32_bf16 v[56:59], v[132:135], v[194:197], 0
	v_mfma_f32_16x16x32_bf16 v[56:59], v[136:139], v[204:207], v[56:59]
	v_mfma_f32_16x16x32_bf16 v[48:51], v[140:143], v[194:197], 0
	v_mfma_f32_16x16x32_bf16 v[48:51], v[144:147], v[204:207], v[48:51]
	v_mfma_f32_16x16x32_bf16 v[40:43], v[132:135], v[208:211], 0
	v_mfma_f32_16x16x32_bf16 v[40:43], v[136:139], v[212:215], v[40:43]
	v_mfma_f32_16x16x32_bf16 v[32:35], v[140:143], v[208:211], 0
	v_mfma_f32_16x16x32_bf16 v[32:35], v[144:147], v[212:215], v[32:35]
	v_mfma_f32_16x16x32_bf16 v[24:27], v[132:135], v[216:219], 0
	v_mfma_f32_16x16x32_bf16 v[24:27], v[136:139], v[220:223], v[24:27]
	v_mfma_f32_16x16x32_bf16 v[16:19], v[140:143], v[216:219], 0
	v_mfma_f32_16x16x32_bf16 v[16:19], v[144:147], v[220:223], v[16:19]
	s_setprio 0
	s_setprio 1
	v_mfma_f32_16x16x32_bf16 v[52:55], v[170:173], v[186:189], 0
	v_mfma_f32_16x16x32_bf16 v[52:55], v[174:177], v[190:193], v[52:55]
	v_mfma_f32_16x16x32_bf16 v[44:47], v[178:181], v[186:189], 0
	v_mfma_f32_16x16x32_bf16 v[44:47], v[182:185], v[190:193], v[44:47]
	v_mfma_f32_16x16x32_bf16 v[36:39], v[170:173], v[194:197], 0
	v_mfma_f32_16x16x32_bf16 v[36:39], v[174:177], v[204:207], v[36:39]
	v_mfma_f32_16x16x32_bf16 v[28:31], v[178:181], v[194:197], 0
	v_mfma_f32_16x16x32_bf16 v[28:31], v[182:185], v[204:207], v[28:31]
	v_mfma_f32_16x16x32_bf16 v[20:23], v[170:173], v[208:211], 0
	v_mfma_f32_16x16x32_bf16 v[20:23], v[174:177], v[212:215], v[20:23]
	v_mfma_f32_16x16x32_bf16 v[12:15], v[178:181], v[208:211], 0
	v_mfma_f32_16x16x32_bf16 v[12:15], v[182:185], v[212:215], v[12:15]
	v_mfma_f32_16x16x32_bf16 v[8:11], v[170:173], v[216:219], 0
	v_mfma_f32_16x16x32_bf16 v[8:11], v[174:177], v[220:223], v[8:11]
	s_setprio 2
	s_barrier
	v_mfma_f32_16x16x32_bf16 v[4:7], v[178:181], v[216:219], 0
	v_mfma_f32_16x16x32_bf16 v[4:7], v[182:185], v[220:223], v[4:7]
	s_setprio 0
	s_add_i32 s30, 0, 0x18000
	s_add_i32 s31, 0, 0x1c000
	v_add_u32_e32 v144, s30, v166
	v_add_u32_e32 v160, s31, v166
	ds_read_b128 v[132:135], v144
	ds_read_b128 v[136:139], v144 offset:1024
	ds_read_b128 v[140:143], v144 offset:2048
	ds_read_b128 v[144:147], v144 offset:3072
	ds_read_b128 v[170:173], v160
	ds_read_b128 v[174:177], v160 offset:1024
	ds_read_b128 v[178:181], v160 offset:2048
	ds_read_b128 v[182:185], v160 offset:3072
	s_add_u32 s26, s44, 0x80000
	s_addc_u32 s27, s45, 0
	s_mov_b32 m0, s62
	v_lshl_add_u64 v[228:229], s[26:27], 0, v[150:151]
	ds_read_b128 v[186:189], v168 offset:32768
	ds_read_b128 v[190:193], v168 offset:33792
	ds_read_b128 v[194:197], v168 offset:34816
	ds_read_b128 v[204:207], v168 offset:35840
	ds_read_b128 v[208:211], v168 offset:36864
	ds_read_b128 v[212:215], v168 offset:37888
	ds_read_b128 v[216:219], v168 offset:38912
	ds_read_b128 v[220:223], v168 offset:39936
	global_load_lds_dwordx4 v[228:229], off
	v_lshl_add_u64 v[228:229], s[26:27], 0, v[148:149]
	s_mov_b32 m0, s63
	s_nop 0
	global_load_lds_dwordx4 v[228:229], off
	s_waitcnt vmcnt(8)
	s_waitcnt lgkmcnt(0)
	s_barrier
	s_setprio 1
	s_waitcnt lgkmcnt(0)
	v_mfma_f32_16x16x32_bf16 v[128:131], v[132:135], v[186:189], v[128:131]
	v_mfma_f32_16x16x32_bf16 v[128:131], v[136:139], v[190:193], v[128:131]
	v_mfma_f32_16x16x32_bf16 v[124:127], v[140:143], v[186:189], v[124:127]
	v_mfma_f32_16x16x32_bf16 v[124:127], v[144:147], v[190:193], v[124:127]
	v_mfma_f32_16x16x32_bf16 v[116:119], v[132:135], v[194:197], v[116:119]
	v_mfma_f32_16x16x32_bf16 v[116:119], v[136:139], v[204:207], v[116:119]
	v_mfma_f32_16x16x32_bf16 v[112:115], v[140:143], v[194:197], v[112:115]
	v_mfma_f32_16x16x32_bf16 v[112:115], v[144:147], v[204:207], v[112:115]
	v_mfma_f32_16x16x32_bf16 v[104:107], v[132:135], v[208:211], v[104:107]
	v_mfma_f32_16x16x32_bf16 v[104:107], v[136:139], v[212:215], v[104:107]
	v_mfma_f32_16x16x32_bf16 v[96:99], v[140:143], v[208:211], v[96:99]
	v_mfma_f32_16x16x32_bf16 v[96:99], v[144:147], v[212:215], v[96:99]
	v_mfma_f32_16x16x32_bf16 v[88:91], v[132:135], v[216:219], v[88:91]
	v_mfma_f32_16x16x32_bf16 v[88:91], v[136:139], v[220:223], v[88:91]
	v_mfma_f32_16x16x32_bf16 v[80:83], v[140:143], v[216:219], v[80:83]
	v_mfma_f32_16x16x32_bf16 v[80:83], v[144:147], v[220:223], v[80:83]
	s_setprio 0
	s_setprio 1
	v_mfma_f32_16x16x32_bf16 v[120:123], v[170:173], v[186:189], v[120:123]
	v_mfma_f32_16x16x32_bf16 v[120:123], v[174:177], v[190:193], v[120:123]
	v_mfma_f32_16x16x32_bf16 v[108:111], v[178:181], v[186:189], v[108:111]
	v_mfma_f32_16x16x32_bf16 v[108:111], v[182:185], v[190:193], v[108:111]
	v_mfma_f32_16x16x32_bf16 v[100:103], v[170:173], v[194:197], v[100:103]
	v_mfma_f32_16x16x32_bf16 v[100:103], v[174:177], v[204:207], v[100:103]
	v_mfma_f32_16x16x32_bf16 v[92:95], v[178:181], v[194:197], v[92:95]
	v_mfma_f32_16x16x32_bf16 v[92:95], v[182:185], v[204:207], v[92:95]
	v_mfma_f32_16x16x32_bf16 v[84:87], v[170:173], v[208:211], v[84:87]
	v_mfma_f32_16x16x32_bf16 v[84:87], v[174:177], v[212:215], v[84:87]
	v_mfma_f32_16x16x32_bf16 v[76:79], v[178:181], v[208:211], v[76:79]
	v_mfma_f32_16x16x32_bf16 v[76:79], v[182:185], v[212:215], v[76:79]
	v_mfma_f32_16x16x32_bf16 v[72:75], v[170:173], v[216:219], v[72:75]
	v_mfma_f32_16x16x32_bf16 v[72:75], v[174:177], v[220:223], v[72:75]
	s_setprio 2
	s_barrier
; #define PG8_STAGE(bufoff, gbase, voff) do { _Pragma("unroll") for (int _i = 0; _i < 2; ++_i) \
;         __builtin_amdgcn_global_load_lds((const unsigned*)((const char*)(gbase) + (voff)[_i]), (LAS unsigned*)(lds + (bufoff) + ldsw + _i * 8192), 16, 0, 0); } while (0)
; #define PG8_LDA(dst, b, h) do { _Pragma("unroll") for (int m = 0; m < 4; ++m) _Pragma("unroll") for (int k = 0; k < 2; ++k) dst[m][k] = *(const LAS bf16x8*)(lds + PG8_SA(b, h) + aoff + m * 2048 + k * 1024); } while (0)
; #define PG8_LDB(dst, b, h) do { _Pragma("unroll") for (int n = 0; n < 2; ++n) _Pragma("unroll") for (int k = 0; k < 2; ++k) dst[n][k] = *(const LAS bf16x8*)(lds + PG8_SB(b, h) + boff + n * 2048 + k * 1024); } while (0)
; #define PG8_WAIT_V(n) asm volatile("s_waitcnt vmcnt(" #n ")" ::: "memory")
; #define PG8_WAIT_L(n) asm volatile("s_waitcnt lgkmcnt(" #n ")" ::: "memory")
; #define PG8_BAR __builtin_amdgcn_s_barrier()
; template <class Epi, class Sched, bool ALIGN_EPI = true>
; __device__ __forceinline__ void gemm_phase(LAS unsigned char* lds, const Gemm g, const Sched& S, const Epi& E) {
;     ...
;             const char* a1 = cA + (size_t)(t + 1) * kstep;
;             const char* a2 = last ? nA : cA + (size_t)(t + 2) * kstep; const char* b2 = last ? nB : cB + (size_t)(t + 2) * kstep;
;             const char* a3 = a2 + kstep; const char* b3 = b2 + kstep;
;             PG8_LDB(B0, 0, 0); PG8_LDB(B1, 0, 1); PG8_SCHED; PG8_LDA(At, 0, 0); PG8_STAGE(PG8_SA(1, 1), a1 + hA, voffA);
;             PG8_WAIT_V(8); PG8_WAIT_L(0); PG8_BAR; PG8_MMA(0, 0, At, B0); PG8_MMA(0, 1, At, B1); PG8_BAR; PG8_SCHED;
;             PG8_LDA(At, 0, 1); PG8_STAGE(PG8_SB(0, 0), b2, voffB); PG8_STAGE(PG8_SB(0, 1), b2 + hB, voffB); PG8_STAGE(PG8_SA(0, 0), a2, voffA);
;             PG8_WAIT_V(8); PG8_WAIT_L(0); PG8_BAR; PG8_MMA(1, 0, At, B0); PG8_MMA(1, 1, At, B1); PG8_BAR; PG8_SCHED;
;             PG8_LDB(B0, 1, 0); PG8_LDB(B1, 1, 1); PG8_SCHED; PG8_LDA(At, 1, 0); PG8_STAGE(PG8_SA(0, 1), a2 + hA, voffA);
;             PG8_WAIT_V(8); PG8_WAIT_L(0); PG8_BAR; PG8_MMA(0, 0, At, B0); PG8_MMA(0, 1, At, B1); PG8_BAR; PG8_SCHED;
;             PG8_LDA(At, 1, 1); PG8_STAGE(PG8_SB(1, 0), b3, voffB); PG8_STAGE(PG8_SB(1, 1), b3 + hB, voffB); PG8_STAGE(PG8_SA(1, 0), a3, voffA);
;             PG8_WAIT_V(8); PG8_WAIT_L(0); PG8_BAR; PG8_MMA(1, 0, At, B0); PG8_MMA(1, 1, At, B1); PG8_BAR; PG8_SCHED;
	v_mfma_f32_16x16x32_bf16 v[68:71], v[178:181], v[216:219], v[68:71]
	v_mfma_f32_16x16x32_bf16 v[68:71], v[182:185], v[220:223], v[68:71]
	s_setprio 0
	s_add_i32 s26, s30, s59
	v_lshl_add_u64 v[156:157], v[156:157], 0, s[86:87]
	s_mov_b32 m0, s26
	s_nop 0
	global_load_lds_dwordx4 v[156:157], off
	s_add_i32 m0, s26, 0x2000
	s_add_u32 s26, s42, 0x80080
	v_lshl_add_u64 v[156:157], v[164:165], 0, s[86:87]
	s_addc_u32 s27, s43, 0
	s_add_i32 s30, s31, s59
	global_load_lds_dwordx4 v[156:157], off
	v_lshl_add_u64 v[156:157], s[26:27], 0, v[2:3]
	s_mov_b32 m0, s30
	s_nop 0
	global_load_lds_dwordx4 v[156:157], off
	v_lshl_add_u64 v[156:157], s[26:27], 0, v[0:1]
	s_add_i32 m0, s30, 0x2000
	s_nop 0
	global_load_lds_dwordx4 v[156:157], off
	v_lshl_add_u64 v[156:157], v[224:225], 0, s[86:87]
	s_mov_b32 m0, s64
	s_nop 0
	global_load_lds_dwordx4 v[156:157], off
	v_lshl_add_u64 v[156:157], v[226:227], 0, s[86:87]
	s_mov_b32 m0, s65
	s_nop 0
	global_load_lds_dwordx4 v[156:157], off
	ds_read_b128 v[186:189], v168 offset:49152
	ds_read_b128 v[190:193], v168 offset:50176
	ds_read_b128 v[194:197], v168 offset:51200
	ds_read_b128 v[204:207], v168 offset:52224
	ds_read_b128 v[208:211], v168 offset:53248
	ds_read_b128 v[212:215], v168 offset:54272
	ds_read_b128 v[216:219], v168 offset:55296
	ds_read_b128 v[220:223], v168 offset:56320
	s_waitcnt vmcnt(8)
	s_waitcnt lgkmcnt(0)
	s_barrier
	s_setprio 1
	s_waitcnt lgkmcnt(0)
	v_mfma_f32_16x16x32_bf16 v[64:67], v[132:135], v[186:189], v[64:67]
	v_mfma_f32_16x16x32_bf16 v[64:67], v[136:139], v[190:193], v[64:67]
	v_mfma_f32_16x16x32_bf16 v[60:63], v[140:143], v[186:189], v[60:63]
	v_mfma_f32_16x16x32_bf16 v[60:63], v[144:147], v[190:193], v[60:63]
	v_mfma_f32_16x16x32_bf16 v[56:59], v[132:135], v[194:197], v[56:59]
	v_mfma_f32_16x16x32_bf16 v[56:59], v[136:139], v[204:207], v[56:59]
	v_mfma_f32_16x16x32_bf16 v[48:51], v[140:143], v[194:197], v[48:51]
	v_mfma_f32_16x16x32_bf16 v[48:51], v[144:147], v[204:207], v[48:51]
	v_mfma_f32_16x16x32_bf16 v[40:43], v[132:135], v[208:211], v[40:43]
	v_mfma_f32_16x16x32_bf16 v[40:43], v[136:139], v[212:215], v[40:43]
	v_mfma_f32_16x16x32_bf16 v[32:35], v[140:143], v[208:211], v[32:35]
	v_mfma_f32_16x16x32_bf16 v[32:35], v[144:147], v[212:215], v[32:35]
	v_mfma_f32_16x16x32_bf16 v[24:27], v[132:135], v[216:219], v[24:27]
	v_mfma_f32_16x16x32_bf16 v[24:27], v[136:139], v[220:223], v[24:27]
	v_mfma_f32_16x16x32_bf16 v[16:19], v[140:143], v[216:219], v[16:19]
	v_mfma_f32_16x16x32_bf16 v[16:19], v[144:147], v[220:223], v[16:19]
	s_setprio 0
	s_setprio 1
	v_mfma_f32_16x16x32_bf16 v[52:55], v[170:173], v[186:189], v[52:55]
	v_mfma_f32_16x16x32_bf16 v[52:55], v[174:177], v[190:193], v[52:55]
	v_mfma_f32_16x16x32_bf16 v[44:47], v[178:181], v[186:189], v[44:47]
	v_mfma_f32_16x16x32_bf16 v[44:47], v[182:185], v[190:193], v[44:47]
	v_mfma_f32_16x16x32_bf16 v[36:39], v[170:173], v[194:197], v[36:39]
	v_mfma_f32_16x16x32_bf16 v[36:39], v[174:177], v[204:207], v[36:39]
	v_mfma_f32_16x16x32_bf16 v[28:31], v[178:181], v[194:197], v[28:31]
	v_mfma_f32_16x16x32_bf16 v[28:31], v[182:185], v[204:207], v[28:31]
	v_mfma_f32_16x16x32_bf16 v[20:23], v[170:173], v[208:211], v[20:23]
	v_mfma_f32_16x16x32_bf16 v[20:23], v[174:177], v[212:215], v[20:23]
	v_mfma_f32_16x16x32_bf16 v[12:15], v[178:181], v[208:211], v[12:15]
	v_mfma_f32_16x16x32_bf16 v[12:15], v[182:185], v[212:215], v[12:15]
	v_mfma_f32_16x16x32_bf16 v[8:11], v[170:173], v[216:219], v[8:11]
	v_mfma_f32_16x16x32_bf16 v[8:11], v[174:177], v[220:223], v[8:11]
	s_setprio 2
	s_barrier
	v_mfma_f32_16x16x32_bf16 v[4:7], v[178:181], v[216:219], v[4:7]
	v_mfma_f32_16x16x32_bf16 v[4:7], v[182:185], v[220:223], v[4:7]
	s_setprio 0
	s_add_i32 s25, s25, 2
	s_add_u32 s6, s6, 0x100
	s_addc_u32 s7, s7, 0
	s_add_u32 s19, s19, 0x100
	s_addc_u32 s24, s24, 0
	s_cmp_gt_u32 s25, 29
	s_cbranch_scc1 .Lpeel_exit_77
.LBB0_77:
	s_add_u32 s26, s6, 0xfff80080
	s_addc_u32 s27, s7, -1
	s_add_i32 s30, 0, 0x10000
	s_cmp_eq_u32 s25, 28
	s_cselect_b32 s45, s15, s27
	s_cselect_b32 s44, s17, s26
	s_cselect_b32 s43, s13, s24
	s_cselect_b32 s42, s18, s19
	s_add_i32 s31, 0, 0x14000
	v_add_u32_e32 v144, s30, v166
	v_add_u32_e32 v156, s31, v166
	ds_read_b128 v[132:135], v144
	ds_read_b128 v[136:139], v144 offset:1024
	ds_read_b128 v[140:143], v144 offset:2048
	ds_read_b128 v[144:147], v144 offset:3072
	ds_read_b128 v[170:173], v156
	ds_read_b128 v[174:177], v156 offset:1024
	ds_read_b128 v[178:181], v156 offset:2048
	ds_read_b128 v[182:185], v156 offset:3072
	v_lshl_add_u64 v[156:157], s[6:7], 0, v[152:153]
	s_add_i32 m0, s60, 0xc000
	ds_read_b128 v[186:189], v168
	ds_read_b128 v[190:193], v168 offset:1024
	ds_read_b128 v[194:197], v168 offset:2048
	ds_read_b128 v[204:207], v168 offset:3072
	ds_read_b128 v[208:211], v168 offset:4096
	ds_read_b128 v[212:215], v168 offset:5120
	ds_read_b128 v[216:219], v168 offset:6144
	ds_read_b128 v[220:223], v168 offset:7168
	global_load_lds_dwordx4 v[156:157], off
	v_lshl_add_u64 v[156:157], s[6:7], 0, v[154:155]
	s_add_i32 m0, s60, 0xe000
	s_nop 0
	global_load_lds_dwordx4 v[156:157], off
	s_waitcnt vmcnt(8)
	s_waitcnt lgkmcnt(0)
	s_barrier
; #define PG8_STAGE(bufoff, gbase, voff) do { _Pragma("unroll") for (int _i = 0; _i < 2; ++_i) \
;         __builtin_amdgcn_global_load_lds((const unsigned*)((const char*)(gbase) + (voff)[_i]), (LAS unsigned*)(lds + (bufoff) + ldsw + _i * 8192), 16, 0, 0); } while (0)
; #define PG8_LDA(dst, b, h) do { _Pragma("unroll") for (int m = 0; m < 4; ++m) _Pragma("unroll") for (int k = 0; k < 2; ++k) dst[m][k] = *(const LAS bf16x8*)(lds + PG8_SA(b, h) + aoff + m * 2048 + k * 1024); } while (0)
; #define PG8_LDB(dst, b, h) do { _Pragma("unroll") for (int n = 0; n < 2; ++n) _Pragma("unroll") for (int k = 0; k < 2; ++k) dst[n][k] = *(const LAS bf16x8*)(lds + PG8_SB(b, h) + boff + n * 2048 + k * 1024); } while (0)
; #define PG8_MMA(ai, bj, At, Bt) do { __builtin_amdgcn_s_setprio(1); _Pragma("unroll") for (int m = 0; m < 4; ++m) _Pragma("unroll") for (int n = 0; n < 2; ++n) _Pragma("unroll") for (int k = 0; k < 2; ++k) \
;         acc[ai][bj][m][n] = __builtin_amdgcn_mfma_f32_16x16x32_bf16(Bt[n][k], At[m][k], acc[ai][bj][m][n], 0, 0, 0); __builtin_amdgcn_s_setprio(0); } while (0)
; #define PG8_WAIT_V(n) asm volatile("s_waitcnt vmcnt(" #n ")" ::: "memory")
; #define PG8_WAIT_L(n) asm volatile("s_waitcnt lgkmcnt(" #n ")" ::: "memory")
; #define PG8_BAR __builtin_amdgcn_s_barrier()
; #define PG8_SCHED __builtin_amdgcn_sched_barrier(0)
; template <class Epi, class Sched, bool ALIGN_EPI = true>
; __device__ __forceinline__ void gemm_phase(LAS unsigned char* lds, const Gemm g, const Sched& S, const Epi& E) {
;     ...
;             PG8_WAIT_V(8); PG8_WAIT_L(0); PG8_BAR; PG8_MMA(0, 0, At, B0); PG8_MMA(0, 1, At, B1); PG8_BAR; PG8_SCHED;
;             PG8_LDA(At, 0, 1); PG8_STAGE(PG8_SB(0, 0), b2, voffB); PG8_STAGE(PG8_SB(0, 1), b2 + hB, voffB); PG8_STAGE(PG8_SA(0, 0), a2, voffA);
;             PG8_WAIT_V(8); PG8_WAIT_L(0); PG8_BAR; PG8_MMA(1, 0, At, B0); PG8_MMA(1, 1, At, B1); PG8_BAR; PG8_SCHED;
;             PG8_LDB(B0, 1, 0); PG8_LDB(B1, 1, 1); PG8_SCHED; PG8_LDA(At, 1, 0); PG8_STAGE(PG8_SA(0, 1), a2 + hA, voffA);
	s_setprio 1
	s_waitcnt lgkmcnt(0)
	v_mfma_f32_16x16x32_bf16 v[128:131], v[132:135], v[186:189], v[128:131]
	v_mfma_f32_16x16x32_bf16 v[128:131], v[136:139], v[190:193], v[128:131]
	v_mfma_f32_16x16x32_bf16 v[124:127], v[140:143], v[186:189], v[124:127]
	v_mfma_f32_16x16x32_bf16 v[124:127], v[144:147], v[190:193], v[124:127]
	v_mfma_f32_16x16x32_bf16 v[116:119], v[132:135], v[194:197], v[116:119]
	v_mfma_f32_16x16x32_bf16 v[116:119], v[136:139], v[204:207], v[116:119]
	v_mfma_f32_16x16x32_bf16 v[112:115], v[140:143], v[194:197], v[112:115]
	v_mfma_f32_16x16x32_bf16 v[112:115], v[144:147], v[204:207], v[112:115]
	v_mfma_f32_16x16x32_bf16 v[104:107], v[132:135], v[208:211], v[104:107]
	v_mfma_f32_16x16x32_bf16 v[104:107], v[136:139], v[212:215], v[104:107]
	v_mfma_f32_16x16x32_bf16 v[96:99], v[140:143], v[208:211], v[96:99]
	v_mfma_f32_16x16x32_bf16 v[96:99], v[144:147], v[212:215], v[96:99]
	v_mfma_f32_16x16x32_bf16 v[88:91], v[132:135], v[216:219], v[88:91]
	v_mfma_f32_16x16x32_bf16 v[88:91], v[136:139], v[220:223], v[88:91]
	v_mfma_f32_16x16x32_bf16 v[80:83], v[140:143], v[216:219], v[80:83]
	v_mfma_f32_16x16x32_bf16 v[80:83], v[144:147], v[220:223], v[80:83]
	s_setprio 0
	s_setprio 1
	v_mfma_f32_16x16x32_bf16 v[120:123], v[170:173], v[186:189], v[120:123]
	v_mfma_f32_16x16x32_bf16 v[120:123], v[174:177], v[190:193], v[120:123]
	v_mfma_f32_16x16x32_bf16 v[108:111], v[178:181], v[186:189], v[108:111]
	v_mfma_f32_16x16x32_bf16 v[108:111], v[182:185], v[190:193], v[108:111]
	v_mfma_f32_16x16x32_bf16 v[100:103], v[170:173], v[194:197], v[100:103]
	v_mfma_f32_16x16x32_bf16 v[100:103], v[174:177], v[204:207], v[100:103]
	v_mfma_f32_16x16x32_bf16 v[92:95], v[178:181], v[194:197], v[92:95]
	v_mfma_f32_16x16x32_bf16 v[92:95], v[182:185], v[204:207], v[92:95]
	v_mfma_f32_16x16x32_bf16 v[84:87], v[170:173], v[208:211], v[84:87]
	v_mfma_f32_16x16x32_bf16 v[84:87], v[174:177], v[212:215], v[84:87]
	v_mfma_f32_16x16x32_bf16 v[76:79], v[178:181], v[208:211], v[76:79]
	v_mfma_f32_16x16x32_bf16 v[76:79], v[182:185], v[212:215], v[76:79]
	v_mfma_f32_16x16x32_bf16 v[72:75], v[170:173], v[216:219], v[72:75]
	v_mfma_f32_16x16x32_bf16 v[72:75], v[174:177], v[220:223], v[72:75]
	s_setprio 2
	s_barrier
	v_mfma_f32_16x16x32_bf16 v[68:71], v[178:181], v[216:219], v[68:71]
	v_mfma_f32_16x16x32_bf16 v[68:71], v[182:185], v[220:223], v[68:71]
	s_setprio 0
	s_add_i32 s26, s30, s59
	v_lshl_add_u64 v[156:157], s[42:43], 0, v[2:3]
	s_mov_b32 m0, s26
	s_nop 0
	global_load_lds_dwordx4 v[156:157], off
	s_add_i32 m0, s26, 0x2000
	s_add_u32 s26, s42, 0x80000
	v_lshl_add_u64 v[164:165], s[42:43], 0, v[0:1]
	s_addc_u32 s27, s43, 0
	s_add_i32 s30, s31, s59
	global_load_lds_dwordx4 v[164:165], off
	v_lshl_add_u64 v[224:225], s[26:27], 0, v[2:3]
	s_mov_b32 m0, s30
	v_lshl_add_u64 v[226:227], s[44:45], 0, v[148:149]
	global_load_lds_dwordx4 v[224:225], off
	v_lshl_add_u64 v[224:225], s[26:27], 0, v[0:1]
	s_add_i32 m0, s30, 0x2000
	s_nop 0
	global_load_lds_dwordx4 v[224:225], off
	v_lshl_add_u64 v[224:225], s[44:45], 0, v[150:151]
	s_mov_b32 m0, s60
	s_nop 0
	global_load_lds_dwordx4 v[224:225], off
	s_mov_b32 m0, s61
	s_nop 0
	global_load_lds_dwordx4 v[226:227], off
	ds_read_b128 v[186:189], v168 offset:16384
	ds_read_b128 v[190:193], v168 offset:17408
	ds_read_b128 v[194:197], v168 offset:18432
	ds_read_b128 v[204:207], v168 offset:19456
	ds_read_b128 v[208:211], v168 offset:20480
	ds_read_b128 v[212:215], v168 offset:21504
	ds_read_b128 v[216:219], v168 offset:22528
	ds_read_b128 v[220:223], v168 offset:23552
	s_waitcnt vmcnt(8)
	s_waitcnt lgkmcnt(0)
	s_barrier
	s_setprio 1
	s_waitcnt lgkmcnt(0)
	v_mfma_f32_16x16x32_bf16 v[64:67], v[132:135], v[186:189], v[64:67]
	v_mfma_f32_16x16x32_bf16 v[64:67], v[136:139], v[190:193], v[64:67]
	v_mfma_f32_16x16x32_bf16 v[60:63], v[140:143], v[186:189], v[60:63]
	v_mfma_f32_16x16x32_bf16 v[60:63], v[144:147], v[190:193], v[60:63]
	v_mfma_f32_16x16x32_bf16 v[56:59], v[132:135], v[194:197], v[56:59]
	v_mfma_f32_16x16x32_bf16 v[56:59], v[136:139], v[204:207], v[56:59]
	v_mfma_f32_16x16x32_bf16 v[48:51], v[140:143], v[194:197], v[48:51]
	v_mfma_f32_16x16x32_bf16 v[48:51], v[144:147], v[204:207], v[48:51]
	v_mfma_f32_16x16x32_bf16 v[40:43], v[132:135], v[208:211], v[40:43]
	v_mfma_f32_16x16x32_bf16 v[40:43], v[136:139], v[212:215], v[40:43]
	v_mfma_f32_16x16x32_bf16 v[32:35], v[140:143], v[208:211], v[32:35]
	v_mfma_f32_16x16x32_bf16 v[32:35], v[144:147], v[212:215], v[32:35]
	v_mfma_f32_16x16x32_bf16 v[24:27], v[132:135], v[216:219], v[24:27]
	v_mfma_f32_16x16x32_bf16 v[24:27], v[136:139], v[220:223], v[24:27]
	v_mfma_f32_16x16x32_bf16 v[16:19], v[140:143], v[216:219], v[16:19]
	v_mfma_f32_16x16x32_bf16 v[16:19], v[144:147], v[220:223], v[16:19]
	s_setprio 0
	s_setprio 1
	v_mfma_f32_16x16x32_bf16 v[52:55], v[170:173], v[186:189], v[52:55]
	v_mfma_f32_16x16x32_bf16 v[52:55], v[174:177], v[190:193], v[52:55]
	v_mfma_f32_16x16x32_bf16 v[44:47], v[178:181], v[186:189], v[44:47]
	v_mfma_f32_16x16x32_bf16 v[44:47], v[182:185], v[190:193], v[44:47]
	v_mfma_f32_16x16x32_bf16 v[36:39], v[170:173], v[194:197], v[36:39]
	v_mfma_f32_16x16x32_bf16 v[36:39], v[174:177], v[204:207], v[36:39]
	v_mfma_f32_16x16x32_bf16 v[28:31], v[178:181], v[194:197], v[28:31]
	v_mfma_f32_16x16x32_bf16 v[28:31], v[182:185], v[204:207], v[28:31]
	v_mfma_f32_16x16x32_bf16 v[20:23], v[170:173], v[208:211], v[20:23]
	v_mfma_f32_16x16x32_bf16 v[20:23], v[174:177], v[212:215], v[20:23]
	v_mfma_f32_16x16x32_bf16 v[12:15], v[178:181], v[208:211], v[12:15]
	v_mfma_f32_16x16x32_bf16 v[12:15], v[182:185], v[212:215], v[12:15]
	v_mfma_f32_16x16x32_bf16 v[8:11], v[170:173], v[216:219], v[8:11]
	v_mfma_f32_16x16x32_bf16 v[8:11], v[174:177], v[220:223], v[8:11]
	s_setprio 2
	s_barrier
; #define PG8_STAGE(bufoff, gbase, voff) do { _Pragma("unroll") for (int _i = 0; _i < 2; ++_i) \
;         __builtin_amdgcn_global_load_lds((const unsigned*)((const char*)(gbase) + (voff)[_i]), (LAS unsigned*)(lds + (bufoff) + ldsw + _i * 8192), 16, 0, 0); } while (0)
; #define PG8_LDA(dst, b, h) do { _Pragma("unroll") for (int m = 0; m < 4; ++m) _Pragma("unroll") for (int k = 0; k < 2; ++k) dst[m][k] = *(const LAS bf16x8*)(lds + PG8_SA(b, h) + aoff + m * 2048 + k * 1024); } while (0)
; #define PG8_LDB(dst, b, h) do { _Pragma("unroll") for (int n = 0; n < 2; ++n) _Pragma("unroll") for (int k = 0; k < 2; ++k) dst[n][k] = *(const LAS bf16x8*)(lds + PG8_SB(b, h) + boff + n * 2048 + k * 1024); } while (0)
; #define PG8_MMA(ai, bj, At, Bt) do { __builtin_amdgcn_s_setprio(1); _Pragma("unroll") for (int m = 0; m < 4; ++m) _Pragma("unroll") for (int n = 0; n < 2; ++n) _Pragma("unroll") for (int k = 0; k < 2; ++k) \
;         acc[ai][bj][m][n] = __builtin_amdgcn_mfma_f32_16x16x32_bf16(Bt[n][k], At[m][k], acc[ai][bj][m][n], 0, 0, 0); __builtin_amdgcn_s_setprio(0); } while (0)
; #define PG8_WAIT_V(n) asm volatile("s_waitcnt vmcnt(" #n ")" ::: "memory")
; #define PG8_WAIT_L(n) asm volatile("s_waitcnt lgkmcnt(" #n ")" ::: "memory")
; #define PG8_BAR __builtin_amdgcn_s_barrier()
; #define PG8_SCHED __builtin_amdgcn_sched_barrier(0)
; template <class Epi, class Sched, bool ALIGN_EPI = true>
; __device__ __forceinline__ void gemm_phase(LAS unsigned char* lds, const Gemm g, const Sched& S, const Epi& E) {
;     ...
;             PG8_LDB(B0, 1, 0); PG8_LDB(B1, 1, 1); PG8_SCHED; PG8_LDA(At, 1, 0); PG8_STAGE(PG8_SA(0, 1), a2 + hA, voffA);
;             PG8_WAIT_V(8); PG8_WAIT_L(0); PG8_BAR; PG8_MMA(0, 0, At, B0); PG8_MMA(0, 1, At, B1); PG8_BAR; PG8_SCHED;
;             PG8_LDA(At, 1, 1); PG8_STAGE(PG8_SB(1, 0), b3, voffB); PG8_STAGE(PG8_SB(1, 1), b3 + hB, voffB); PG8_STAGE(PG8_SA(1, 0), a3, voffA);
;             PG8_WAIT_V(8); PG8_WAIT_L(0); PG8_BAR; PG8_MMA(1, 0, At, B0); PG8_MMA(1, 1, At, B1); PG8_BAR; PG8_SCHED;
	v_mfma_f32_16x16x32_bf16 v[4:7], v[178:181], v[216:219], v[4:7]
	v_mfma_f32_16x16x32_bf16 v[4:7], v[182:185], v[220:223], v[4:7]
	s_setprio 0
	s_add_i32 s30, 0, 0x18000
	s_add_i32 s31, 0, 0x1c000
	v_add_u32_e32 v144, s30, v166
	v_add_u32_e32 v160, s31, v166
	ds_read_b128 v[132:135], v144
	ds_read_b128 v[136:139], v144 offset:1024
	ds_read_b128 v[140:143], v144 offset:2048
	ds_read_b128 v[144:147], v144 offset:3072
	ds_read_b128 v[170:173], v160
	ds_read_b128 v[174:177], v160 offset:1024
	ds_read_b128 v[178:181], v160 offset:2048
	ds_read_b128 v[182:185], v160 offset:3072
	s_add_u32 s26, s44, 0x80000
	s_addc_u32 s27, s45, 0
	s_mov_b32 m0, s62
	v_lshl_add_u64 v[228:229], s[26:27], 0, v[150:151]
	ds_read_b128 v[186:189], v168 offset:32768
	ds_read_b128 v[190:193], v168 offset:33792
	ds_read_b128 v[194:197], v168 offset:34816
	ds_read_b128 v[204:207], v168 offset:35840
	ds_read_b128 v[208:211], v168 offset:36864
	ds_read_b128 v[212:215], v168 offset:37888
	ds_read_b128 v[216:219], v168 offset:38912
	ds_read_b128 v[220:223], v168 offset:39936
	global_load_lds_dwordx4 v[228:229], off
	v_lshl_add_u64 v[228:229], s[26:27], 0, v[148:149]
	s_mov_b32 m0, s63
	s_nop 0
	global_load_lds_dwordx4 v[228:229], off
	s_waitcnt vmcnt(8)
	s_waitcnt lgkmcnt(0)
	s_barrier
	s_setprio 1
	s_waitcnt lgkmcnt(0)
	v_mfma_f32_16x16x32_bf16 v[128:131], v[132:135], v[186:189], v[128:131]
	v_mfma_f32_16x16x32_bf16 v[128:131], v[136:139], v[190:193], v[128:131]
	v_mfma_f32_16x16x32_bf16 v[124:127], v[140:143], v[186:189], v[124:127]
	v_mfma_f32_16x16x32_bf16 v[124:127], v[144:147], v[190:193], v[124:127]
	v_mfma_f32_16x16x32_bf16 v[116:119], v[132:135], v[194:197], v[116:119]
	v_mfma_f32_16x16x32_bf16 v[116:119], v[136:139], v[204:207], v[116:119]
	v_mfma_f32_16x16x32_bf16 v[112:115], v[140:143], v[194:197], v[112:115]
	v_mfma_f32_16x16x32_bf16 v[112:115], v[144:147], v[204:207], v[112:115]
	v_mfma_f32_16x16x32_bf16 v[104:107], v[132:135], v[208:211], v[104:107]
	v_mfma_f32_16x16x32_bf16 v[104:107], v[136:139], v[212:215], v[104:107]
	v_mfma_f32_16x16x32_bf16 v[96:99], v[140:143], v[208:211], v[96:99]
	v_mfma_f32_16x16x32_bf16 v[96:99], v[144:147], v[212:215], v[96:99]
	v_mfma_f32_16x16x32_bf16 v[88:91], v[132:135], v[216:219], v[88:91]
	v_mfma_f32_16x16x32_bf16 v[88:91], v[136:139], v[220:223], v[88:91]
	v_mfma_f32_16x16x32_bf16 v[80:83], v[140:143], v[216:219], v[80:83]
	v_mfma_f32_16x16x32_bf16 v[80:83], v[144:147], v[220:223], v[80:83]
	s_setprio 0
	s_setprio 1
	v_mfma_f32_16x16x32_bf16 v[120:123], v[170:173], v[186:189], v[120:123]
	v_mfma_f32_16x16x32_bf16 v[120:123], v[174:177], v[190:193], v[120:123]
	v_mfma_f32_16x16x32_bf16 v[108:111], v[178:181], v[186:189], v[108:111]
	v_mfma_f32_16x16x32_bf16 v[108:111], v[182:185], v[190:193], v[108:111]
	v_mfma_f32_16x16x32_bf16 v[100:103], v[170:173], v[194:197], v[100:103]
	v_mfma_f32_16x16x32_bf16 v[100:103], v[174:177], v[204:207], v[100:103]
	v_mfma_f32_16x16x32_bf16 v[92:95], v[178:181], v[194:197], v[92:95]
	v_mfma_f32_16x16x32_bf16 v[92:95], v[182:185], v[204:207], v[92:95]
	v_mfma_f32_16x16x32_bf16 v[84:87], v[170:173], v[208:211], v[84:87]
	v_mfma_f32_16x16x32_bf16 v[84:87], v[174:177], v[212:215], v[84:87]
	v_mfma_f32_16x16x32_bf16 v[76:79], v[178:181], v[208:211], v[76:79]
	v_mfma_f32_16x16x32_bf16 v[76:79], v[182:185], v[212:215], v[76:79]
	v_mfma_f32_16x16x32_bf16 v[72:75], v[170:173], v[216:219], v[72:75]
	v_mfma_f32_16x16x32_bf16 v[72:75], v[174:177], v[220:223], v[72:75]
	s_setprio 2
	s_barrier
; #define PG8_STAGE(bufoff, gbase, voff) do { _Pragma("unroll") for (int _i = 0; _i < 2; ++_i) \
;         __builtin_amdgcn_global_load_lds((const unsigned*)((const char*)(gbase) + (voff)[_i]), (LAS unsigned*)(lds + (bufoff) + ldsw + _i * 8192), 16, 0, 0); } while (0)
; #define PG8_LDA(dst, b, h) do { _Pragma("unroll") for (int m = 0; m < 4; ++m) _Pragma("unroll") for (int k = 0; k < 2; ++k) dst[m][k] = *(const LAS bf16x8*)(lds + PG8_SA(b, h) + aoff + m * 2048 + k * 1024); } while (0)
; #define PG8_MMA(ai, bj, At, Bt) do { __builtin_amdgcn_s_setprio(1); _Pragma("unroll") for (int m = 0; m < 4; ++m) _Pragma("unroll") for (int n = 0; n < 2; ++n) _Pragma("unroll") for (int k = 0; k < 2; ++k) \
;         acc[ai][bj][m][n] = __builtin_amdgcn_mfma_f32_16x16x32_bf16(Bt[n][k], At[m][k], acc[ai][bj][m][n], 0, 0, 0); __builtin_amdgcn_s_setprio(0); } while (0)
; #define PG8_WAIT_V(n) asm volatile("s_waitcnt vmcnt(" #n ")" ::: "memory")
; #define PG8_WAIT_L(n) asm volatile("s_waitcnt lgkmcnt(" #n ")" ::: "memory")
; #define PG8_BAR __builtin_amdgcn_s_barrier()
; #define PG8_SCHED __builtin_amdgcn_sched_barrier(0)
; template <class Epi, class Sched, bool ALIGN_EPI = true>
; __device__ __forceinline__ void gemm_phase(LAS unsigned char* lds, const Gemm g, const Sched& S, const Epi& E) {
;     ...
;             PG8_LDA(At, 1, 1); PG8_STAGE(PG8_SB(1, 0), b3, voffB); PG8_STAGE(PG8_SB(1, 1), b3 + hB, voffB); PG8_STAGE(PG8_SA(1, 0), a3, voffA);
;             PG8_WAIT_V(8); PG8_WAIT_L(0); PG8_BAR; PG8_MMA(1, 0, At, B0); PG8_MMA(1, 1, At, B1); PG8_BAR; PG8_SCHED;
;         }
	v_mfma_f32_16x16x32_bf16 v[68:71], v[178:181], v[216:219], v[68:71]
	v_mfma_f32_16x16x32_bf16 v[68:71], v[182:185], v[220:223], v[68:71]
	s_setprio 0
	s_add_i32 s26, s30, s59
	v_lshl_add_u64 v[156:157], v[156:157], 0, s[86:87]
	s_mov_b32 m0, s26
	s_nop 0
	global_load_lds_dwordx4 v[156:157], off
	s_add_i32 m0, s26, 0x2000
	s_add_u32 s26, s42, 0x80080
	v_lshl_add_u64 v[156:157], v[164:165], 0, s[86:87]
	s_addc_u32 s27, s43, 0
	s_add_i32 s30, s31, s59
	global_load_lds_dwordx4 v[156:157], off
	v_lshl_add_u64 v[156:157], s[26:27], 0, v[2:3]
	s_mov_b32 m0, s30
	s_nop 0
	global_load_lds_dwordx4 v[156:157], off
	v_lshl_add_u64 v[156:157], s[26:27], 0, v[0:1]
	s_add_i32 m0, s30, 0x2000
	s_nop 0
	global_load_lds_dwordx4 v[156:157], off
	v_lshl_add_u64 v[156:157], v[224:225], 0, s[86:87]
	s_mov_b32 m0, s64
	s_nop 0
	global_load_lds_dwordx4 v[156:157], off
	v_lshl_add_u64 v[156:157], v[226:227], 0, s[86:87]
	s_mov_b32 m0, s65
	s_nop 0
	global_load_lds_dwordx4 v[156:157], off
	ds_read_b128 v[186:189], v168 offset:49152
	ds_read_b128 v[190:193], v168 offset:50176
	ds_read_b128 v[194:197], v168 offset:51200
	ds_read_b128 v[204:207], v168 offset:52224
	ds_read_b128 v[208:211], v168 offset:53248
	ds_read_b128 v[212:215], v168 offset:54272
	ds_read_b128 v[216:219], v168 offset:55296
	ds_read_b128 v[220:223], v168 offset:56320
	s_waitcnt vmcnt(8)
	s_waitcnt lgkmcnt(0)
	s_barrier
	s_setprio 1
	s_waitcnt lgkmcnt(0)
	v_mfma_f32_16x16x32_bf16 v[64:67], v[132:135], v[186:189], v[64:67]
	v_mfma_f32_16x16x32_bf16 v[64:67], v[136:139], v[190:193], v[64:67]
	v_mfma_f32_16x16x32_bf16 v[60:63], v[140:143], v[186:189], v[60:63]
	v_mfma_f32_16x16x32_bf16 v[60:63], v[144:147], v[190:193], v[60:63]
	v_mfma_f32_16x16x32_bf16 v[56:59], v[132:135], v[194:197], v[56:59]
	v_mfma_f32_16x16x32_bf16 v[56:59], v[136:139], v[204:207], v[56:59]
	v_mfma_f32_16x16x32_bf16 v[48:51], v[140:143], v[194:197], v[48:51]
	v_mfma_f32_16x16x32_bf16 v[48:51], v[144:147], v[204:207], v[48:51]
	v_mfma_f32_16x16x32_bf16 v[40:43], v[132:135], v[208:211], v[40:43]
	v_mfma_f32_16x16x32_bf16 v[40:43], v[136:139], v[212:215], v[40:43]
	v_mfma_f32_16x16x32_bf16 v[32:35], v[140:143], v[208:211], v[32:35]
	v_mfma_f32_16x16x32_bf16 v[32:35], v[144:147], v[212:215], v[32:35]
	v_mfma_f32_16x16x32_bf16 v[24:27], v[132:135], v[216:219], v[24:27]
	v_mfma_f32_16x16x32_bf16 v[24:27], v[136:139], v[220:223], v[24:27]
	v_mfma_f32_16x16x32_bf16 v[16:19], v[140:143], v[216:219], v[16:19]
	v_mfma_f32_16x16x32_bf16 v[16:19], v[144:147], v[220:223], v[16:19]
	s_setprio 0
	s_setprio 1
	v_mfma_f32_16x16x32_bf16 v[52:55], v[170:173], v[186:189], v[52:55]
	v_mfma_f32_16x16x32_bf16 v[52:55], v[174:177], v[190:193], v[52:55]
	v_mfma_f32_16x16x32_bf16 v[44:47], v[178:181], v[186:189], v[44:47]
	v_mfma_f32_16x16x32_bf16 v[44:47], v[182:185], v[190:193], v[44:47]
	v_mfma_f32_16x16x32_bf16 v[36:39], v[170:173], v[194:197], v[36:39]
	v_mfma_f32_16x16x32_bf16 v[36:39], v[174:177], v[204:207], v[36:39]
	v_mfma_f32_16x16x32_bf16 v[28:31], v[178:181], v[194:197], v[28:31]
	v_mfma_f32_16x16x32_bf16 v[28:31], v[182:185], v[204:207], v[28:31]
	v_mfma_f32_16x16x32_bf16 v[20:23], v[170:173], v[208:211], v[20:23]
	v_mfma_f32_16x16x32_bf16 v[20:23], v[174:177], v[212:215], v[20:23]
	v_mfma_f32_16x16x32_bf16 v[12:15], v[178:181], v[208:211], v[12:15]
	v_mfma_f32_16x16x32_bf16 v[12:15], v[182:185], v[212:215], v[12:15]
	v_mfma_f32_16x16x32_bf16 v[8:11], v[170:173], v[216:219], v[8:11]
	v_mfma_f32_16x16x32_bf16 v[8:11], v[174:177], v[220:223], v[8:11]
	s_setprio 2
	s_barrier
	v_mfma_f32_16x16x32_bf16 v[4:7], v[178:181], v[216:219], v[4:7]
	v_mfma_f32_16x16x32_bf16 v[4:7], v[182:185], v[220:223], v[4:7]
	s_setprio 0
	s_add_i32 s25, s25, 2
	s_add_u32 s6, s6, 0x100
	s_addc_u32 s7, s7, 0
	s_add_u32 s19, s19, 0x100
	s_addc_u32 s24, s24, 0
	s_cmp_gt_u32 s25, 29
	s_cbranch_scc0 .LBB0_77

;     __device__ bool next(int i, Unit& u) const { if (i >= 2) return false; const int x = c & 7, j = c >> 3; u.pm = 32 * i + 4 * x + (j & 3); u.pn = j >> 2; return true; }
; #define PG8_STAGE(bufoff, gbase, voff) do { _Pragma("unroll") for (int _i = 0; _i < 2; ++_i) \
;         __builtin_amdgcn_global_load_lds((const unsigned*)((const char*)(gbase) + (voff)[_i]), (LAS unsigned*)(lds + (bufoff) + ldsw + _i * 8192), 16, 0, 0); } while (0)
; #define PG8_LDA(dst, b, h) do { _Pragma("unroll") for (int m = 0; m < 4; ++m) _Pragma("unroll") for (int k = 0; k < 2; ++k) dst[m][k] = *(const LAS bf16x8*)(lds + PG8_SA(b, h) + aoff + m * 2048 + k * 1024); } while (0)
; #define PG8_LDB(dst, b, h) do { _Pragma("unroll") for (int n = 0; n < 2; ++n) _Pragma("unroll") for (int k = 0; k < 2; ++k) dst[n][k] = *(const LAS bf16x8*)(lds + PG8_SB(b, h) + boff + n * 2048 + k * 1024); } while (0)
; #define PG8_WAIT_V(n) asm volatile("s_waitcnt vmcnt(" #n ")" ::: "memory")
; #define PG8_WAIT_L(n) asm volatile("s_waitcnt lgkmcnt(" #n ")" ::: "memory")
; #define PG8_BAR __builtin_amdgcn_s_barrier()
; template <class Epi, class Sched, bool ALIGN_EPI = true>
; __device__ __forceinline__ void gemm_phase(LAS unsigned char* lds, const Gemm g, const Sched& S, const Epi& E) {
;     ...
;         const bool has_next = S.next(ui + 1, nxt);
;         const char* nA = has_next ? (const char*)g.A + ((size_t)nxt.pm * BM * g.lda + (size_t)nxt.pn * g.a_pn_off) * 2 : cA; const char* nB = has_next ? (const char*)g.Bt + (size_t)nxt.pn * BM * g.ldb * 2 : cB;
;         for (int t = 0; t < nt; t += 2) {
;             const bool last = (t == nt - 2);
;             const char* a1 = cA + (size_t)(t + 1) * kstep;
;             const char* a2 = last ? nA : cA + (size_t)(t + 2) * kstep; const char* b2 = last ? nB : cB + (size_t)(t + 2) * kstep;
;             const char* a3 = a2 + kstep; const char* b3 = b2 + kstep;
;             PG8_LDB(B0, 0, 0); PG8_LDB(B1, 0, 1); PG8_SCHED; PG8_LDA(At, 0, 0); PG8_STAGE(PG8_SA(1, 1), a1 + hA, voffA);
;             PG8_WAIT_V(8); PG8_WAIT_L(0); PG8_BAR; PG8_MMA(0, 0, At, B0); PG8_MMA(0, 1, At, B1); PG8_BAR; PG8_SCHED;
;             PG8_LDA(At, 0, 1); PG8_STAGE(PG8_SB(0, 0), b2, voffB); PG8_STAGE(PG8_SB(0, 1), b2 + hB, voffB); PG8_STAGE(PG8_SA(0, 0), a2, voffA);
;             PG8_WAIT_V(8); PG8_WAIT_L(0); PG8_BAR; PG8_MMA(1, 0, At, B0); PG8_MMA(1, 1, At, B1); PG8_BAR; PG8_SCHED;
.LBB0_217:
	s_ashr_i32 s11, s10, 31
	s_lshl_b64 s[12:13], s[10:11], 20
	s_add_u32 s12, s46, s12
	s_addc_u32 s13, s47, s13
	s_and_b64 s[14:15], s[4:5], exec
	s_cselect_b32 s11, s13, s39
	s_cselect_b32 s18, s12, s38
	s_ashr_i32 s9, s8, 31
	s_lshl_b64 s[14:15], s[8:9], 20
	s_add_u32 s14, s44, s14
	s_addc_u32 s15, s45, s15
	s_and_b64 s[24:25], s[4:5], exec
	s_cselect_b32 s9, s15, s41
	s_cselect_b32 s19, s14, s40
	s_add_u32 s38, s38, 0x80080
	s_addc_u32 s39, s39, 0
	s_add_u32 s24, s40, 0x100
	s_addc_u32 s25, s41, 0
	s_mov_b32 s26, -2
	s_add_u32 s27, s38, 0xfff80080
	s_addc_u32 s30, s39, -1
	s_add_i32 s31, 0, 0x10000
	s_cmp_eq_u32 s26, 28
	s_cselect_b32 s43, s11, s30
	s_cselect_b32 s42, s18, s27
	v_add_u32_e32 v156, s31, v145
	s_cselect_b32 s41, s9, s25
	s_cselect_b32 s40, s19, s24
	s_add_i32 s27, 0, 0x14000
	ds_read_b128 v[140:143], v156
	ds_read_b128 v[148:151], v156 offset:1024
	ds_read_b128 v[152:155], v156 offset:2048
	ds_read_b128 v[164:167], v156 offset:3072
	v_add_u32_e32 v156, s27, v145
	ds_read_b128 v[168:171], v156
	ds_read_b128 v[172:175], v156 offset:1024
	ds_read_b128 v[176:179], v156 offset:2048
	ds_read_b128 v[180:183], v156 offset:3072
	v_lshl_add_u64 v[156:157], s[38:39], 0, v[136:137]
	s_add_i32 m0, s58, 0xc000
	ds_read_b128 v[184:187], v147
	ds_read_b128 v[188:191], v147 offset:1024
	ds_read_b128 v[192:195], v147 offset:2048
	ds_read_b128 v[204:207], v147 offset:3072
	ds_read_b128 v[208:211], v147 offset:4096
	ds_read_b128 v[212:215], v147 offset:5120
	ds_read_b128 v[216:219], v147 offset:6144
	ds_read_b128 v[220:223], v147 offset:7168
	global_load_lds_dwordx4 v[156:157], off
	v_lshl_add_u64 v[156:157], s[38:39], 0, v[138:139]
	s_add_i32 m0, s58, 0xe000
	s_nop 0
	global_load_lds_dwordx4 v[156:157], off
	s_waitcnt vmcnt(8)
	s_waitcnt lgkmcnt(0)
	s_barrier
	s_setprio 1
	s_waitcnt lgkmcnt(0)
	v_mfma_f32_16x16x32_bf16 v[128:131], v[140:143], v[184:187], 0
	v_mfma_f32_16x16x32_bf16 v[128:131], v[148:151], v[188:191], v[128:131]
	v_mfma_f32_16x16x32_bf16 v[124:127], v[152:155], v[184:187], 0
	v_mfma_f32_16x16x32_bf16 v[124:127], v[164:167], v[188:191], v[124:127]
	v_mfma_f32_16x16x32_bf16 v[120:123], v[140:143], v[192:195], 0
	v_mfma_f32_16x16x32_bf16 v[120:123], v[148:151], v[204:207], v[120:123]
	v_mfma_f32_16x16x32_bf16 v[112:115], v[152:155], v[192:195], 0
	v_mfma_f32_16x16x32_bf16 v[112:115], v[164:167], v[204:207], v[112:115]
	v_mfma_f32_16x16x32_bf16 v[104:107], v[140:143], v[208:211], 0
	v_mfma_f32_16x16x32_bf16 v[104:107], v[148:151], v[212:215], v[104:107]
	v_mfma_f32_16x16x32_bf16 v[96:99], v[152:155], v[208:211], 0
	v_mfma_f32_16x16x32_bf16 v[96:99], v[164:167], v[212:215], v[96:99]
	v_mfma_f32_16x16x32_bf16 v[88:91], v[140:143], v[216:219], 0
	v_mfma_f32_16x16x32_bf16 v[88:91], v[148:151], v[220:223], v[88:91]
	v_mfma_f32_16x16x32_bf16 v[80:83], v[152:155], v[216:219], 0
	v_mfma_f32_16x16x32_bf16 v[80:83], v[164:167], v[220:223], v[80:83]
	s_setprio 0
	s_setprio 1
	v_mfma_f32_16x16x32_bf16 v[116:119], v[168:171], v[184:187], 0
	v_mfma_f32_16x16x32_bf16 v[116:119], v[172:175], v[188:191], v[116:119]
	v_mfma_f32_16x16x32_bf16 v[108:111], v[176:179], v[184:187], 0
	v_mfma_f32_16x16x32_bf16 v[108:111], v[180:183], v[188:191], v[108:111]
	v_mfma_f32_16x16x32_bf16 v[100:103], v[168:171], v[192:195], 0
	v_mfma_f32_16x16x32_bf16 v[100:103], v[172:175], v[204:207], v[100:103]
	v_mfma_f32_16x16x32_bf16 v[92:95], v[176:179], v[192:195], 0
	v_mfma_f32_16x16x32_bf16 v[92:95], v[180:183], v[204:207], v[92:95]
	v_mfma_f32_16x16x32_bf16 v[84:87], v[168:171], v[208:211], 0
	v_mfma_f32_16x16x32_bf16 v[84:87], v[172:175], v[212:215], v[84:87]
	v_mfma_f32_16x16x32_bf16 v[76:79], v[176:179], v[208:211], 0
	v_mfma_f32_16x16x32_bf16 v[76:79], v[180:183], v[212:215], v[76:79]
	v_mfma_f32_16x16x32_bf16 v[72:75], v[168:171], v[216:219], 0
	v_mfma_f32_16x16x32_bf16 v[72:75], v[172:175], v[220:223], v[72:75]
	s_setprio 2
	s_barrier
	v_mfma_f32_16x16x32_bf16 v[68:71], v[176:179], v[216:219], 0
	v_mfma_f32_16x16x32_bf16 v[68:71], v[180:183], v[220:223], v[68:71]
	s_setprio 0
	s_add_i32 s30, s31, s53
	v_lshl_add_u64 v[156:157], s[40:41], 0, v[2:3]
	s_mov_b32 m0, s30
	s_nop 0
	global_load_lds_dwordx4 v[156:157], off
	s_add_i32 m0, s30, 0x2000
	s_add_u32 s30, s40, 0x80000
	v_lshl_add_u64 v[196:197], s[40:41], 0, v[0:1]
	s_addc_u32 s31, s41, 0
	s_add_i32 s27, s27, s53
	global_load_lds_dwordx4 v[196:197], off
	v_lshl_add_u64 v[224:225], s[30:31], 0, v[2:3]
	s_mov_b32 m0, s27
	v_lshl_add_u64 v[226:227], s[42:43], 0, v[132:133]
	global_load_lds_dwordx4 v[224:225], off
	v_lshl_add_u64 v[224:225], s[30:31], 0, v[0:1]
	s_add_i32 m0, s27, 0x2000
	s_nop 0
	global_load_lds_dwordx4 v[224:225], off
	v_lshl_add_u64 v[224:225], s[42:43], 0, v[134:135]
	s_mov_b32 m0, s58
	s_nop 0
	global_load_lds_dwordx4 v[224:225], off
	s_mov_b32 m0, s59
	s_nop 0
	global_load_lds_dwordx4 v[226:227], off
	ds_read_b128 v[184:187], v147 offset:16384
	ds_read_b128 v[188:191], v147 offset:17408
	ds_read_b128 v[192:195], v147 offset:18432
	ds_read_b128 v[204:207], v147 offset:19456
	ds_read_b128 v[208:211], v147 offset:20480
	ds_read_b128 v[212:215], v147 offset:21504
	ds_read_b128 v[216:219], v147 offset:22528
	ds_read_b128 v[220:223], v147 offset:23552
	s_waitcnt vmcnt(8)
	s_waitcnt lgkmcnt(0)
	s_barrier
; #define PG8_STAGE(bufoff, gbase, voff) do { _Pragma("unroll") for (int _i = 0; _i < 2; ++_i) \
;         __builtin_amdgcn_global_load_lds((const unsigned*)((const char*)(gbase) + (voff)[_i]), (LAS unsigned*)(lds + (bufoff) + ldsw + _i * 8192), 16, 0, 0); } while (0)
; #define PG8_LDA(dst, b, h) do { _Pragma("unroll") for (int m = 0; m < 4; ++m) _Pragma("unroll") for (int k = 0; k < 2; ++k) dst[m][k] = *(const LAS bf16x8*)(lds + PG8_SA(b, h) + aoff + m * 2048 + k * 1024); } while (0)
; #define PG8_LDB(dst, b, h) do { _Pragma("unroll") for (int n = 0; n < 2; ++n) _Pragma("unroll") for (int k = 0; k < 2; ++k) dst[n][k] = *(const LAS bf16x8*)(lds + PG8_SB(b, h) + boff + n * 2048 + k * 1024); } while (0)
; #define PG8_MMA(ai, bj, At, Bt) do { __builtin_amdgcn_s_setprio(1); _Pragma("unroll") for (int m = 0; m < 4; ++m) _Pragma("unroll") for (int n = 0; n < 2; ++n) _Pragma("unroll") for (int k = 0; k < 2; ++k) \
;         acc[ai][bj][m][n] = __builtin_amdgcn_mfma_f32_16x16x32_bf16(Bt[n][k], At[m][k], acc[ai][bj][m][n], 0, 0, 0); __builtin_amdgcn_s_setprio(0); } while (0)
; #define PG8_WAIT_V(n) asm volatile("s_waitcnt vmcnt(" #n ")" ::: "memory")
; #define PG8_WAIT_L(n) asm volatile("s_waitcnt lgkmcnt(" #n ")" ::: "memory")
; #define PG8_BAR __builtin_amdgcn_s_barrier()
; #define PG8_SCHED __builtin_amdgcn_sched_barrier(0)
; template <class Epi, class Sched, bool ALIGN_EPI = true>
; __device__ __forceinline__ void gemm_phase(LAS unsigned char* lds, const Gemm g, const Sched& S, const Epi& E) {
;     ...
;             PG8_WAIT_V(8); PG8_WAIT_L(0); PG8_BAR; PG8_MMA(1, 0, At, B0); PG8_MMA(1, 1, At, B1); PG8_BAR; PG8_SCHED;
;             PG8_LDB(B0, 1, 0); PG8_LDB(B1, 1, 1); PG8_SCHED; PG8_LDA(At, 1, 0); PG8_STAGE(PG8_SA(0, 1), a2 + hA, voffA);
;             PG8_WAIT_V(8); PG8_WAIT_L(0); PG8_BAR; PG8_MMA(0, 0, At, B0); PG8_MMA(0, 1, At, B1); PG8_BAR; PG8_SCHED;
;             PG8_LDA(At, 1, 1); PG8_STAGE(PG8_SB(1, 0), b3, voffB); PG8_STAGE(PG8_SB(1, 1), b3 + hB, voffB); PG8_STAGE(PG8_SA(1, 0), a3, voffA);
;             PG8_WAIT_V(8); PG8_WAIT_L(0); PG8_BAR; PG8_MMA(1, 0, At, B0); PG8_MMA(1, 1, At, B1); PG8_BAR; PG8_SCHED;
	s_setprio 1
	s_waitcnt lgkmcnt(0)
	v_mfma_f32_16x16x32_bf16 v[64:67], v[140:143], v[184:187], 0
	v_mfma_f32_16x16x32_bf16 v[64:67], v[148:151], v[188:191], v[64:67]
	v_mfma_f32_16x16x32_bf16 v[60:63], v[152:155], v[184:187], 0
	v_mfma_f32_16x16x32_bf16 v[60:63], v[164:167], v[188:191], v[60:63]
	v_mfma_f32_16x16x32_bf16 v[56:59], v[140:143], v[192:195], 0
	v_mfma_f32_16x16x32_bf16 v[56:59], v[148:151], v[204:207], v[56:59]
	v_mfma_f32_16x16x32_bf16 v[48:51], v[152:155], v[192:195], 0
	v_mfma_f32_16x16x32_bf16 v[48:51], v[164:167], v[204:207], v[48:51]
	v_mfma_f32_16x16x32_bf16 v[40:43], v[140:143], v[208:211], 0
	v_mfma_f32_16x16x32_bf16 v[40:43], v[148:151], v[212:215], v[40:43]
	v_mfma_f32_16x16x32_bf16 v[32:35], v[152:155], v[208:211], 0
	v_mfma_f32_16x16x32_bf16 v[32:35], v[164:167], v[212:215], v[32:35]
	v_mfma_f32_16x16x32_bf16 v[24:27], v[140:143], v[216:219], 0
	v_mfma_f32_16x16x32_bf16 v[24:27], v[148:151], v[220:223], v[24:27]
	v_mfma_f32_16x16x32_bf16 v[16:19], v[152:155], v[216:219], 0
	v_mfma_f32_16x16x32_bf16 v[16:19], v[164:167], v[220:223], v[16:19]
	s_setprio 0
	s_setprio 1
	v_mfma_f32_16x16x32_bf16 v[52:55], v[168:171], v[184:187], 0
	v_mfma_f32_16x16x32_bf16 v[52:55], v[172:175], v[188:191], v[52:55]
	v_mfma_f32_16x16x32_bf16 v[44:47], v[176:179], v[184:187], 0
	v_mfma_f32_16x16x32_bf16 v[44:47], v[180:183], v[188:191], v[44:47]
	v_mfma_f32_16x16x32_bf16 v[36:39], v[168:171], v[192:195], 0
	v_mfma_f32_16x16x32_bf16 v[36:39], v[172:175], v[204:207], v[36:39]
	v_mfma_f32_16x16x32_bf16 v[28:31], v[176:179], v[192:195], 0
	v_mfma_f32_16x16x32_bf16 v[28:31], v[180:183], v[204:207], v[28:31]
	v_mfma_f32_16x16x32_bf16 v[20:23], v[168:171], v[208:211], 0
	v_mfma_f32_16x16x32_bf16 v[20:23], v[172:175], v[212:215], v[20:23]
	v_mfma_f32_16x16x32_bf16 v[12:15], v[176:179], v[208:211], 0
	v_mfma_f32_16x16x32_bf16 v[12:15], v[180:183], v[212:215], v[12:15]
	v_mfma_f32_16x16x32_bf16 v[8:11], v[168:171], v[216:219], 0
	v_mfma_f32_16x16x32_bf16 v[8:11], v[172:175], v[220:223], v[8:11]
	s_setprio 2
	s_barrier
	v_mfma_f32_16x16x32_bf16 v[4:7], v[176:179], v[216:219], 0
	v_mfma_f32_16x16x32_bf16 v[4:7], v[180:183], v[220:223], v[4:7]
	s_setprio 0
	s_add_i32 s27, 0, 0x18000
	v_add_u32_e32 v158, s27, v145
	s_add_i32 s65, 0, 0x1c000
	ds_read_b128 v[140:143], v158
	ds_read_b128 v[148:151], v158 offset:1024
	ds_read_b128 v[152:155], v158 offset:2048
	ds_read_b128 v[164:167], v158 offset:3072
	v_add_u32_e32 v158, s65, v145
	ds_read_b128 v[168:171], v158
	ds_read_b128 v[172:175], v158 offset:1024
	ds_read_b128 v[176:179], v158 offset:2048
	ds_read_b128 v[180:183], v158 offset:3072
	s_add_u32 s30, s42, 0x80000
	s_addc_u32 s31, s43, 0
	s_mov_b32 m0, s60
	v_lshl_add_u64 v[228:229], s[30:31], 0, v[134:135]
	ds_read_b128 v[184:187], v147 offset:32768
	ds_read_b128 v[188:191], v147 offset:33792
	ds_read_b128 v[192:195], v147 offset:34816
	ds_read_b128 v[204:207], v147 offset:35840
	ds_read_b128 v[208:211], v147 offset:36864
	ds_read_b128 v[212:215], v147 offset:37888
	ds_read_b128 v[216:219], v147 offset:38912
	ds_read_b128 v[220:223], v147 offset:39936
	global_load_lds_dwordx4 v[228:229], off
	v_lshl_add_u64 v[228:229], s[30:31], 0, v[132:133]
	s_mov_b32 m0, s61
	s_nop 0
	global_load_lds_dwordx4 v[228:229], off
	s_waitcnt vmcnt(8)
	s_waitcnt lgkmcnt(0)
	s_barrier
	s_setprio 1
	s_waitcnt lgkmcnt(0)
	v_mfma_f32_16x16x32_bf16 v[128:131], v[140:143], v[184:187], v[128:131]
	v_mfma_f32_16x16x32_bf16 v[128:131], v[148:151], v[188:191], v[128:131]
	v_mfma_f32_16x16x32_bf16 v[124:127], v[152:155], v[184:187], v[124:127]
	v_mfma_f32_16x16x32_bf16 v[124:127], v[164:167], v[188:191], v[124:127]
	v_mfma_f32_16x16x32_bf16 v[120:123], v[140:143], v[192:195], v[120:123]
	v_mfma_f32_16x16x32_bf16 v[120:123], v[148:151], v[204:207], v[120:123]
	v_mfma_f32_16x16x32_bf16 v[112:115], v[152:155], v[192:195], v[112:115]
	v_mfma_f32_16x16x32_bf16 v[112:115], v[164:167], v[204:207], v[112:115]
	v_mfma_f32_16x16x32_bf16 v[104:107], v[140:143], v[208:211], v[104:107]
	v_mfma_f32_16x16x32_bf16 v[104:107], v[148:151], v[212:215], v[104:107]
	v_mfma_f32_16x16x32_bf16 v[96:99], v[152:155], v[208:211], v[96:99]
	v_mfma_f32_16x16x32_bf16 v[96:99], v[164:167], v[212:215], v[96:99]
	v_mfma_f32_16x16x32_bf16 v[88:91], v[140:143], v[216:219], v[88:91]
	v_mfma_f32_16x16x32_bf16 v[88:91], v[148:151], v[220:223], v[88:91]
	v_mfma_f32_16x16x32_bf16 v[80:83], v[152:155], v[216:219], v[80:83]
	v_mfma_f32_16x16x32_bf16 v[80:83], v[164:167], v[220:223], v[80:83]
	s_setprio 0
	s_setprio 1
	v_mfma_f32_16x16x32_bf16 v[116:119], v[168:171], v[184:187], v[116:119]
	v_mfma_f32_16x16x32_bf16 v[116:119], v[172:175], v[188:191], v[116:119]
	v_mfma_f32_16x16x32_bf16 v[108:111], v[176:179], v[184:187], v[108:111]
	v_mfma_f32_16x16x32_bf16 v[108:111], v[180:183], v[188:191], v[108:111]
	v_mfma_f32_16x16x32_bf16 v[100:103], v[168:171], v[192:195], v[100:103]
	v_mfma_f32_16x16x32_bf16 v[100:103], v[172:175], v[204:207], v[100:103]
	v_mfma_f32_16x16x32_bf16 v[92:95], v[176:179], v[192:195], v[92:95]
	v_mfma_f32_16x16x32_bf16 v[92:95], v[180:183], v[204:207], v[92:95]
	v_mfma_f32_16x16x32_bf16 v[84:87], v[168:171], v[208:211], v[84:87]
	v_mfma_f32_16x16x32_bf16 v[84:87], v[172:175], v[212:215], v[84:87]
	v_mfma_f32_16x16x32_bf16 v[76:79], v[176:179], v[208:211], v[76:79]
	v_mfma_f32_16x16x32_bf16 v[76:79], v[180:183], v[212:215], v[76:79]
	v_mfma_f32_16x16x32_bf16 v[72:75], v[168:171], v[216:219], v[72:75]
	v_mfma_f32_16x16x32_bf16 v[72:75], v[172:175], v[220:223], v[72:75]
	s_setprio 2
	s_barrier
; #define PG8_STAGE(bufoff, gbase, voff) do { _Pragma("unroll") for (int _i = 0; _i < 2; ++_i) \
;         __builtin_amdgcn_global_load_lds((const unsigned*)((const char*)(gbase) + (voff)[_i]), (LAS unsigned*)(lds + (bufoff) + ldsw + _i * 8192), 16, 0, 0); } while (0)
; #define PG8_LDA(dst, b, h) do { _Pragma("unroll") for (int m = 0; m < 4; ++m) _Pragma("unroll") for (int k = 0; k < 2; ++k) dst[m][k] = *(const LAS bf16x8*)(lds + PG8_SA(b, h) + aoff + m * 2048 + k * 1024); } while (0)
; #define PG8_LDB(dst, b, h) do { _Pragma("unroll") for (int n = 0; n < 2; ++n) _Pragma("unroll") for (int k = 0; k < 2; ++k) dst[n][k] = *(const LAS bf16x8*)(lds + PG8_SB(b, h) + boff + n * 2048 + k * 1024); } while (0)
; #define PG8_WAIT_V(n) asm volatile("s_waitcnt vmcnt(" #n ")" ::: "memory")
; #define PG8_WAIT_L(n) asm volatile("s_waitcnt lgkmcnt(" #n ")" ::: "memory")
; #define PG8_BAR __builtin_amdgcn_s_barrier()
; template <class Epi, class Sched, bool ALIGN_EPI = true>
; __device__ __forceinline__ void gemm_phase(LAS unsigned char* lds, const Gemm g, const Sched& S, const Epi& E) {
;     ...
;             const char* a1 = cA + (size_t)(t + 1) * kstep;
;             const char* a2 = last ? nA : cA + (size_t)(t + 2) * kstep; const char* b2 = last ? nB : cB + (size_t)(t + 2) * kstep;
;             const char* a3 = a2 + kstep; const char* b3 = b2 + kstep;
;             PG8_LDB(B0, 0, 0); PG8_LDB(B1, 0, 1); PG8_SCHED; PG8_LDA(At, 0, 0); PG8_STAGE(PG8_SA(1, 1), a1 + hA, voffA);
;             PG8_WAIT_V(8); PG8_WAIT_L(0); PG8_BAR; PG8_MMA(0, 0, At, B0); PG8_MMA(0, 1, At, B1); PG8_BAR; PG8_SCHED;
;             PG8_LDA(At, 0, 1); PG8_STAGE(PG8_SB(0, 0), b2, voffB); PG8_STAGE(PG8_SB(0, 1), b2 + hB, voffB); PG8_STAGE(PG8_SA(0, 0), a2, voffA);
;             PG8_WAIT_V(8); PG8_WAIT_L(0); PG8_BAR; PG8_MMA(1, 0, At, B0); PG8_MMA(1, 1, At, B1); PG8_BAR; PG8_SCHED;
;             PG8_LDB(B0, 1, 0); PG8_LDB(B1, 1, 1); PG8_SCHED; PG8_LDA(At, 1, 0); PG8_STAGE(PG8_SA(0, 1), a2 + hA, voffA);
;             PG8_WAIT_V(8); PG8_WAIT_L(0); PG8_BAR; PG8_MMA(0, 0, At, B0); PG8_MMA(0, 1, At, B1); PG8_BAR; PG8_SCHED;
;             PG8_LDA(At, 1, 1); PG8_STAGE(PG8_SB(1, 0), b3, voffB); PG8_STAGE(PG8_SB(1, 1), b3 + hB, voffB); PG8_STAGE(PG8_SA(1, 0), a3, voffA);
;             PG8_WAIT_V(8); PG8_WAIT_L(0); PG8_BAR; PG8_MMA(1, 0, At, B0); PG8_MMA(1, 1, At, B1); PG8_BAR; PG8_SCHED;
	v_mfma_f32_16x16x32_bf16 v[68:71], v[176:179], v[216:219], v[68:71]
	v_mfma_f32_16x16x32_bf16 v[68:71], v[180:183], v[220:223], v[68:71]
	s_setprio 0
	s_add_i32 s27, s27, s53
	v_lshl_add_u64 v[156:157], v[156:157], 0, s[86:87]
	s_mov_b32 m0, s27
	s_nop 0
	global_load_lds_dwordx4 v[156:157], off
	s_add_i32 m0, s27, 0x2000
	s_add_u32 s30, s40, 0x80080
	v_lshl_add_u64 v[156:157], v[196:197], 0, s[86:87]
	s_addc_u32 s31, s41, 0
	s_add_i32 s27, s65, s53
	global_load_lds_dwordx4 v[156:157], off
	v_lshl_add_u64 v[156:157], s[30:31], 0, v[2:3]
	s_mov_b32 m0, s27
	s_nop 0
	global_load_lds_dwordx4 v[156:157], off
	v_lshl_add_u64 v[156:157], s[30:31], 0, v[0:1]
	s_add_i32 m0, s27, 0x2000
	s_nop 0
	global_load_lds_dwordx4 v[156:157], off
	v_lshl_add_u64 v[156:157], v[224:225], 0, s[86:87]
	s_mov_b32 m0, s62
	s_nop 0
	global_load_lds_dwordx4 v[156:157], off
	v_lshl_add_u64 v[156:157], v[226:227], 0, s[86:87]
	s_mov_b32 m0, s63
	s_nop 0
	global_load_lds_dwordx4 v[156:157], off
	ds_read_b128 v[184:187], v147 offset:49152
	ds_read_b128 v[188:191], v147 offset:50176
	ds_read_b128 v[192:195], v147 offset:51200
	ds_read_b128 v[204:207], v147 offset:52224
	ds_read_b128 v[208:211], v147 offset:53248
	ds_read_b128 v[212:215], v147 offset:54272
	ds_read_b128 v[216:219], v147 offset:55296
	ds_read_b128 v[220:223], v147 offset:56320
	s_waitcnt vmcnt(8)
	s_waitcnt lgkmcnt(0)
	s_barrier
	s_setprio 1
	s_waitcnt lgkmcnt(0)
	v_mfma_f32_16x16x32_bf16 v[64:67], v[140:143], v[184:187], v[64:67]
	v_mfma_f32_16x16x32_bf16 v[64:67], v[148:151], v[188:191], v[64:67]
	v_mfma_f32_16x16x32_bf16 v[60:63], v[152:155], v[184:187], v[60:63]
	v_mfma_f32_16x16x32_bf16 v[60:63], v[164:167], v[188:191], v[60:63]
	v_mfma_f32_16x16x32_bf16 v[56:59], v[140:143], v[192:195], v[56:59]
	v_mfma_f32_16x16x32_bf16 v[56:59], v[148:151], v[204:207], v[56:59]
	v_mfma_f32_16x16x32_bf16 v[48:51], v[152:155], v[192:195], v[48:51]
	v_mfma_f32_16x16x32_bf16 v[48:51], v[164:167], v[204:207], v[48:51]
	v_mfma_f32_16x16x32_bf16 v[40:43], v[140:143], v[208:211], v[40:43]
	v_mfma_f32_16x16x32_bf16 v[40:43], v[148:151], v[212:215], v[40:43]
	v_mfma_f32_16x16x32_bf16 v[32:35], v[152:155], v[208:211], v[32:35]
	v_mfma_f32_16x16x32_bf16 v[32:35], v[164:167], v[212:215], v[32:35]
	v_mfma_f32_16x16x32_bf16 v[24:27], v[140:143], v[216:219], v[24:27]
	v_mfma_f32_16x16x32_bf16 v[24:27], v[148:151], v[220:223], v[24:27]
	v_mfma_f32_16x16x32_bf16 v[16:19], v[152:155], v[216:219], v[16:19]
	v_mfma_f32_16x16x32_bf16 v[16:19], v[164:167], v[220:223], v[16:19]
	s_setprio 0
	s_setprio 1
	v_mfma_f32_16x16x32_bf16 v[52:55], v[168:171], v[184:187], v[52:55]
	v_mfma_f32_16x16x32_bf16 v[52:55], v[172:175], v[188:191], v[52:55]
	v_mfma_f32_16x16x32_bf16 v[44:47], v[176:179], v[184:187], v[44:47]
	v_mfma_f32_16x16x32_bf16 v[44:47], v[180:183], v[188:191], v[44:47]
	v_mfma_f32_16x16x32_bf16 v[36:39], v[168:171], v[192:195], v[36:39]
	v_mfma_f32_16x16x32_bf16 v[36:39], v[172:175], v[204:207], v[36:39]
	v_mfma_f32_16x16x32_bf16 v[28:31], v[176:179], v[192:195], v[28:31]
	v_mfma_f32_16x16x32_bf16 v[28:31], v[180:183], v[204:207], v[28:31]
	v_mfma_f32_16x16x32_bf16 v[20:23], v[168:171], v[208:211], v[20:23]
	v_mfma_f32_16x16x32_bf16 v[20:23], v[172:175], v[212:215], v[20:23]
	v_mfma_f32_16x16x32_bf16 v[12:15], v[176:179], v[208:211], v[12:15]
	v_mfma_f32_16x16x32_bf16 v[12:15], v[180:183], v[212:215], v[12:15]
	v_mfma_f32_16x16x32_bf16 v[8:11], v[168:171], v[216:219], v[8:11]
	v_mfma_f32_16x16x32_bf16 v[8:11], v[172:175], v[220:223], v[8:11]
	s_setprio 2
	s_barrier
	v_mfma_f32_16x16x32_bf16 v[4:7], v[176:179], v[216:219], v[4:7]
	v_mfma_f32_16x16x32_bf16 v[4:7], v[180:183], v[220:223], v[4:7]
	s_setprio 0
	s_add_i32 s26, s26, 2
	s_add_u32 s38, s38, 0x100
	s_addc_u32 s39, s39, 0
	s_add_u32 s24, s24, 0x100
	s_addc_u32 s25, s25, 0
	s_cmp_gt_u32 s26, 29
	s_cbranch_scc1 .Lpeel_exit_218
.LBB0_218:
	s_add_u32 s27, s38, 0xfff80080
	s_addc_u32 s30, s39, -1
	s_add_i32 s31, 0, 0x10000
	s_cmp_eq_u32 s26, 28
	s_cselect_b32 s43, s11, s30
	s_cselect_b32 s42, s18, s27
	v_add_u32_e32 v156, s31, v145
	s_cselect_b32 s41, s9, s25
	s_cselect_b32 s40, s19, s24
	s_add_i32 s27, 0, 0x14000
	ds_read_b128 v[140:143], v156
	ds_read_b128 v[148:151], v156 offset:1024
	ds_read_b128 v[152:155], v156 offset:2048
	ds_read_b128 v[164:167], v156 offset:3072
	v_add_u32_e32 v156, s27, v145
	ds_read_b128 v[168:171], v156
	ds_read_b128 v[172:175], v156 offset:1024
	ds_read_b128 v[176:179], v156 offset:2048
	ds_read_b128 v[180:183], v156 offset:3072
	v_lshl_add_u64 v[156:157], s[38:39], 0, v[136:137]
	s_add_i32 m0, s58, 0xc000
	ds_read_b128 v[184:187], v147
	ds_read_b128 v[188:191], v147 offset:1024
	ds_read_b128 v[192:195], v147 offset:2048
	ds_read_b128 v[204:207], v147 offset:3072
	ds_read_b128 v[208:211], v147 offset:4096
	ds_read_b128 v[212:215], v147 offset:5120
	ds_read_b128 v[216:219], v147 offset:6144
	ds_read_b128 v[220:223], v147 offset:7168
	global_load_lds_dwordx4 v[156:157], off
	v_lshl_add_u64 v[156:157], s[38:39], 0, v[138:139]
	s_add_i32 m0, s58, 0xe000
	s_nop 0
	global_load_lds_dwordx4 v[156:157], off
	s_waitcnt vmcnt(8)
	s_waitcnt lgkmcnt(0)
	s_barrier
; #define PG8_STAGE(bufoff, gbase, voff) do { _Pragma("unroll") for (int _i = 0; _i < 2; ++_i) \
;         __builtin_amdgcn_global_load_lds((const unsigned*)((const char*)(gbase) + (voff)[_i]), (LAS unsigned*)(lds + (bufoff) + ldsw + _i * 8192), 16, 0, 0); } while (0)
; #define PG8_LDA(dst, b, h) do { _Pragma("unroll") for (int m = 0; m < 4; ++m) _Pragma("unroll") for (int k = 0; k < 2; ++k) dst[m][k] = *(const LAS bf16x8*)(lds + PG8_SA(b, h) + aoff + m * 2048 + k * 1024); } while (0)
; #define PG8_LDB(dst, b, h) do { _Pragma("unroll") for (int n = 0; n < 2; ++n) _Pragma("unroll") for (int k = 0; k < 2; ++k) dst[n][k] = *(const LAS bf16x8*)(lds + PG8_SB(b, h) + boff + n * 2048 + k * 1024); } while (0)
; #define PG8_MMA(ai, bj, At, Bt) do { __builtin_amdgcn_s_setprio(1); _Pragma("unroll") for (int m = 0; m < 4; ++m) _Pragma("unroll") for (int n = 0; n < 2; ++n) _Pragma("unroll") for (int k = 0; k < 2; ++k) \
;         acc[ai][bj][m][n] = __builtin_amdgcn_mfma_f32_16x16x32_bf16(Bt[n][k], At[m][k], acc[ai][bj][m][n], 0, 0, 0); __builtin_amdgcn_s_setprio(0); } while (0)
; #define PG8_WAIT_V(n) asm volatile("s_waitcnt vmcnt(" #n ")" ::: "memory")
; #define PG8_WAIT_L(n) asm volatile("s_waitcnt lgkmcnt(" #n ")" ::: "memory")
; #define PG8_BAR __builtin_amdgcn_s_barrier()
; #define PG8_SCHED __builtin_amdgcn_sched_barrier(0)
; template <class Epi, class Sched, bool ALIGN_EPI = true>
; __device__ __forceinline__ void gemm_phase(LAS unsigned char* lds, const Gemm g, const Sched& S, const Epi& E) {
;     ...
;             PG8_WAIT_V(8); PG8_WAIT_L(0); PG8_BAR; PG8_MMA(0, 0, At, B0); PG8_MMA(0, 1, At, B1); PG8_BAR; PG8_SCHED;
;             PG8_LDA(At, 0, 1); PG8_STAGE(PG8_SB(0, 0), b2, voffB); PG8_STAGE(PG8_SB(0, 1), b2 + hB, voffB); PG8_STAGE(PG8_SA(0, 0), a2, voffA);
;             PG8_WAIT_V(8); PG8_WAIT_L(0); PG8_BAR; PG8_MMA(1, 0, At, B0); PG8_MMA(1, 1, At, B1); PG8_BAR; PG8_SCHED;
;             PG8_LDB(B0, 1, 0); PG8_LDB(B1, 1, 1); PG8_SCHED; PG8_LDA(At, 1, 0); PG8_STAGE(PG8_SA(0, 1), a2 + hA, voffA);
	s_setprio 1
	s_waitcnt lgkmcnt(0)
	v_mfma_f32_16x16x32_bf16 v[128:131], v[140:143], v[184:187], v[128:131]
	v_mfma_f32_16x16x32_bf16 v[128:131], v[148:151], v[188:191], v[128:131]
	v_mfma_f32_16x16x32_bf16 v[124:127], v[152:155], v[184:187], v[124:127]
	v_mfma_f32_16x16x32_bf16 v[124:127], v[164:167], v[188:191], v[124:127]
	v_mfma_f32_16x16x32_bf16 v[120:123], v[140:143], v[192:195], v[120:123]
	v_mfma_f32_16x16x32_bf16 v[120:123], v[148:151], v[204:207], v[120:123]
	v_mfma_f32_16x16x32_bf16 v[112:115], v[152:155], v[192:195], v[112:115]
	v_mfma_f32_16x16x32_bf16 v[112:115], v[164:167], v[204:207], v[112:115]
	v_mfma_f32_16x16x32_bf16 v[104:107], v[140:143], v[208:211], v[104:107]
	v_mfma_f32_16x16x32_bf16 v[104:107], v[148:151], v[212:215], v[104:107]
	v_mfma_f32_16x16x32_bf16 v[96:99], v[152:155], v[208:211], v[96:99]
	v_mfma_f32_16x16x32_bf16 v[96:99], v[164:167], v[212:215], v[96:99]
	v_mfma_f32_16x16x32_bf16 v[88:91], v[140:143], v[216:219], v[88:91]
	v_mfma_f32_16x16x32_bf16 v[88:91], v[148:151], v[220:223], v[88:91]
	v_mfma_f32_16x16x32_bf16 v[80:83], v[152:155], v[216:219], v[80:83]
	v_mfma_f32_16x16x32_bf16 v[80:83], v[164:167], v[220:223], v[80:83]
	s_setprio 0
	s_setprio 1
	v_mfma_f32_16x16x32_bf16 v[116:119], v[168:171], v[184:187], v[116:119]
	v_mfma_f32_16x16x32_bf16 v[116:119], v[172:175], v[188:191], v[116:119]
	v_mfma_f32_16x16x32_bf16 v[108:111], v[176:179], v[184:187], v[108:111]
	v_mfma_f32_16x16x32_bf16 v[108:111], v[180:183], v[188:191], v[108:111]
	v_mfma_f32_16x16x32_bf16 v[100:103], v[168:171], v[192:195], v[100:103]
	v_mfma_f32_16x16x32_bf16 v[100:103], v[172:175], v[204:207], v[100:103]
	v_mfma_f32_16x16x32_bf16 v[92:95], v[176:179], v[192:195], v[92:95]
	v_mfma_f32_16x16x32_bf16 v[92:95], v[180:183], v[204:207], v[92:95]
	v_mfma_f32_16x16x32_bf16 v[84:87], v[168:171], v[208:211], v[84:87]
	v_mfma_f32_16x16x32_bf16 v[84:87], v[172:175], v[212:215], v[84:87]
	v_mfma_f32_16x16x32_bf16 v[76:79], v[176:179], v[208:211], v[76:79]
	v_mfma_f32_16x16x32_bf16 v[76:79], v[180:183], v[212:215], v[76:79]
	v_mfma_f32_16x16x32_bf16 v[72:75], v[168:171], v[216:219], v[72:75]
	v_mfma_f32_16x16x32_bf16 v[72:75], v[172:175], v[220:223], v[72:75]
	s_setprio 2
	s_barrier
	v_mfma_f32_16x16x32_bf16 v[68:71], v[176:179], v[216:219], v[68:71]
	v_mfma_f32_16x16x32_bf16 v[68:71], v[180:183], v[220:223], v[68:71]
	s_setprio 0
	s_add_i32 s30, s31, s53
	v_lshl_add_u64 v[156:157], s[40:41], 0, v[2:3]
	s_mov_b32 m0, s30
	s_nop 0
	global_load_lds_dwordx4 v[156:157], off
	s_add_i32 m0, s30, 0x2000
	s_add_u32 s30, s40, 0x80000
	v_lshl_add_u64 v[196:197], s[40:41], 0, v[0:1]
	s_addc_u32 s31, s41, 0
	s_add_i32 s27, s27, s53
	global_load_lds_dwordx4 v[196:197], off
	v_lshl_add_u64 v[224:225], s[30:31], 0, v[2:3]
	s_mov_b32 m0, s27
	v_lshl_add_u64 v[226:227], s[42:43], 0, v[132:133]
	global_load_lds_dwordx4 v[224:225], off
	v_lshl_add_u64 v[224:225], s[30:31], 0, v[0:1]
	s_add_i32 m0, s27, 0x2000
	s_nop 0
	global_load_lds_dwordx4 v[224:225], off
	v_lshl_add_u64 v[224:225], s[42:43], 0, v[134:135]
	s_mov_b32 m0, s58
	s_nop 0
	global_load_lds_dwordx4 v[224:225], off
	s_mov_b32 m0, s59
	s_nop 0
	global_load_lds_dwordx4 v[226:227], off
	ds_read_b128 v[184:187], v147 offset:16384
	ds_read_b128 v[188:191], v147 offset:17408
	ds_read_b128 v[192:195], v147 offset:18432
	ds_read_b128 v[204:207], v147 offset:19456
	ds_read_b128 v[208:211], v147 offset:20480
	ds_read_b128 v[212:215], v147 offset:21504
	ds_read_b128 v[216:219], v147 offset:22528
	ds_read_b128 v[220:223], v147 offset:23552
	s_waitcnt vmcnt(8)
	s_waitcnt lgkmcnt(0)
	s_barrier
	s_setprio 1
	s_waitcnt lgkmcnt(0)
	v_mfma_f32_16x16x32_bf16 v[64:67], v[140:143], v[184:187], v[64:67]
	v_mfma_f32_16x16x32_bf16 v[64:67], v[148:151], v[188:191], v[64:67]
	v_mfma_f32_16x16x32_bf16 v[60:63], v[152:155], v[184:187], v[60:63]
	v_mfma_f32_16x16x32_bf16 v[60:63], v[164:167], v[188:191], v[60:63]
	v_mfma_f32_16x16x32_bf16 v[56:59], v[140:143], v[192:195], v[56:59]
	v_mfma_f32_16x16x32_bf16 v[56:59], v[148:151], v[204:207], v[56:59]
	v_mfma_f32_16x16x32_bf16 v[48:51], v[152:155], v[192:195], v[48:51]
	v_mfma_f32_16x16x32_bf16 v[48:51], v[164:167], v[204:207], v[48:51]
	v_mfma_f32_16x16x32_bf16 v[40:43], v[140:143], v[208:211], v[40:43]
	v_mfma_f32_16x16x32_bf16 v[40:43], v[148:151], v[212:215], v[40:43]
	v_mfma_f32_16x16x32_bf16 v[32:35], v[152:155], v[208:211], v[32:35]
	v_mfma_f32_16x16x32_bf16 v[32:35], v[164:167], v[212:215], v[32:35]
	v_mfma_f32_16x16x32_bf16 v[24:27], v[140:143], v[216:219], v[24:27]
	v_mfma_f32_16x16x32_bf16 v[24:27], v[148:151], v[220:223], v[24:27]
	v_mfma_f32_16x16x32_bf16 v[16:19], v[152:155], v[216:219], v[16:19]
	v_mfma_f32_16x16x32_bf16 v[16:19], v[164:167], v[220:223], v[16:19]
	s_setprio 0
	s_setprio 1
	v_mfma_f32_16x16x32_bf16 v[52:55], v[168:171], v[184:187], v[52:55]
	v_mfma_f32_16x16x32_bf16 v[52:55], v[172:175], v[188:191], v[52:55]
	v_mfma_f32_16x16x32_bf16 v[44:47], v[176:179], v[184:187], v[44:47]
	v_mfma_f32_16x16x32_bf16 v[44:47], v[180:183], v[188:191], v[44:47]
	v_mfma_f32_16x16x32_bf16 v[36:39], v[168:171], v[192:195], v[36:39]
	v_mfma_f32_16x16x32_bf16 v[36:39], v[172:175], v[204:207], v[36:39]
	v_mfma_f32_16x16x32_bf16 v[28:31], v[176:179], v[192:195], v[28:31]
	v_mfma_f32_16x16x32_bf16 v[28:31], v[180:183], v[204:207], v[28:31]
	v_mfma_f32_16x16x32_bf16 v[20:23], v[168:171], v[208:211], v[20:23]
	v_mfma_f32_16x16x32_bf16 v[20:23], v[172:175], v[212:215], v[20:23]
	v_mfma_f32_16x16x32_bf16 v[12:15], v[176:179], v[208:211], v[12:15]
	v_mfma_f32_16x16x32_bf16 v[12:15], v[180:183], v[212:215], v[12:15]
	v_mfma_f32_16x16x32_bf16 v[8:11], v[168:171], v[216:219], v[8:11]
	v_mfma_f32_16x16x32_bf16 v[8:11], v[172:175], v[220:223], v[8:11]
	s_setprio 2
	s_barrier
; #define PG8_STAGE(bufoff, gbase, voff) do { _Pragma("unroll") for (int _i = 0; _i < 2; ++_i) \
;         __builtin_amdgcn_global_load_lds((const unsigned*)((const char*)(gbase) + (voff)[_i]), (LAS unsigned*)(lds + (bufoff) + ldsw + _i * 8192), 16, 0, 0); } while (0)
; #define PG8_LDA(dst, b, h) do { _Pragma("unroll") for (int m = 0; m < 4; ++m) _Pragma("unroll") for (int k = 0; k < 2; ++k) dst[m][k] = *(const LAS bf16x8*)(lds + PG8_SA(b, h) + aoff + m * 2048 + k * 1024); } while (0)
; #define PG8_LDB(dst, b, h) do { _Pragma("unroll") for (int n = 0; n < 2; ++n) _Pragma("unroll") for (int k = 0; k < 2; ++k) dst[n][k] = *(const LAS bf16x8*)(lds + PG8_SB(b, h) + boff + n * 2048 + k * 1024); } while (0)
; #define PG8_MMA(ai, bj, At, Bt) do { __builtin_amdgcn_s_setprio(1); _Pragma("unroll") for (int m = 0; m < 4; ++m) _Pragma("unroll") for (int n = 0; n < 2; ++n) _Pragma("unroll") for (int k = 0; k < 2; ++k) \
;         acc[ai][bj][m][n] = __builtin_amdgcn_mfma_f32_16x16x32_bf16(Bt[n][k], At[m][k], acc[ai][bj][m][n], 0, 0, 0); __builtin_amdgcn_s_setprio(0); } while (0)
; #define PG8_WAIT_V(n) asm volatile("s_waitcnt vmcnt(" #n ")" ::: "memory")
; #define PG8_WAIT_L(n) asm volatile("s_waitcnt lgkmcnt(" #n ")" ::: "memory")
; #define PG8_BAR __builtin_amdgcn_s_barrier()
; #define PG8_SCHED __builtin_amdgcn_sched_barrier(0)
; template <class Epi, class Sched, bool ALIGN_EPI = true>
; __device__ __forceinline__ void gemm_phase(LAS unsigned char* lds, const Gemm g, const Sched& S, const Epi& E) {
;     ...
;             PG8_LDB(B0, 1, 0); PG8_LDB(B1, 1, 1); PG8_SCHED; PG8_LDA(At, 1, 0); PG8_STAGE(PG8_SA(0, 1), a2 + hA, voffA);
;             PG8_WAIT_V(8); PG8_WAIT_L(0); PG8_BAR; PG8_MMA(0, 0, At, B0); PG8_MMA(0, 1, At, B1); PG8_BAR; PG8_SCHED;
;             PG8_LDA(At, 1, 1); PG8_STAGE(PG8_SB(1, 0), b3, voffB); PG8_STAGE(PG8_SB(1, 1), b3 + hB, voffB); PG8_STAGE(PG8_SA(1, 0), a3, voffA);
;             PG8_WAIT_V(8); PG8_WAIT_L(0); PG8_BAR; PG8_MMA(1, 0, At, B0); PG8_MMA(1, 1, At, B1); PG8_BAR; PG8_SCHED;
	v_mfma_f32_16x16x32_bf16 v[4:7], v[176:179], v[216:219], v[4:7]
	v_mfma_f32_16x16x32_bf16 v[4:7], v[180:183], v[220:223], v[4:7]
	s_setprio 0
	s_add_i32 s27, 0, 0x18000
	v_add_u32_e32 v158, s27, v145
	s_add_i32 s65, 0, 0x1c000
	ds_read_b128 v[140:143], v158
	ds_read_b128 v[148:151], v158 offset:1024
	ds_read_b128 v[152:155], v158 offset:2048
	ds_read_b128 v[164:167], v158 offset:3072
	v_add_u32_e32 v158, s65, v145
	ds_read_b128 v[168:171], v158
	ds_read_b128 v[172:175], v158 offset:1024
	ds_read_b128 v[176:179], v158 offset:2048
	ds_read_b128 v[180:183], v158 offset:3072
	s_add_u32 s30, s42, 0x80000
	s_addc_u32 s31, s43, 0
	s_mov_b32 m0, s60
	v_lshl_add_u64 v[228:229], s[30:31], 0, v[134:135]
	ds_read_b128 v[184:187], v147 offset:32768
	ds_read_b128 v[188:191], v147 offset:33792
	ds_read_b128 v[192:195], v147 offset:34816
	ds_read_b128 v[204:207], v147 offset:35840
	ds_read_b128 v[208:211], v147 offset:36864
	ds_read_b128 v[212:215], v147 offset:37888
	ds_read_b128 v[216:219], v147 offset:38912
	ds_read_b128 v[220:223], v147 offset:39936
	global_load_lds_dwordx4 v[228:229], off
	v_lshl_add_u64 v[228:229], s[30:31], 0, v[132:133]
	s_mov_b32 m0, s61
	s_nop 0
	global_load_lds_dwordx4 v[228:229], off
	s_waitcnt vmcnt(8)
	s_waitcnt lgkmcnt(0)
	s_barrier
	s_setprio 1
	s_waitcnt lgkmcnt(0)
	v_mfma_f32_16x16x32_bf16 v[128:131], v[140:143], v[184:187], v[128:131]
	v_mfma_f32_16x16x32_bf16 v[128:131], v[148:151], v[188:191], v[128:131]
	v_mfma_f32_16x16x32_bf16 v[124:127], v[152:155], v[184:187], v[124:127]
	v_mfma_f32_16x16x32_bf16 v[124:127], v[164:167], v[188:191], v[124:127]
	v_mfma_f32_16x16x32_bf16 v[120:123], v[140:143], v[192:195], v[120:123]
	v_mfma_f32_16x16x32_bf16 v[120:123], v[148:151], v[204:207], v[120:123]
	v_mfma_f32_16x16x32_bf16 v[112:115], v[152:155], v[192:195], v[112:115]
	v_mfma_f32_16x16x32_bf16 v[112:115], v[164:167], v[204:207], v[112:115]
	v_mfma_f32_16x16x32_bf16 v[104:107], v[140:143], v[208:211], v[104:107]
	v_mfma_f32_16x16x32_bf16 v[104:107], v[148:151], v[212:215], v[104:107]
	v_mfma_f32_16x16x32_bf16 v[96:99], v[152:155], v[208:211], v[96:99]
	v_mfma_f32_16x16x32_bf16 v[96:99], v[164:167], v[212:215], v[96:99]
	v_mfma_f32_16x16x32_bf16 v[88:91], v[140:143], v[216:219], v[88:91]
	v_mfma_f32_16x16x32_bf16 v[88:91], v[148:151], v[220:223], v[88:91]
	v_mfma_f32_16x16x32_bf16 v[80:83], v[152:155], v[216:219], v[80:83]
	v_mfma_f32_16x16x32_bf16 v[80:83], v[164:167], v[220:223], v[80:83]
	s_setprio 0
	s_setprio 1
	v_mfma_f32_16x16x32_bf16 v[116:119], v[168:171], v[184:187], v[116:119]
	v_mfma_f32_16x16x32_bf16 v[116:119], v[172:175], v[188:191], v[116:119]
	v_mfma_f32_16x16x32_bf16 v[108:111], v[176:179], v[184:187], v[108:111]
	v_mfma_f32_16x16x32_bf16 v[108:111], v[180:183], v[188:191], v[108:111]
	v_mfma_f32_16x16x32_bf16 v[100:103], v[168:171], v[192:195], v[100:103]
	v_mfma_f32_16x16x32_bf16 v[100:103], v[172:175], v[204:207], v[100:103]
	v_mfma_f32_16x16x32_bf16 v[92:95], v[176:179], v[192:195], v[92:95]
	v_mfma_f32_16x16x32_bf16 v[92:95], v[180:183], v[204:207], v[92:95]
	v_mfma_f32_16x16x32_bf16 v[84:87], v[168:171], v[208:211], v[84:87]
	v_mfma_f32_16x16x32_bf16 v[84:87], v[172:175], v[212:215], v[84:87]
	v_mfma_f32_16x16x32_bf16 v[76:79], v[176:179], v[208:211], v[76:79]
	v_mfma_f32_16x16x32_bf16 v[76:79], v[180:183], v[212:215], v[76:79]
	v_mfma_f32_16x16x32_bf16 v[72:75], v[168:171], v[216:219], v[72:75]
	v_mfma_f32_16x16x32_bf16 v[72:75], v[172:175], v[220:223], v[72:75]
	s_setprio 2
	s_barrier
; #define PG8_STAGE(bufoff, gbase, voff) do { _Pragma("unroll") for (int _i = 0; _i < 2; ++_i) \
;         __builtin_amdgcn_global_load_lds((const unsigned*)((const char*)(gbase) + (voff)[_i]), (LAS unsigned*)(lds + (bufoff) + ldsw + _i * 8192), 16, 0, 0); } while (0)
; #define PG8_LDA(dst, b, h) do { _Pragma("unroll") for (int m = 0; m < 4; ++m) _Pragma("unroll") for (int k = 0; k < 2; ++k) dst[m][k] = *(const LAS bf16x8*)(lds + PG8_SA(b, h) + aoff + m * 2048 + k * 1024); } while (0)
; #define PG8_MMA(ai, bj, At, Bt) do { __builtin_amdgcn_s_setprio(1); _Pragma("unroll") for (int m = 0; m < 4; ++m) _Pragma("unroll") for (int n = 0; n < 2; ++n) _Pragma("unroll") for (int k = 0; k < 2; ++k) \
;         acc[ai][bj][m][n] = __builtin_amdgcn_mfma_f32_16x16x32_bf16(Bt[n][k], At[m][k], acc[ai][bj][m][n], 0, 0, 0); __builtin_amdgcn_s_setprio(0); } while (0)
; #define PG8_WAIT_V(n) asm volatile("s_waitcnt vmcnt(" #n ")" ::: "memory")
; #define PG8_WAIT_L(n) asm volatile("s_waitcnt lgkmcnt(" #n ")" ::: "memory")
; #define PG8_BAR __builtin_amdgcn_s_barrier()
; #define PG8_SCHED __builtin_amdgcn_sched_barrier(0)
; template <class Epi, class Sched, bool ALIGN_EPI = true>
; __device__ __forceinline__ void gemm_phase(LAS unsigned char* lds, const Gemm g, const Sched& S, const Epi& E) {
;     ...
;             PG8_LDA(At, 1, 1); PG8_STAGE(PG8_SB(1, 0), b3, voffB); PG8_STAGE(PG8_SB(1, 1), b3 + hB, voffB); PG8_STAGE(PG8_SA(1, 0), a3, voffA);
;             PG8_WAIT_V(8); PG8_WAIT_L(0); PG8_BAR; PG8_MMA(1, 0, At, B0); PG8_MMA(1, 1, At, B1); PG8_BAR; PG8_SCHED;
;         }
	v_mfma_f32_16x16x32_bf16 v[68:71], v[176:179], v[216:219], v[68:71]
	v_mfma_f32_16x16x32_bf16 v[68:71], v[180:183], v[220:223], v[68:71]
	s_setprio 0
	s_add_i32 s27, s27, s53
	v_lshl_add_u64 v[156:157], v[156:157], 0, s[86:87]
	s_mov_b32 m0, s27
	s_nop 0
	global_load_lds_dwordx4 v[156:157], off
	s_add_i32 m0, s27, 0x2000
	s_add_u32 s30, s40, 0x80080
	v_lshl_add_u64 v[156:157], v[196:197], 0, s[86:87]
	s_addc_u32 s31, s41, 0
	s_add_i32 s27, s65, s53
	global_load_lds_dwordx4 v[156:157], off
	v_lshl_add_u64 v[156:157], s[30:31], 0, v[2:3]
	s_mov_b32 m0, s27
	s_nop 0
	global_load_lds_dwordx4 v[156:157], off
	v_lshl_add_u64 v[156:157], s[30:31], 0, v[0:1]
	s_add_i32 m0, s27, 0x2000
	s_nop 0
	global_load_lds_dwordx4 v[156:157], off
	v_lshl_add_u64 v[156:157], v[224:225], 0, s[86:87]
	s_mov_b32 m0, s62
	s_nop 0
	global_load_lds_dwordx4 v[156:157], off
	v_lshl_add_u64 v[156:157], v[226:227], 0, s[86:87]
	s_mov_b32 m0, s63
	s_nop 0
	global_load_lds_dwordx4 v[156:157], off
	ds_read_b128 v[184:187], v147 offset:49152
	ds_read_b128 v[188:191], v147 offset:50176
	ds_read_b128 v[192:195], v147 offset:51200
	ds_read_b128 v[204:207], v147 offset:52224
	ds_read_b128 v[208:211], v147 offset:53248
	ds_read_b128 v[212:215], v147 offset:54272
	ds_read_b128 v[216:219], v147 offset:55296
	ds_read_b128 v[220:223], v147 offset:56320
	s_waitcnt vmcnt(8)
	s_waitcnt lgkmcnt(0)
	s_barrier
	s_setprio 1
	s_waitcnt lgkmcnt(0)
	v_mfma_f32_16x16x32_bf16 v[64:67], v[140:143], v[184:187], v[64:67]
	v_mfma_f32_16x16x32_bf16 v[64:67], v[148:151], v[188:191], v[64:67]
	v_mfma_f32_16x16x32_bf16 v[60:63], v[152:155], v[184:187], v[60:63]
	v_mfma_f32_16x16x32_bf16 v[60:63], v[164:167], v[188:191], v[60:63]
	v_mfma_f32_16x16x32_bf16 v[56:59], v[140:143], v[192:195], v[56:59]
	v_mfma_f32_16x16x32_bf16 v[56:59], v[148:151], v[204:207], v[56:59]
	v_mfma_f32_16x16x32_bf16 v[48:51], v[152:155], v[192:195], v[48:51]
	v_mfma_f32_16x16x32_bf16 v[48:51], v[164:167], v[204:207], v[48:51]
	v_mfma_f32_16x16x32_bf16 v[40:43], v[140:143], v[208:211], v[40:43]
	v_mfma_f32_16x16x32_bf16 v[40:43], v[148:151], v[212:215], v[40:43]
	v_mfma_f32_16x16x32_bf16 v[32:35], v[152:155], v[208:211], v[32:35]
	v_mfma_f32_16x16x32_bf16 v[32:35], v[164:167], v[212:215], v[32:35]
	v_mfma_f32_16x16x32_bf16 v[24:27], v[140:143], v[216:219], v[24:27]
	v_mfma_f32_16x16x32_bf16 v[24:27], v[148:151], v[220:223], v[24:27]
	v_mfma_f32_16x16x32_bf16 v[16:19], v[152:155], v[216:219], v[16:19]
	v_mfma_f32_16x16x32_bf16 v[16:19], v[164:167], v[220:223], v[16:19]
	s_setprio 0
	s_setprio 1
	v_mfma_f32_16x16x32_bf16 v[52:55], v[168:171], v[184:187], v[52:55]
	v_mfma_f32_16x16x32_bf16 v[52:55], v[172:175], v[188:191], v[52:55]
	v_mfma_f32_16x16x32_bf16 v[44:47], v[176:179], v[184:187], v[44:47]
	v_mfma_f32_16x16x32_bf16 v[44:47], v[180:183], v[188:191], v[44:47]
	v_mfma_f32_16x16x32_bf16 v[36:39], v[168:171], v[192:195], v[36:39]
	v_mfma_f32_16x16x32_bf16 v[36:39], v[172:175], v[204:207], v[36:39]
	v_mfma_f32_16x16x32_bf16 v[28:31], v[176:179], v[192:195], v[28:31]
	v_mfma_f32_16x16x32_bf16 v[28:31], v[180:183], v[204:207], v[28:31]
	v_mfma_f32_16x16x32_bf16 v[20:23], v[168:171], v[208:211], v[20:23]
	v_mfma_f32_16x16x32_bf16 v[20:23], v[172:175], v[212:215], v[20:23]
	v_mfma_f32_16x16x32_bf16 v[12:15], v[176:179], v[208:211], v[12:15]
	v_mfma_f32_16x16x32_bf16 v[12:15], v[180:183], v[212:215], v[12:15]
	v_mfma_f32_16x16x32_bf16 v[8:11], v[168:171], v[216:219], v[8:11]
	v_mfma_f32_16x16x32_bf16 v[8:11], v[172:175], v[220:223], v[8:11]
	s_setprio 2
	s_barrier
	v_mfma_f32_16x16x32_bf16 v[4:7], v[176:179], v[216:219], v[4:7]
	v_mfma_f32_16x16x32_bf16 v[4:7], v[180:183], v[220:223], v[4:7]
	s_setprio 0
	s_add_i32 s26, s26, 2
	s_add_u32 s38, s38, 0x100
	s_addc_u32 s39, s39, 0
	s_add_u32 s24, s24, 0x100
	s_addc_u32 s25, s25, 0
	s_cmp_gt_u32 s26, 29
	s_cbranch_scc0 .LBB0_218

;     __device__ bool next(int i, Unit& u) const { if (i >= 2) return false; const int x = c & 7, j = c >> 3; u.pm = 32 * i + 4 * x + (j & 3); u.pn = j >> 2; return true; }
; #define PG8_STAGE(bufoff, gbase, voff) do { _Pragma("unroll") for (int _i = 0; _i < 2; ++_i) \
;         __builtin_amdgcn_global_load_lds((const unsigned*)((const char*)(gbase) + (voff)[_i]), (LAS unsigned*)(lds + (bufoff) + ldsw + _i * 8192), 16, 0, 0); } while (0)
; #define PG8_LDA(dst, b, h) do { _Pragma("unroll") for (int m = 0; m < 4; ++m) _Pragma("unroll") for (int k = 0; k < 2; ++k) dst[m][k] = *(const LAS bf16x8*)(lds + PG8_SA(b, h) + aoff + m * 2048 + k * 1024); } while (0)
; #define PG8_LDB(dst, b, h) do { _Pragma("unroll") for (int n = 0; n < 2; ++n) _Pragma("unroll") for (int k = 0; k < 2; ++k) dst[n][k] = *(const LAS bf16x8*)(lds + PG8_SB(b, h) + boff + n * 2048 + k * 1024); } while (0)
; #define PG8_WAIT_V(n) asm volatile("s_waitcnt vmcnt(" #n ")" ::: "memory")
; #define PG8_WAIT_L(n) asm volatile("s_waitcnt lgkmcnt(" #n ")" ::: "memory")
; #define PG8_BAR __builtin_amdgcn_s_barrier()
; template <class Epi, class Sched, bool ALIGN_EPI = true>
; __device__ __forceinline__ void gemm_phase(LAS unsigned char* lds, const Gemm g, const Sched& S, const Epi& E) {
;     ...
;         const bool has_next = S.next(ui + 1, nxt);
;         const char* nA = has_next ? (const char*)g.A + ((size_t)nxt.pm * BM * g.lda + (size_t)nxt.pn * g.a_pn_off) * 2 : cA; const char* nB = has_next ? (const char*)g.Bt + (size_t)nxt.pn * BM * g.ldb * 2 : cB;
;         for (int t = 0; t < nt; t += 2) {
;             const bool last = (t == nt - 2);
;             const char* a1 = cA + (size_t)(t + 1) * kstep;
;             const char* a2 = last ? nA : cA + (size_t)(t + 2) * kstep; const char* b2 = last ? nB : cB + (size_t)(t + 2) * kstep;
;             const char* a3 = a2 + kstep; const char* b3 = b2 + kstep;
;             PG8_LDB(B0, 0, 0); PG8_LDB(B1, 0, 1); PG8_SCHED; PG8_LDA(At, 0, 0); PG8_STAGE(PG8_SA(1, 1), a1 + hA, voffA);
;             PG8_WAIT_V(8); PG8_WAIT_L(0); PG8_BAR; PG8_MMA(0, 0, At, B0); PG8_MMA(0, 1, At, B1); PG8_BAR; PG8_SCHED;
;             PG8_LDA(At, 0, 1); PG8_STAGE(PG8_SB(0, 0), b2, voffB); PG8_STAGE(PG8_SB(0, 1), b2 + hB, voffB); PG8_STAGE(PG8_SA(0, 0), a2, voffA);
;             PG8_WAIT_V(8); PG8_WAIT_L(0); PG8_BAR; PG8_MMA(1, 0, At, B0); PG8_MMA(1, 1, At, B1); PG8_BAR; PG8_SCHED;
.LBB0_666:
	s_mov_b32 s82, s81
	s_or_b32 s81, s17, s68
	s_mov_b64 s[10:11], s[12:13]
	s_lshl_b32 s12, s81, 20
	s_add_u32 s12, s28, s12
	s_addc_u32 s13, s29, 0
	s_and_b64 s[16:17], s[38:39], exec
	s_cselect_b32 s16, s13, s11
	s_cselect_b32 s17, s12, s10
	s_add_u32 s18, s10, 0x100
	s_addc_u32 s19, s11, 0
	s_add_u32 s10, s10, 0x80080
	s_addc_u32 s11, s11, 0
	v_lshl_add_u64 v[132:133], s[10:11], 0, v[166:167]
	v_lshl_add_u64 v[134:135], s[10:11], 0, v[168:169]
	s_mov_b32 s24, -2
	s_mov_b64 s[10:11], 0
	s_add_u32 vcc_lo, s10, 0x100
	s_addc_u32 vcc_hi, s11, 0
	s_add_u32 s25, s18, s10
	s_addc_u32 s26, s19, s11
	s_add_i32 s27, 0, 0x10000
	s_cmp_eq_u32 s24, 28
	s_cselect_b32 s65, s16, s26
	s_cselect_b32 s26, 0, vcc_lo
	s_cselect_b32 s64, s17, s25
	s_cselect_b32 s25, 0, vcc_hi
	s_add_u32 s62, s14, s26
	v_add_u32_e32 v160, s27, v186
	s_addc_u32 s63, s15, s25
	s_add_i32 s25, 0, 0x14000
	ds_read_b128 v[136:139], v160
	ds_read_b128 v[140:143], v160 offset:1024
	ds_read_b128 v[144:147], v160 offset:2048
	ds_read_b128 v[170:173], v160 offset:3072
	v_add_u32_e32 v160, s25, v186
	ds_read_b128 v[174:177], v160
	ds_read_b128 v[178:181], v160 offset:1024
	ds_read_b128 v[182:185], v160 offset:2048
	ds_read_b128 v[208:211], v160 offset:3072
	v_lshl_add_u64 v[244:245], v[132:133], 0, s[10:11]
	s_add_i32 m0, s53, 0xc000
	ds_read_b128 v[212:215], v197
	ds_read_b128 v[216:219], v197 offset:1024
	ds_read_b128 v[220:223], v197 offset:2048
	ds_read_b128 v[224:227], v197 offset:3072
	ds_read_b128 v[228:231], v197 offset:4096
	ds_read_b128 v[232:235], v197 offset:5120
	ds_read_b128 v[236:239], v197 offset:6144
	ds_read_b128 v[240:243], v197 offset:7168
	global_load_lds_dwordx4 v[244:245], off
	v_lshl_add_u64 v[244:245], v[134:135], 0, s[10:11]
	s_add_i32 m0, s53, 0xe000
	s_nop 0
	global_load_lds_dwordx4 v[244:245], off
	s_waitcnt vmcnt(8)
	s_waitcnt lgkmcnt(0)
	s_barrier
	s_setprio 1
	s_waitcnt lgkmcnt(0)
	v_mfma_f32_16x16x32_bf16 v[36:39], v[136:139], v[212:215], 0
	v_mfma_f32_16x16x32_bf16 v[36:39], v[140:143], v[216:219], v[36:39]
	v_mfma_f32_16x16x32_bf16 v[40:43], v[144:147], v[212:215], 0
	v_mfma_f32_16x16x32_bf16 v[40:43], v[170:173], v[216:219], v[40:43]
	v_mfma_f32_16x16x32_bf16 v[68:71], v[136:139], v[220:223], 0
	v_mfma_f32_16x16x32_bf16 v[68:71], v[140:143], v[224:227], v[68:71]
	v_mfma_f32_16x16x32_bf16 v[72:75], v[144:147], v[220:223], 0
	v_mfma_f32_16x16x32_bf16 v[72:75], v[170:173], v[224:227], v[72:75]
	v_mfma_f32_16x16x32_bf16 v[100:103], v[136:139], v[228:231], 0
	v_mfma_f32_16x16x32_bf16 v[100:103], v[140:143], v[232:235], v[100:103]
	v_mfma_f32_16x16x32_bf16 v[104:107], v[144:147], v[228:231], 0
	v_mfma_f32_16x16x32_bf16 v[104:107], v[170:173], v[232:235], v[104:107]
	v_mfma_f32_16x16x32_bf16 v[128:131], v[136:139], v[236:239], 0
	v_mfma_f32_16x16x32_bf16 v[128:131], v[140:143], v[240:243], v[128:131]
	v_mfma_f32_16x16x32_bf16 v[124:127], v[144:147], v[236:239], 0
	v_mfma_f32_16x16x32_bf16 v[124:127], v[170:173], v[240:243], v[124:127]
	s_setprio 0
	s_setprio 1
	v_mfma_f32_16x16x32_bf16 v[8:11], v[174:177], v[212:215], 0
	v_mfma_f32_16x16x32_bf16 v[8:11], v[178:181], v[216:219], v[8:11]
	v_mfma_f32_16x16x32_bf16 v[4:7], v[182:185], v[212:215], 0
	v_mfma_f32_16x16x32_bf16 v[4:7], v[208:211], v[216:219], v[4:7]
	v_mfma_f32_16x16x32_bf16 v[32:35], v[174:177], v[220:223], 0
	v_mfma_f32_16x16x32_bf16 v[32:35], v[178:181], v[224:227], v[32:35]
	v_mfma_f32_16x16x32_bf16 v[28:31], v[182:185], v[220:223], 0
	v_mfma_f32_16x16x32_bf16 v[28:31], v[208:211], v[224:227], v[28:31]
	v_mfma_f32_16x16x32_bf16 v[56:59], v[174:177], v[228:231], 0
	v_mfma_f32_16x16x32_bf16 v[56:59], v[178:181], v[232:235], v[56:59]
	v_mfma_f32_16x16x32_bf16 v[52:55], v[182:185], v[228:231], 0
	v_mfma_f32_16x16x32_bf16 v[52:55], v[208:211], v[232:235], v[52:55]
	v_mfma_f32_16x16x32_bf16 v[80:83], v[174:177], v[236:239], 0
	v_mfma_f32_16x16x32_bf16 v[80:83], v[178:181], v[240:243], v[80:83]
	s_setprio 2
	s_barrier
	v_mfma_f32_16x16x32_bf16 v[76:79], v[182:185], v[236:239], 0
	v_mfma_f32_16x16x32_bf16 v[76:79], v[208:211], v[240:243], v[76:79]
	s_setprio 0
	s_add_i32 s10, s27, s67
	v_lshl_add_u64 v[244:245], s[62:63], 0, v[2:3]
	s_mov_b32 m0, s10
	s_nop 0
	global_load_lds_dwordx4 v[244:245], off
	s_add_i32 m0, s10, 0x2000
	s_add_u32 s10, s62, 0x80000
	v_lshl_add_u64 v[246:247], s[62:63], 0, v[150:151]
	s_addc_u32 s11, s63, 0
	s_add_i32 s25, s25, s67
	global_load_lds_dwordx4 v[246:247], off
	v_lshl_add_u64 v[248:249], s[10:11], 0, v[2:3]
	s_mov_b32 m0, s25
	v_lshl_add_u64 v[160:161], s[64:65], 0, v[148:149]
	global_load_lds_dwordx4 v[248:249], off
	v_lshl_add_u64 v[248:249], s[10:11], 0, v[150:151]
	s_add_i32 m0, s25, 0x2000
	s_nop 0
	global_load_lds_dwordx4 v[248:249], off
	v_lshl_add_u64 v[248:249], s[64:65], 0, v[0:1]
	s_mov_b32 m0, s53
	s_nop 0
	global_load_lds_dwordx4 v[248:249], off
	s_mov_b32 m0, s66
	s_nop 0
	global_load_lds_dwordx4 v[160:161], off
	ds_read_b128 v[212:215], v197 offset:16384
	ds_read_b128 v[216:219], v197 offset:17408
	ds_read_b128 v[220:223], v197 offset:18432
	ds_read_b128 v[224:227], v197 offset:19456
	ds_read_b128 v[228:231], v197 offset:20480
	ds_read_b128 v[232:235], v197 offset:21504
	ds_read_b128 v[236:239], v197 offset:22528
	ds_read_b128 v[240:243], v197 offset:23552
	s_waitcnt vmcnt(8)
	s_waitcnt lgkmcnt(0)
	s_barrier
; #define PG8_STAGE(bufoff, gbase, voff) do { _Pragma("unroll") for (int _i = 0; _i < 2; ++_i) \
;         __builtin_amdgcn_global_load_lds((const unsigned*)((const char*)(gbase) + (voff)[_i]), (LAS unsigned*)(lds + (bufoff) + ldsw + _i * 8192), 16, 0, 0); } while (0)
; #define PG8_LDA(dst, b, h) do { _Pragma("unroll") for (int m = 0; m < 4; ++m) _Pragma("unroll") for (int k = 0; k < 2; ++k) dst[m][k] = *(const LAS bf16x8*)(lds + PG8_SA(b, h) + aoff + m * 2048 + k * 1024); } while (0)
; #define PG8_LDB(dst, b, h) do { _Pragma("unroll") for (int n = 0; n < 2; ++n) _Pragma("unroll") for (int k = 0; k < 2; ++k) dst[n][k] = *(const LAS bf16x8*)(lds + PG8_SB(b, h) + boff + n * 2048 + k * 1024); } while (0)
; #define PG8_MMA(ai, bj, At, Bt) do { __builtin_amdgcn_s_setprio(1); _Pragma("unroll") for (int m = 0; m < 4; ++m) _Pragma("unroll") for (int n = 0; n < 2; ++n) _Pragma("unroll") for (int k = 0; k < 2; ++k) \
;         acc[ai][bj][m][n] = __builtin_amdgcn_mfma_f32_16x16x32_bf16(Bt[n][k], At[m][k], acc[ai][bj][m][n], 0, 0, 0); __builtin_amdgcn_s_setprio(0); } while (0)
; #define PG8_WAIT_V(n) asm volatile("s_waitcnt vmcnt(" #n ")" ::: "memory")
; #define PG8_WAIT_L(n) asm volatile("s_waitcnt lgkmcnt(" #n ")" ::: "memory")
; #define PG8_BAR __builtin_amdgcn_s_barrier()
; #define PG8_SCHED __builtin_amdgcn_sched_barrier(0)
; template <class Epi, class Sched, bool ALIGN_EPI = true>
; __device__ __forceinline__ void gemm_phase(LAS unsigned char* lds, const Gemm g, const Sched& S, const Epi& E) {
;     ...
;             PG8_WAIT_V(8); PG8_WAIT_L(0); PG8_BAR; PG8_MMA(1, 0, At, B0); PG8_MMA(1, 1, At, B1); PG8_BAR; PG8_SCHED;
;             PG8_LDB(B0, 1, 0); PG8_LDB(B1, 1, 1); PG8_SCHED; PG8_LDA(At, 1, 0); PG8_STAGE(PG8_SA(0, 1), a2 + hA, voffA);
;             PG8_WAIT_V(8); PG8_WAIT_L(0); PG8_BAR; PG8_MMA(0, 0, At, B0); PG8_MMA(0, 1, At, B1); PG8_BAR; PG8_SCHED;
	s_setprio 1
	s_waitcnt lgkmcnt(0)
	v_mfma_f32_16x16x32_bf16 v[120:123], v[136:139], v[212:215], 0
	v_mfma_f32_16x16x32_bf16 v[120:123], v[140:143], v[216:219], v[120:123]
	v_mfma_f32_16x16x32_bf16 v[116:119], v[144:147], v[212:215], 0
	v_mfma_f32_16x16x32_bf16 v[116:119], v[170:173], v[216:219], v[116:119]
	v_mfma_f32_16x16x32_bf16 v[96:99], v[136:139], v[220:223], 0
	v_mfma_f32_16x16x32_bf16 v[96:99], v[140:143], v[224:227], v[96:99]
	v_mfma_f32_16x16x32_bf16 v[92:95], v[144:147], v[220:223], 0
	v_mfma_f32_16x16x32_bf16 v[92:95], v[170:173], v[224:227], v[92:95]
	v_mfma_f32_16x16x32_bf16 v[64:67], v[136:139], v[228:231], 0
	v_mfma_f32_16x16x32_bf16 v[64:67], v[140:143], v[232:235], v[64:67]
	v_mfma_f32_16x16x32_bf16 v[60:63], v[144:147], v[228:231], 0
	v_mfma_f32_16x16x32_bf16 v[60:63], v[170:173], v[232:235], v[60:63]
	v_mfma_f32_16x16x32_bf16 v[24:27], v[136:139], v[236:239], 0
	v_mfma_f32_16x16x32_bf16 v[24:27], v[140:143], v[240:243], v[24:27]
	v_mfma_f32_16x16x32_bf16 v[20:23], v[144:147], v[236:239], 0
	v_mfma_f32_16x16x32_bf16 v[20:23], v[170:173], v[240:243], v[20:23]
	s_setprio 0
	s_setprio 1
	v_mfma_f32_16x16x32_bf16 v[112:115], v[174:177], v[212:215], 0
	v_mfma_f32_16x16x32_bf16 v[112:115], v[178:181], v[216:219], v[112:115]
	v_mfma_f32_16x16x32_bf16 v[108:111], v[182:185], v[212:215], 0
	v_mfma_f32_16x16x32_bf16 v[108:111], v[208:211], v[216:219], v[108:111]
	v_mfma_f32_16x16x32_bf16 v[88:91], v[174:177], v[220:223], 0
	v_mfma_f32_16x16x32_bf16 v[88:91], v[178:181], v[224:227], v[88:91]
	v_mfma_f32_16x16x32_bf16 v[84:87], v[182:185], v[220:223], 0
	v_mfma_f32_16x16x32_bf16 v[84:87], v[208:211], v[224:227], v[84:87]
	v_mfma_f32_16x16x32_bf16 v[48:51], v[174:177], v[228:231], 0
	v_mfma_f32_16x16x32_bf16 v[48:51], v[178:181], v[232:235], v[48:51]
	v_mfma_f32_16x16x32_bf16 v[44:47], v[182:185], v[228:231], 0
	v_mfma_f32_16x16x32_bf16 v[44:47], v[208:211], v[232:235], v[44:47]
	v_mfma_f32_16x16x32_bf16 v[16:19], v[174:177], v[236:239], 0
	v_mfma_f32_16x16x32_bf16 v[16:19], v[178:181], v[240:243], v[16:19]
	s_setprio 2
	s_barrier
	v_mfma_f32_16x16x32_bf16 v[12:15], v[182:185], v[236:239], 0
	v_mfma_f32_16x16x32_bf16 v[12:15], v[208:211], v[240:243], v[12:15]
	s_setprio 0
	s_add_i32 s25, 0, 0x18000
	v_add_u32_e32 v162, s25, v186
	s_add_i32 s26, 0, 0x1c000
	ds_read_b128 v[136:139], v162
	ds_read_b128 v[140:143], v162 offset:1024
	ds_read_b128 v[144:147], v162 offset:2048
	ds_read_b128 v[170:173], v162 offset:3072
	v_add_u32_e32 v162, s26, v186
	ds_read_b128 v[174:177], v162
	ds_read_b128 v[178:181], v162 offset:1024
	ds_read_b128 v[182:185], v162 offset:2048
	ds_read_b128 v[208:211], v162 offset:3072
	s_add_u32 s10, s64, 0x80000
	s_addc_u32 s11, s65, 0
	s_mov_b32 m0, s75
	v_lshl_add_u64 v[162:163], s[10:11], 0, v[0:1]
	ds_read_b128 v[212:215], v197 offset:32768
	ds_read_b128 v[216:219], v197 offset:33792
	ds_read_b128 v[220:223], v197 offset:34816
	ds_read_b128 v[224:227], v197 offset:35840
	ds_read_b128 v[228:231], v197 offset:36864
	ds_read_b128 v[232:235], v197 offset:37888
	ds_read_b128 v[236:239], v197 offset:38912
	ds_read_b128 v[240:243], v197 offset:39936
	global_load_lds_dwordx4 v[162:163], off
	v_lshl_add_u64 v[162:163], s[10:11], 0, v[148:149]
	s_mov_b32 m0, s76
	s_nop 0
	global_load_lds_dwordx4 v[162:163], off
	s_waitcnt vmcnt(8)
	s_waitcnt lgkmcnt(0)
	s_barrier
	s_setprio 1
	s_waitcnt lgkmcnt(0)
	v_mfma_f32_16x16x32_bf16 v[36:39], v[136:139], v[212:215], v[36:39]
	v_mfma_f32_16x16x32_bf16 v[36:39], v[140:143], v[216:219], v[36:39]
	v_mfma_f32_16x16x32_bf16 v[40:43], v[144:147], v[212:215], v[40:43]
	v_mfma_f32_16x16x32_bf16 v[40:43], v[170:173], v[216:219], v[40:43]
	v_mfma_f32_16x16x32_bf16 v[68:71], v[136:139], v[220:223], v[68:71]
	v_mfma_f32_16x16x32_bf16 v[68:71], v[140:143], v[224:227], v[68:71]
	v_mfma_f32_16x16x32_bf16 v[72:75], v[144:147], v[220:223], v[72:75]
	v_mfma_f32_16x16x32_bf16 v[72:75], v[170:173], v[224:227], v[72:75]
	v_mfma_f32_16x16x32_bf16 v[100:103], v[136:139], v[228:231], v[100:103]
	v_mfma_f32_16x16x32_bf16 v[100:103], v[140:143], v[232:235], v[100:103]
	v_mfma_f32_16x16x32_bf16 v[104:107], v[144:147], v[228:231], v[104:107]
	v_mfma_f32_16x16x32_bf16 v[104:107], v[170:173], v[232:235], v[104:107]
	v_mfma_f32_16x16x32_bf16 v[128:131], v[136:139], v[236:239], v[128:131]
	v_mfma_f32_16x16x32_bf16 v[128:131], v[140:143], v[240:243], v[128:131]
	v_mfma_f32_16x16x32_bf16 v[124:127], v[144:147], v[236:239], v[124:127]
	v_mfma_f32_16x16x32_bf16 v[124:127], v[170:173], v[240:243], v[124:127]
	s_setprio 0
	s_setprio 1
	v_mfma_f32_16x16x32_bf16 v[8:11], v[174:177], v[212:215], v[8:11]
	v_mfma_f32_16x16x32_bf16 v[8:11], v[178:181], v[216:219], v[8:11]
	v_mfma_f32_16x16x32_bf16 v[4:7], v[182:185], v[212:215], v[4:7]
	v_mfma_f32_16x16x32_bf16 v[4:7], v[208:211], v[216:219], v[4:7]
	v_mfma_f32_16x16x32_bf16 v[32:35], v[174:177], v[220:223], v[32:35]
	v_mfma_f32_16x16x32_bf16 v[32:35], v[178:181], v[224:227], v[32:35]
	v_mfma_f32_16x16x32_bf16 v[28:31], v[182:185], v[220:223], v[28:31]
	v_mfma_f32_16x16x32_bf16 v[28:31], v[208:211], v[224:227], v[28:31]
	v_mfma_f32_16x16x32_bf16 v[56:59], v[174:177], v[228:231], v[56:59]
	v_mfma_f32_16x16x32_bf16 v[56:59], v[178:181], v[232:235], v[56:59]
	v_mfma_f32_16x16x32_bf16 v[52:55], v[182:185], v[228:231], v[52:55]
	v_mfma_f32_16x16x32_bf16 v[52:55], v[208:211], v[232:235], v[52:55]
	v_mfma_f32_16x16x32_bf16 v[80:83], v[174:177], v[236:239], v[80:83]
	v_mfma_f32_16x16x32_bf16 v[80:83], v[178:181], v[240:243], v[80:83]
	s_setprio 2
	s_barrier
; #define PG8_STAGE(bufoff, gbase, voff) do { _Pragma("unroll") for (int _i = 0; _i < 2; ++_i) \
;         __builtin_amdgcn_global_load_lds((const unsigned*)((const char*)(gbase) + (voff)[_i]), (LAS unsigned*)(lds + (bufoff) + ldsw + _i * 8192), 16, 0, 0); } while (0)
; #define PG8_LDA(dst, b, h) do { _Pragma("unroll") for (int m = 0; m < 4; ++m) _Pragma("unroll") for (int k = 0; k < 2; ++k) dst[m][k] = *(const LAS bf16x8*)(lds + PG8_SA(b, h) + aoff + m * 2048 + k * 1024); } while (0)
; #define PG8_LDB(dst, b, h) do { _Pragma("unroll") for (int n = 0; n < 2; ++n) _Pragma("unroll") for (int k = 0; k < 2; ++k) dst[n][k] = *(const LAS bf16x8*)(lds + PG8_SB(b, h) + boff + n * 2048 + k * 1024); } while (0)
; #define PG8_WAIT_V(n) asm volatile("s_waitcnt vmcnt(" #n ")" ::: "memory")
; #define PG8_BAR __builtin_amdgcn_s_barrier()
; template <class Epi, class Sched, bool ALIGN_EPI = true>
; __device__ __forceinline__ void gemm_phase(LAS unsigned char* lds, const Gemm g, const Sched& S, const Epi& E) {
;     ...
;         for (int t = 0; t < nt; t += 2) {
;             const bool last = (t == nt - 2);
;             const char* a1 = cA + (size_t)(t + 1) * kstep;
;             const char* a2 = last ? nA : cA + (size_t)(t + 2) * kstep; const char* b2 = last ? nB : cB + (size_t)(t + 2) * kstep;
;             const char* a3 = a2 + kstep; const char* b3 = b2 + kstep;
;             PG8_LDB(B0, 0, 0); PG8_LDB(B1, 0, 1); PG8_SCHED; PG8_LDA(At, 0, 0); PG8_STAGE(PG8_SA(1, 1), a1 + hA, voffA);
;             PG8_WAIT_V(8); PG8_WAIT_L(0); PG8_BAR; PG8_MMA(0, 0, At, B0); PG8_MMA(0, 1, At, B1); PG8_BAR; PG8_SCHED;
;             PG8_LDA(At, 0, 1); PG8_STAGE(PG8_SB(0, 0), b2, voffB); PG8_STAGE(PG8_SB(0, 1), b2 + hB, voffB); PG8_STAGE(PG8_SA(0, 0), a2, voffA);
;             PG8_WAIT_V(8); PG8_WAIT_L(0); PG8_BAR; PG8_MMA(1, 0, At, B0); PG8_MMA(1, 1, At, B1); PG8_BAR; PG8_SCHED;
;             PG8_LDB(B0, 1, 0); PG8_LDB(B1, 1, 1); PG8_SCHED; PG8_LDA(At, 1, 0); PG8_STAGE(PG8_SA(0, 1), a2 + hA, voffA);
;             PG8_WAIT_V(8); PG8_WAIT_L(0); PG8_BAR; PG8_MMA(0, 0, At, B0); PG8_MMA(0, 1, At, B1); PG8_BAR; PG8_SCHED;
;             PG8_LDA(At, 1, 1); PG8_STAGE(PG8_SB(1, 0), b3, voffB); PG8_STAGE(PG8_SB(1, 1), b3 + hB, voffB); PG8_STAGE(PG8_SA(1, 0), a3, voffA);
;             PG8_WAIT_V(8); PG8_WAIT_L(0); PG8_BAR; PG8_MMA(1, 0, At, B0); PG8_MMA(1, 1, At, B1); PG8_BAR; PG8_SCHED;
	v_mfma_f32_16x16x32_bf16 v[76:79], v[182:185], v[236:239], v[76:79]
	v_mfma_f32_16x16x32_bf16 v[76:79], v[208:211], v[240:243], v[76:79]
	s_setprio 0
	s_add_i32 s10, s25, s67
	v_lshl_add_u64 v[162:163], v[244:245], 0, s[86:87]
	s_mov_b32 m0, s10
	s_nop 0
	global_load_lds_dwordx4 v[162:163], off
	s_add_i32 m0, s10, 0x2000
	s_add_u32 s10, s62, 0x80080
	v_lshl_add_u64 v[162:163], v[246:247], 0, s[86:87]
	s_addc_u32 s11, s63, 0
	s_add_i32 s25, s26, s67
	global_load_lds_dwordx4 v[162:163], off
	v_lshl_add_u64 v[162:163], s[10:11], 0, v[2:3]
	s_mov_b32 m0, s25
	v_lshl_add_u64 v[160:161], v[160:161], 0, s[86:87]
	global_load_lds_dwordx4 v[162:163], off
	v_lshl_add_u64 v[162:163], s[10:11], 0, v[150:151]
	s_add_i32 m0, s25, 0x2000
	s_nop 0
	global_load_lds_dwordx4 v[162:163], off
	v_lshl_add_u64 v[162:163], v[248:249], 0, s[86:87]
	s_mov_b32 m0, s79
	s_nop 0
	global_load_lds_dwordx4 v[162:163], off
	s_mov_b32 m0, s80
	s_nop 0
	global_load_lds_dwordx4 v[160:161], off
	ds_read_b128 v[212:215], v197 offset:49152
	ds_read_b128 v[216:219], v197 offset:50176
	ds_read_b128 v[220:223], v197 offset:51200
	ds_read_b128 v[224:227], v197 offset:52224
	ds_read_b128 v[228:231], v197 offset:53248
	ds_read_b128 v[232:235], v197 offset:54272
	ds_read_b128 v[236:239], v197 offset:55296
	ds_read_b128 v[240:243], v197 offset:56320
	s_waitcnt vmcnt(8)
	s_waitcnt lgkmcnt(0)
	s_barrier
	s_setprio 1
	s_waitcnt lgkmcnt(0)
	v_mfma_f32_16x16x32_bf16 v[120:123], v[136:139], v[212:215], v[120:123]
	v_mfma_f32_16x16x32_bf16 v[120:123], v[140:143], v[216:219], v[120:123]
	v_mfma_f32_16x16x32_bf16 v[116:119], v[144:147], v[212:215], v[116:119]
	v_mfma_f32_16x16x32_bf16 v[116:119], v[170:173], v[216:219], v[116:119]
	v_mfma_f32_16x16x32_bf16 v[96:99], v[136:139], v[220:223], v[96:99]
	v_mfma_f32_16x16x32_bf16 v[96:99], v[140:143], v[224:227], v[96:99]
	v_mfma_f32_16x16x32_bf16 v[92:95], v[144:147], v[220:223], v[92:95]
	v_mfma_f32_16x16x32_bf16 v[92:95], v[170:173], v[224:227], v[92:95]
	v_mfma_f32_16x16x32_bf16 v[64:67], v[136:139], v[228:231], v[64:67]
	v_mfma_f32_16x16x32_bf16 v[64:67], v[140:143], v[232:235], v[64:67]
	v_mfma_f32_16x16x32_bf16 v[60:63], v[144:147], v[228:231], v[60:63]
	v_mfma_f32_16x16x32_bf16 v[60:63], v[170:173], v[232:235], v[60:63]
	v_mfma_f32_16x16x32_bf16 v[24:27], v[136:139], v[236:239], v[24:27]
	v_mfma_f32_16x16x32_bf16 v[24:27], v[140:143], v[240:243], v[24:27]
	v_mfma_f32_16x16x32_bf16 v[20:23], v[144:147], v[236:239], v[20:23]
	v_mfma_f32_16x16x32_bf16 v[20:23], v[170:173], v[240:243], v[20:23]
	s_setprio 0
	s_setprio 1
	v_mfma_f32_16x16x32_bf16 v[112:115], v[174:177], v[212:215], v[112:115]
	v_mfma_f32_16x16x32_bf16 v[112:115], v[178:181], v[216:219], v[112:115]
	v_mfma_f32_16x16x32_bf16 v[108:111], v[182:185], v[212:215], v[108:111]
	v_mfma_f32_16x16x32_bf16 v[108:111], v[208:211], v[216:219], v[108:111]
	v_mfma_f32_16x16x32_bf16 v[88:91], v[174:177], v[220:223], v[88:91]
	v_mfma_f32_16x16x32_bf16 v[88:91], v[178:181], v[224:227], v[88:91]
	v_mfma_f32_16x16x32_bf16 v[84:87], v[182:185], v[220:223], v[84:87]
	v_mfma_f32_16x16x32_bf16 v[84:87], v[208:211], v[224:227], v[84:87]
	v_mfma_f32_16x16x32_bf16 v[48:51], v[174:177], v[228:231], v[48:51]
	v_mfma_f32_16x16x32_bf16 v[48:51], v[178:181], v[232:235], v[48:51]
	v_mfma_f32_16x16x32_bf16 v[44:47], v[182:185], v[228:231], v[44:47]
	v_mfma_f32_16x16x32_bf16 v[44:47], v[208:211], v[232:235], v[44:47]
	v_mfma_f32_16x16x32_bf16 v[16:19], v[174:177], v[236:239], v[16:19]
	v_mfma_f32_16x16x32_bf16 v[16:19], v[178:181], v[240:243], v[16:19]
	s_setprio 2
	s_barrier
	v_mfma_f32_16x16x32_bf16 v[12:15], v[182:185], v[236:239], v[12:15]
	v_mfma_f32_16x16x32_bf16 v[12:15], v[208:211], v[240:243], v[12:15]
	s_setprio 0
	s_add_i32 s24, s24, 2
	s_cmp_gt_u32 s24, 29
	s_mov_b64 s[10:11], vcc
	s_cbranch_scc1 .Lpeel_exit_667
.LBB0_667:
	s_add_u32 vcc_lo, s10, 0x100
	s_addc_u32 vcc_hi, s11, 0
	s_add_u32 s25, s18, s10
	s_addc_u32 s26, s19, s11
	s_add_i32 s27, 0, 0x10000
	s_cmp_eq_u32 s24, 28
	s_cselect_b32 s65, s16, s26
	s_cselect_b32 s26, 0, vcc_lo
	s_cselect_b32 s64, s17, s25
	s_cselect_b32 s25, 0, vcc_hi
	s_add_u32 s62, s14, s26
	v_add_u32_e32 v160, s27, v186
	s_addc_u32 s63, s15, s25
	s_add_i32 s25, 0, 0x14000
	ds_read_b128 v[136:139], v160
	ds_read_b128 v[140:143], v160 offset:1024
	ds_read_b128 v[144:147], v160 offset:2048
	ds_read_b128 v[170:173], v160 offset:3072
	v_add_u32_e32 v160, s25, v186
	ds_read_b128 v[174:177], v160
	ds_read_b128 v[178:181], v160 offset:1024
	ds_read_b128 v[182:185], v160 offset:2048
	ds_read_b128 v[208:211], v160 offset:3072
	v_lshl_add_u64 v[244:245], v[132:133], 0, s[10:11]
	s_add_i32 m0, s53, 0xc000
	ds_read_b128 v[212:215], v197
	ds_read_b128 v[216:219], v197 offset:1024
	ds_read_b128 v[220:223], v197 offset:2048
	ds_read_b128 v[224:227], v197 offset:3072
	ds_read_b128 v[228:231], v197 offset:4096
	ds_read_b128 v[232:235], v197 offset:5120
	ds_read_b128 v[236:239], v197 offset:6144
	ds_read_b128 v[240:243], v197 offset:7168
	global_load_lds_dwordx4 v[244:245], off
	v_lshl_add_u64 v[244:245], v[134:135], 0, s[10:11]
	s_add_i32 m0, s53, 0xe000
	s_nop 0
	global_load_lds_dwordx4 v[244:245], off
	s_waitcnt vmcnt(8)
	s_waitcnt lgkmcnt(0)
	s_barrier
; #define PG8_STAGE(bufoff, gbase, voff) do { _Pragma("unroll") for (int _i = 0; _i < 2; ++_i) \
;         __builtin_amdgcn_global_load_lds((const unsigned*)((const char*)(gbase) + (voff)[_i]), (LAS unsigned*)(lds + (bufoff) + ldsw + _i * 8192), 16, 0, 0); } while (0)
; #define PG8_LDA(dst, b, h) do { _Pragma("unroll") for (int m = 0; m < 4; ++m) _Pragma("unroll") for (int k = 0; k < 2; ++k) dst[m][k] = *(const LAS bf16x8*)(lds + PG8_SA(b, h) + aoff + m * 2048 + k * 1024); } while (0)
; #define PG8_MMA(ai, bj, At, Bt) do { __builtin_amdgcn_s_setprio(1); _Pragma("unroll") for (int m = 0; m < 4; ++m) _Pragma("unroll") for (int n = 0; n < 2; ++n) _Pragma("unroll") for (int k = 0; k < 2; ++k) \
;         acc[ai][bj][m][n] = __builtin_amdgcn_mfma_f32_16x16x32_bf16(Bt[n][k], At[m][k], acc[ai][bj][m][n], 0, 0, 0); __builtin_amdgcn_s_setprio(0); } while (0)
; #define PG8_WAIT_V(n) asm volatile("s_waitcnt vmcnt(" #n ")" ::: "memory")
; #define PG8_WAIT_L(n) asm volatile("s_waitcnt lgkmcnt(" #n ")" ::: "memory")
; #define PG8_BAR __builtin_amdgcn_s_barrier()
; #define PG8_SCHED __builtin_amdgcn_sched_barrier(0)
; template <class Epi, class Sched, bool ALIGN_EPI = true>
; __device__ __forceinline__ void gemm_phase(LAS unsigned char* lds, const Gemm g, const Sched& S, const Epi& E) {
;     ...
;             PG8_WAIT_V(8); PG8_WAIT_L(0); PG8_BAR; PG8_MMA(0, 0, At, B0); PG8_MMA(0, 1, At, B1); PG8_BAR; PG8_SCHED;
;             PG8_LDA(At, 0, 1); PG8_STAGE(PG8_SB(0, 0), b2, voffB); PG8_STAGE(PG8_SB(0, 1), b2 + hB, voffB); PG8_STAGE(PG8_SA(0, 0), a2, voffA);
;             PG8_WAIT_V(8); PG8_WAIT_L(0); PG8_BAR; PG8_MMA(1, 0, At, B0); PG8_MMA(1, 1, At, B1); PG8_BAR; PG8_SCHED;
	s_setprio 1
	s_waitcnt lgkmcnt(0)
	v_mfma_f32_16x16x32_bf16 v[36:39], v[136:139], v[212:215], v[36:39]
	v_mfma_f32_16x16x32_bf16 v[36:39], v[140:143], v[216:219], v[36:39]
	v_mfma_f32_16x16x32_bf16 v[40:43], v[144:147], v[212:215], v[40:43]
	v_mfma_f32_16x16x32_bf16 v[40:43], v[170:173], v[216:219], v[40:43]
	v_mfma_f32_16x16x32_bf16 v[68:71], v[136:139], v[220:223], v[68:71]
	v_mfma_f32_16x16x32_bf16 v[68:71], v[140:143], v[224:227], v[68:71]
	v_mfma_f32_16x16x32_bf16 v[72:75], v[144:147], v[220:223], v[72:75]
	v_mfma_f32_16x16x32_bf16 v[72:75], v[170:173], v[224:227], v[72:75]
	v_mfma_f32_16x16x32_bf16 v[100:103], v[136:139], v[228:231], v[100:103]
	v_mfma_f32_16x16x32_bf16 v[100:103], v[140:143], v[232:235], v[100:103]
	v_mfma_f32_16x16x32_bf16 v[104:107], v[144:147], v[228:231], v[104:107]
	v_mfma_f32_16x16x32_bf16 v[104:107], v[170:173], v[232:235], v[104:107]
	v_mfma_f32_16x16x32_bf16 v[128:131], v[136:139], v[236:239], v[128:131]
	v_mfma_f32_16x16x32_bf16 v[128:131], v[140:143], v[240:243], v[128:131]
	v_mfma_f32_16x16x32_bf16 v[124:127], v[144:147], v[236:239], v[124:127]
	v_mfma_f32_16x16x32_bf16 v[124:127], v[170:173], v[240:243], v[124:127]
	s_setprio 0
	s_setprio 1
	v_mfma_f32_16x16x32_bf16 v[8:11], v[174:177], v[212:215], v[8:11]
	v_mfma_f32_16x16x32_bf16 v[8:11], v[178:181], v[216:219], v[8:11]
	v_mfma_f32_16x16x32_bf16 v[4:7], v[182:185], v[212:215], v[4:7]
	v_mfma_f32_16x16x32_bf16 v[4:7], v[208:211], v[216:219], v[4:7]
	v_mfma_f32_16x16x32_bf16 v[32:35], v[174:177], v[220:223], v[32:35]
	v_mfma_f32_16x16x32_bf16 v[32:35], v[178:181], v[224:227], v[32:35]
	v_mfma_f32_16x16x32_bf16 v[28:31], v[182:185], v[220:223], v[28:31]
	v_mfma_f32_16x16x32_bf16 v[28:31], v[208:211], v[224:227], v[28:31]
	v_mfma_f32_16x16x32_bf16 v[56:59], v[174:177], v[228:231], v[56:59]
	v_mfma_f32_16x16x32_bf16 v[56:59], v[178:181], v[232:235], v[56:59]
	v_mfma_f32_16x16x32_bf16 v[52:55], v[182:185], v[228:231], v[52:55]
	v_mfma_f32_16x16x32_bf16 v[52:55], v[208:211], v[232:235], v[52:55]
	v_mfma_f32_16x16x32_bf16 v[80:83], v[174:177], v[236:239], v[80:83]
	v_mfma_f32_16x16x32_bf16 v[80:83], v[178:181], v[240:243], v[80:83]
	s_setprio 2
	s_barrier
	v_mfma_f32_16x16x32_bf16 v[76:79], v[182:185], v[236:239], v[76:79]
	v_mfma_f32_16x16x32_bf16 v[76:79], v[208:211], v[240:243], v[76:79]
	s_setprio 0
	s_add_i32 s10, s27, s67
	v_lshl_add_u64 v[244:245], s[62:63], 0, v[2:3]
	s_mov_b32 m0, s10
	s_nop 0
	global_load_lds_dwordx4 v[244:245], off
	s_add_i32 m0, s10, 0x2000
	s_add_u32 s10, s62, 0x80000
	v_lshl_add_u64 v[246:247], s[62:63], 0, v[150:151]
	s_addc_u32 s11, s63, 0
	s_add_i32 s25, s25, s67
	global_load_lds_dwordx4 v[246:247], off
	v_lshl_add_u64 v[248:249], s[10:11], 0, v[2:3]
	s_mov_b32 m0, s25
	v_lshl_add_u64 v[160:161], s[64:65], 0, v[148:149]
	global_load_lds_dwordx4 v[248:249], off
	v_lshl_add_u64 v[248:249], s[10:11], 0, v[150:151]
	s_add_i32 m0, s25, 0x2000
	s_nop 0
	global_load_lds_dwordx4 v[248:249], off
	v_lshl_add_u64 v[248:249], s[64:65], 0, v[0:1]
	s_mov_b32 m0, s53
	s_nop 0
	global_load_lds_dwordx4 v[248:249], off
	s_mov_b32 m0, s66
	s_nop 0
	global_load_lds_dwordx4 v[160:161], off
	ds_read_b128 v[212:215], v197 offset:16384
	ds_read_b128 v[216:219], v197 offset:17408
	ds_read_b128 v[220:223], v197 offset:18432
	ds_read_b128 v[224:227], v197 offset:19456
	ds_read_b128 v[228:231], v197 offset:20480
	ds_read_b128 v[232:235], v197 offset:21504
	ds_read_b128 v[236:239], v197 offset:22528
	ds_read_b128 v[240:243], v197 offset:23552
	s_waitcnt vmcnt(8)
	s_waitcnt lgkmcnt(0)
	s_barrier
	s_setprio 1
	s_waitcnt lgkmcnt(0)
	v_mfma_f32_16x16x32_bf16 v[120:123], v[136:139], v[212:215], v[120:123]
	v_mfma_f32_16x16x32_bf16 v[120:123], v[140:143], v[216:219], v[120:123]
	v_mfma_f32_16x16x32_bf16 v[116:119], v[144:147], v[212:215], v[116:119]
	v_mfma_f32_16x16x32_bf16 v[116:119], v[170:173], v[216:219], v[116:119]
	v_mfma_f32_16x16x32_bf16 v[96:99], v[136:139], v[220:223], v[96:99]
	v_mfma_f32_16x16x32_bf16 v[96:99], v[140:143], v[224:227], v[96:99]
	v_mfma_f32_16x16x32_bf16 v[92:95], v[144:147], v[220:223], v[92:95]
	v_mfma_f32_16x16x32_bf16 v[92:95], v[170:173], v[224:227], v[92:95]
	v_mfma_f32_16x16x32_bf16 v[64:67], v[136:139], v[228:231], v[64:67]
	v_mfma_f32_16x16x32_bf16 v[64:67], v[140:143], v[232:235], v[64:67]
	v_mfma_f32_16x16x32_bf16 v[60:63], v[144:147], v[228:231], v[60:63]
	v_mfma_f32_16x16x32_bf16 v[60:63], v[170:173], v[232:235], v[60:63]
	v_mfma_f32_16x16x32_bf16 v[24:27], v[136:139], v[236:239], v[24:27]
	v_mfma_f32_16x16x32_bf16 v[24:27], v[140:143], v[240:243], v[24:27]
	v_mfma_f32_16x16x32_bf16 v[20:23], v[144:147], v[236:239], v[20:23]
	v_mfma_f32_16x16x32_bf16 v[20:23], v[170:173], v[240:243], v[20:23]
	s_setprio 0
	s_setprio 1
	v_mfma_f32_16x16x32_bf16 v[112:115], v[174:177], v[212:215], v[112:115]
	v_mfma_f32_16x16x32_bf16 v[112:115], v[178:181], v[216:219], v[112:115]
	v_mfma_f32_16x16x32_bf16 v[108:111], v[182:185], v[212:215], v[108:111]
	v_mfma_f32_16x16x32_bf16 v[108:111], v[208:211], v[216:219], v[108:111]
	v_mfma_f32_16x16x32_bf16 v[88:91], v[174:177], v[220:223], v[88:91]
	v_mfma_f32_16x16x32_bf16 v[88:91], v[178:181], v[224:227], v[88:91]
	v_mfma_f32_16x16x32_bf16 v[84:87], v[182:185], v[220:223], v[84:87]
	v_mfma_f32_16x16x32_bf16 v[84:87], v[208:211], v[224:227], v[84:87]
	v_mfma_f32_16x16x32_bf16 v[48:51], v[174:177], v[228:231], v[48:51]
	v_mfma_f32_16x16x32_bf16 v[48:51], v[178:181], v[232:235], v[48:51]
	v_mfma_f32_16x16x32_bf16 v[44:47], v[182:185], v[228:231], v[44:47]
	v_mfma_f32_16x16x32_bf16 v[44:47], v[208:211], v[232:235], v[44:47]
	v_mfma_f32_16x16x32_bf16 v[16:19], v[174:177], v[236:239], v[16:19]
	v_mfma_f32_16x16x32_bf16 v[16:19], v[178:181], v[240:243], v[16:19]
	s_setprio 2
	s_barrier
; #define PG8_STAGE(bufoff, gbase, voff) do { _Pragma("unroll") for (int _i = 0; _i < 2; ++_i) \
;         __builtin_amdgcn_global_load_lds((const unsigned*)((const char*)(gbase) + (voff)[_i]), (LAS unsigned*)(lds + (bufoff) + ldsw + _i * 8192), 16, 0, 0); } while (0)
; #define PG8_LDA(dst, b, h) do { _Pragma("unroll") for (int m = 0; m < 4; ++m) _Pragma("unroll") for (int k = 0; k < 2; ++k) dst[m][k] = *(const LAS bf16x8*)(lds + PG8_SA(b, h) + aoff + m * 2048 + k * 1024); } while (0)
; #define PG8_LDB(dst, b, h) do { _Pragma("unroll") for (int n = 0; n < 2; ++n) _Pragma("unroll") for (int k = 0; k < 2; ++k) dst[n][k] = *(const LAS bf16x8*)(lds + PG8_SB(b, h) + boff + n * 2048 + k * 1024); } while (0)
; #define PG8_MMA(ai, bj, At, Bt) do { __builtin_amdgcn_s_setprio(1); _Pragma("unroll") for (int m = 0; m < 4; ++m) _Pragma("unroll") for (int n = 0; n < 2; ++n) _Pragma("unroll") for (int k = 0; k < 2; ++k) \
;         acc[ai][bj][m][n] = __builtin_amdgcn_mfma_f32_16x16x32_bf16(Bt[n][k], At[m][k], acc[ai][bj][m][n], 0, 0, 0); __builtin_amdgcn_s_setprio(0); } while (0)
; #define PG8_WAIT_V(n) asm volatile("s_waitcnt vmcnt(" #n ")" ::: "memory")
; #define PG8_WAIT_L(n) asm volatile("s_waitcnt lgkmcnt(" #n ")" ::: "memory")
; #define PG8_BAR __builtin_amdgcn_s_barrier()
; #define PG8_SCHED __builtin_amdgcn_sched_barrier(0)
; template <class Epi, class Sched, bool ALIGN_EPI = true>
; __device__ __forceinline__ void gemm_phase(LAS unsigned char* lds, const Gemm g, const Sched& S, const Epi& E) {
;     ...
;             PG8_WAIT_V(8); PG8_WAIT_L(0); PG8_BAR; PG8_MMA(1, 0, At, B0); PG8_MMA(1, 1, At, B1); PG8_BAR; PG8_SCHED;
;             PG8_LDB(B0, 1, 0); PG8_LDB(B1, 1, 1); PG8_SCHED; PG8_LDA(At, 1, 0); PG8_STAGE(PG8_SA(0, 1), a2 + hA, voffA);
;             PG8_WAIT_V(8); PG8_WAIT_L(0); PG8_BAR; PG8_MMA(0, 0, At, B0); PG8_MMA(0, 1, At, B1); PG8_BAR; PG8_SCHED;
	v_mfma_f32_16x16x32_bf16 v[12:15], v[182:185], v[236:239], v[12:15]
	v_mfma_f32_16x16x32_bf16 v[12:15], v[208:211], v[240:243], v[12:15]
	s_setprio 0
	s_add_i32 s25, 0, 0x18000
	v_add_u32_e32 v162, s25, v186
	s_add_i32 s26, 0, 0x1c000
	ds_read_b128 v[136:139], v162
	ds_read_b128 v[140:143], v162 offset:1024
	ds_read_b128 v[144:147], v162 offset:2048
	ds_read_b128 v[170:173], v162 offset:3072
	v_add_u32_e32 v162, s26, v186
	ds_read_b128 v[174:177], v162
	ds_read_b128 v[178:181], v162 offset:1024
	ds_read_b128 v[182:185], v162 offset:2048
	ds_read_b128 v[208:211], v162 offset:3072
	s_add_u32 s10, s64, 0x80000
	s_addc_u32 s11, s65, 0
	s_mov_b32 m0, s75
	v_lshl_add_u64 v[162:163], s[10:11], 0, v[0:1]
	ds_read_b128 v[212:215], v197 offset:32768
	ds_read_b128 v[216:219], v197 offset:33792
	ds_read_b128 v[220:223], v197 offset:34816
	ds_read_b128 v[224:227], v197 offset:35840
	ds_read_b128 v[228:231], v197 offset:36864
	ds_read_b128 v[232:235], v197 offset:37888
	ds_read_b128 v[236:239], v197 offset:38912
	ds_read_b128 v[240:243], v197 offset:39936
	global_load_lds_dwordx4 v[162:163], off
	v_lshl_add_u64 v[162:163], s[10:11], 0, v[148:149]
	s_mov_b32 m0, s76
	s_nop 0
	global_load_lds_dwordx4 v[162:163], off
	s_waitcnt vmcnt(8)
	s_waitcnt lgkmcnt(0)
	s_barrier
	s_setprio 1
	s_waitcnt lgkmcnt(0)
	v_mfma_f32_16x16x32_bf16 v[36:39], v[136:139], v[212:215], v[36:39]
	v_mfma_f32_16x16x32_bf16 v[36:39], v[140:143], v[216:219], v[36:39]
	v_mfma_f32_16x16x32_bf16 v[40:43], v[144:147], v[212:215], v[40:43]
	v_mfma_f32_16x16x32_bf16 v[40:43], v[170:173], v[216:219], v[40:43]
	v_mfma_f32_16x16x32_bf16 v[68:71], v[136:139], v[220:223], v[68:71]
	v_mfma_f32_16x16x32_bf16 v[68:71], v[140:143], v[224:227], v[68:71]
	v_mfma_f32_16x16x32_bf16 v[72:75], v[144:147], v[220:223], v[72:75]
	v_mfma_f32_16x16x32_bf16 v[72:75], v[170:173], v[224:227], v[72:75]
	v_mfma_f32_16x16x32_bf16 v[100:103], v[136:139], v[228:231], v[100:103]
	v_mfma_f32_16x16x32_bf16 v[100:103], v[140:143], v[232:235], v[100:103]
	v_mfma_f32_16x16x32_bf16 v[104:107], v[144:147], v[228:231], v[104:107]
	v_mfma_f32_16x16x32_bf16 v[104:107], v[170:173], v[232:235], v[104:107]
	v_mfma_f32_16x16x32_bf16 v[128:131], v[136:139], v[236:239], v[128:131]
	v_mfma_f32_16x16x32_bf16 v[128:131], v[140:143], v[240:243], v[128:131]
	v_mfma_f32_16x16x32_bf16 v[124:127], v[144:147], v[236:239], v[124:127]
	v_mfma_f32_16x16x32_bf16 v[124:127], v[170:173], v[240:243], v[124:127]
	s_setprio 0
	s_setprio 1
	v_mfma_f32_16x16x32_bf16 v[8:11], v[174:177], v[212:215], v[8:11]
	v_mfma_f32_16x16x32_bf16 v[8:11], v[178:181], v[216:219], v[8:11]
	v_mfma_f32_16x16x32_bf16 v[4:7], v[182:185], v[212:215], v[4:7]
	v_mfma_f32_16x16x32_bf16 v[4:7], v[208:211], v[216:219], v[4:7]
	v_mfma_f32_16x16x32_bf16 v[32:35], v[174:177], v[220:223], v[32:35]
	v_mfma_f32_16x16x32_bf16 v[32:35], v[178:181], v[224:227], v[32:35]
	v_mfma_f32_16x16x32_bf16 v[28:31], v[182:185], v[220:223], v[28:31]
	v_mfma_f32_16x16x32_bf16 v[28:31], v[208:211], v[224:227], v[28:31]
	v_mfma_f32_16x16x32_bf16 v[56:59], v[174:177], v[228:231], v[56:59]
	v_mfma_f32_16x16x32_bf16 v[56:59], v[178:181], v[232:235], v[56:59]
	v_mfma_f32_16x16x32_bf16 v[52:55], v[182:185], v[228:231], v[52:55]
	v_mfma_f32_16x16x32_bf16 v[52:55], v[208:211], v[232:235], v[52:55]
	v_mfma_f32_16x16x32_bf16 v[80:83], v[174:177], v[236:239], v[80:83]
	v_mfma_f32_16x16x32_bf16 v[80:83], v[178:181], v[240:243], v[80:83]
	s_setprio 2
	s_barrier
; #define PG8_STAGE(bufoff, gbase, voff) do { _Pragma("unroll") for (int _i = 0; _i < 2; ++_i) \
;         __builtin_amdgcn_global_load_lds((const unsigned*)((const char*)(gbase) + (voff)[_i]), (LAS unsigned*)(lds + (bufoff) + ldsw + _i * 8192), 16, 0, 0); } while (0)
; #define PG8_LDA(dst, b, h) do { _Pragma("unroll") for (int m = 0; m < 4; ++m) _Pragma("unroll") for (int k = 0; k < 2; ++k) dst[m][k] = *(const LAS bf16x8*)(lds + PG8_SA(b, h) + aoff + m * 2048 + k * 1024); } while (0)
; #define PG8_LDB(dst, b, h) do { _Pragma("unroll") for (int n = 0; n < 2; ++n) _Pragma("unroll") for (int k = 0; k < 2; ++k) dst[n][k] = *(const LAS bf16x8*)(lds + PG8_SB(b, h) + boff + n * 2048 + k * 1024); } while (0)
; #define PG8_WAIT_V(n) asm volatile("s_waitcnt vmcnt(" #n ")" ::: "memory")
; #define PG8_BAR __builtin_amdgcn_s_barrier()
; template <class Epi, class Sched, bool ALIGN_EPI = true>
; __device__ __forceinline__ void gemm_phase(LAS unsigned char* lds, const Gemm g, const Sched& S, const Epi& E) {
;     ...
;         for (int t = 0; t < nt; t += 2) {
;             const bool last = (t == nt - 2);
;             const char* a1 = cA + (size_t)(t + 1) * kstep;
;             const char* a2 = last ? nA : cA + (size_t)(t + 2) * kstep; const char* b2 = last ? nB : cB + (size_t)(t + 2) * kstep;
;             const char* a3 = a2 + kstep; const char* b3 = b2 + kstep;
;             PG8_LDB(B0, 0, 0); PG8_LDB(B1, 0, 1); PG8_SCHED; PG8_LDA(At, 0, 0); PG8_STAGE(PG8_SA(1, 1), a1 + hA, voffA);
;             PG8_WAIT_V(8); PG8_WAIT_L(0); PG8_BAR; PG8_MMA(0, 0, At, B0); PG8_MMA(0, 1, At, B1); PG8_BAR; PG8_SCHED;
;             PG8_LDA(At, 0, 1); PG8_STAGE(PG8_SB(0, 0), b2, voffB); PG8_STAGE(PG8_SB(0, 1), b2 + hB, voffB); PG8_STAGE(PG8_SA(0, 0), a2, voffA);
;             PG8_WAIT_V(8); PG8_WAIT_L(0); PG8_BAR; PG8_MMA(1, 0, At, B0); PG8_MMA(1, 1, At, B1); PG8_BAR; PG8_SCHED;
;             PG8_LDB(B0, 1, 0); PG8_LDB(B1, 1, 1); PG8_SCHED; PG8_LDA(At, 1, 0); PG8_STAGE(PG8_SA(0, 1), a2 + hA, voffA);
;             PG8_WAIT_V(8); PG8_WAIT_L(0); PG8_BAR; PG8_MMA(0, 0, At, B0); PG8_MMA(0, 1, At, B1); PG8_BAR; PG8_SCHED;
;             PG8_LDA(At, 1, 1); PG8_STAGE(PG8_SB(1, 0), b3, voffB); PG8_STAGE(PG8_SB(1, 1), b3 + hB, voffB); PG8_STAGE(PG8_SA(1, 0), a3, voffA);
;             PG8_WAIT_V(8); PG8_WAIT_L(0); PG8_BAR; PG8_MMA(1, 0, At, B0); PG8_MMA(1, 1, At, B1); PG8_BAR; PG8_SCHED;
	v_mfma_f32_16x16x32_bf16 v[76:79], v[182:185], v[236:239], v[76:79]
	v_mfma_f32_16x16x32_bf16 v[76:79], v[208:211], v[240:243], v[76:79]
	s_setprio 0
	s_add_i32 s10, s25, s67
	v_lshl_add_u64 v[162:163], v[244:245], 0, s[86:87]
	s_mov_b32 m0, s10
	s_nop 0
	global_load_lds_dwordx4 v[162:163], off
	s_add_i32 m0, s10, 0x2000
	s_add_u32 s10, s62, 0x80080
	v_lshl_add_u64 v[162:163], v[246:247], 0, s[86:87]
	s_addc_u32 s11, s63, 0
	s_add_i32 s25, s26, s67
	global_load_lds_dwordx4 v[162:163], off
	v_lshl_add_u64 v[162:163], s[10:11], 0, v[2:3]
	s_mov_b32 m0, s25
	v_lshl_add_u64 v[160:161], v[160:161], 0, s[86:87]
	global_load_lds_dwordx4 v[162:163], off
	v_lshl_add_u64 v[162:163], s[10:11], 0, v[150:151]
	s_add_i32 m0, s25, 0x2000
	s_nop 0
	global_load_lds_dwordx4 v[162:163], off
	v_lshl_add_u64 v[162:163], v[248:249], 0, s[86:87]
	s_mov_b32 m0, s79
	s_nop 0
	global_load_lds_dwordx4 v[162:163], off
	s_mov_b32 m0, s80
	s_nop 0
	global_load_lds_dwordx4 v[160:161], off
	ds_read_b128 v[212:215], v197 offset:49152
	ds_read_b128 v[216:219], v197 offset:50176
	ds_read_b128 v[220:223], v197 offset:51200
	ds_read_b128 v[224:227], v197 offset:52224
	ds_read_b128 v[228:231], v197 offset:53248
	ds_read_b128 v[232:235], v197 offset:54272
	ds_read_b128 v[236:239], v197 offset:55296
	ds_read_b128 v[240:243], v197 offset:56320
	s_waitcnt vmcnt(8)
	s_waitcnt lgkmcnt(0)
	s_barrier
	s_setprio 1
	s_waitcnt lgkmcnt(0)
	v_mfma_f32_16x16x32_bf16 v[120:123], v[136:139], v[212:215], v[120:123]
	v_mfma_f32_16x16x32_bf16 v[120:123], v[140:143], v[216:219], v[120:123]
	v_mfma_f32_16x16x32_bf16 v[116:119], v[144:147], v[212:215], v[116:119]
	v_mfma_f32_16x16x32_bf16 v[116:119], v[170:173], v[216:219], v[116:119]
	v_mfma_f32_16x16x32_bf16 v[96:99], v[136:139], v[220:223], v[96:99]
	v_mfma_f32_16x16x32_bf16 v[96:99], v[140:143], v[224:227], v[96:99]
	v_mfma_f32_16x16x32_bf16 v[92:95], v[144:147], v[220:223], v[92:95]
	v_mfma_f32_16x16x32_bf16 v[92:95], v[170:173], v[224:227], v[92:95]
	v_mfma_f32_16x16x32_bf16 v[64:67], v[136:139], v[228:231], v[64:67]
	v_mfma_f32_16x16x32_bf16 v[64:67], v[140:143], v[232:235], v[64:67]
	v_mfma_f32_16x16x32_bf16 v[60:63], v[144:147], v[228:231], v[60:63]
	v_mfma_f32_16x16x32_bf16 v[60:63], v[170:173], v[232:235], v[60:63]
	v_mfma_f32_16x16x32_bf16 v[24:27], v[136:139], v[236:239], v[24:27]
	v_mfma_f32_16x16x32_bf16 v[24:27], v[140:143], v[240:243], v[24:27]
	v_mfma_f32_16x16x32_bf16 v[20:23], v[144:147], v[236:239], v[20:23]
	v_mfma_f32_16x16x32_bf16 v[20:23], v[170:173], v[240:243], v[20:23]
	s_setprio 0
	s_setprio 1
	v_mfma_f32_16x16x32_bf16 v[112:115], v[174:177], v[212:215], v[112:115]
	v_mfma_f32_16x16x32_bf16 v[112:115], v[178:181], v[216:219], v[112:115]
	v_mfma_f32_16x16x32_bf16 v[108:111], v[182:185], v[212:215], v[108:111]
	v_mfma_f32_16x16x32_bf16 v[108:111], v[208:211], v[216:219], v[108:111]
	v_mfma_f32_16x16x32_bf16 v[88:91], v[174:177], v[220:223], v[88:91]
	v_mfma_f32_16x16x32_bf16 v[88:91], v[178:181], v[224:227], v[88:91]
	v_mfma_f32_16x16x32_bf16 v[84:87], v[182:185], v[220:223], v[84:87]
	v_mfma_f32_16x16x32_bf16 v[84:87], v[208:211], v[224:227], v[84:87]
	v_mfma_f32_16x16x32_bf16 v[48:51], v[174:177], v[228:231], v[48:51]
	v_mfma_f32_16x16x32_bf16 v[48:51], v[178:181], v[232:235], v[48:51]
	v_mfma_f32_16x16x32_bf16 v[44:47], v[182:185], v[228:231], v[44:47]
	v_mfma_f32_16x16x32_bf16 v[44:47], v[208:211], v[232:235], v[44:47]
	v_mfma_f32_16x16x32_bf16 v[16:19], v[174:177], v[236:239], v[16:19]
	v_mfma_f32_16x16x32_bf16 v[16:19], v[178:181], v[240:243], v[16:19]
	s_setprio 2
	s_barrier
	v_mfma_f32_16x16x32_bf16 v[12:15], v[182:185], v[236:239], v[12:15]
	v_mfma_f32_16x16x32_bf16 v[12:15], v[208:211], v[240:243], v[12:15]
	s_setprio 0
	s_add_i32 s24, s24, 2
	s_cmp_gt_u32 s24, 29
	s_mov_b64 s[10:11], vcc
	s_cbranch_scc0 .LBB0_667

;     __device__ bool next(int i, Unit& u) const { if (i >= 2) return false; const int x = c & 7, j = c >> 3; u.pm = 32 * i + 4 * x + (j & 3); u.pn = j >> 2; return true; }
; #define PG8_STAGE(bufoff, gbase, voff) do { _Pragma("unroll") for (int _i = 0; _i < 2; ++_i) \
;         __builtin_amdgcn_global_load_lds((const unsigned*)((const char*)(gbase) + (voff)[_i]), (LAS unsigned*)(lds + (bufoff) + ldsw + _i * 8192), 16, 0, 0); } while (0)
; #define PG8_WAIT_V(n) asm volatile("s_waitcnt vmcnt(" #n ")" ::: "memory")
; #define PG8_WAIT_L(n) asm volatile("s_waitcnt lgkmcnt(" #n ")" ::: "memory")
; #define PG8_BAR __builtin_amdgcn_s_barrier()
;     __device__ __forceinline__ void operator()(f32x4 (&acc)[2][2][4][2], const Unit& u, int wr, int wc, int fr_, int fq_, int wid, int lane_) const {
;     ...
;             const int t = wid * 64 + lane, kind = t >> 6, pr = t & 63, bj = kind >> 2, tap = kind & 3;
;             const float* src = (tap < 3) ? (cw + (size_t)tap * FF2 + bj * FF + u.pn * 128 + 2 * pr) : (cb + bj * FF + u.pn * 128 + 2 * pr);
;             const f32x2 wv = *(const f32x2*)src;
; template <class Epi, class Sched, bool ALIGN_EPI = true>
; __device__ __forceinline__ void gemm_phase(LAS unsigned char* lds, const Gemm g, const Sched& S, const Epi& E) {
;     ...
;         const bool has_next = S.next(ui + 1, nxt);
;         const char* nA = has_next ? (const char*)g.A + ((size_t)nxt.pm * BM * g.lda + (size_t)nxt.pn * g.a_pn_off) * 2 : cA; const char* nB = has_next ? (const char*)g.Bt + (size_t)nxt.pn * BM * g.ldb * 2 : cB;
;         for (int t = 0; t < nt; t += 2) {
;             const bool last = (t == nt - 2);
;             const char* a1 = cA + (size_t)(t + 1) * kstep;
;             const char* a2 = last ? nA : cA + (size_t)(t + 2) * kstep; const char* b2 = last ? nB : cB + (size_t)(t + 2) * kstep;
;             const char* a3 = a2 + kstep; const char* b3 = b2 + kstep;
;             PG8_LDB(B0, 0, 0); PG8_LDB(B1, 0, 1); PG8_SCHED; PG8_LDA(At, 0, 0); PG8_STAGE(PG8_SA(1, 1), a1 + hA, voffA);
;             PG8_WAIT_V(8); PG8_WAIT_L(0); PG8_BAR; PG8_MMA(0, 0, At, B0); PG8_MMA(0, 1, At, B1); PG8_BAR; PG8_SCHED;
;             PG8_LDA(At, 0, 1); PG8_STAGE(PG8_SB(0, 0), b2, voffB); PG8_STAGE(PG8_SB(0, 1), b2 + hB, voffB); PG8_STAGE(PG8_SA(0, 0), a2, voffA);
;             PG8_WAIT_V(8); PG8_WAIT_L(0); PG8_BAR; PG8_MMA(1, 0, At, B0); PG8_MMA(1, 1, At, B1); PG8_BAR; PG8_SCHED;
.LBB0_827:
	s_ashr_i32 s39, s38, 31
	s_lshl_b64 s[16:17], s[38:39], 20
	s_add_u32 s40, s46, s16
	s_addc_u32 s41, s47, s17
	s_and_b64 s[16:17], s[4:5], exec
	s_cselect_b32 s16, s41, s7
	s_cselect_b32 s17, s40, s6
	s_ashr_i32 s15, s14, 31
	s_lshl_b64 s[18:19], s[14:15], 20
	s_add_u32 s42, s53, s18
	s_addc_u32 s43, s60, s19
	s_and_b64 s[18:19], s[4:5], exec
	s_cselect_b32 s15, s43, s45
	s_cselect_b32 s18, s42, s44
	s_add_u32 s6, s6, 0x80080
	s_addc_u32 s7, s7, 0
	s_add_u32 s19, s44, 0x100
	s_addc_u32 s24, s45, 0
	s_mov_b32 s25, -2
	v_add_u32_e32 v228, s77, v158
	v_ashrrev_i32_e32 v229, 6, v228
	v_and_b32_e32 v230, 3, v229
	v_lshrrev_b32_e32 v231, 8, v228
	v_mul_u32_u24_e32 v228, 0x2c00, v230
	v_lshlrev_b32_e32 v228, 2, v228
	v_mov_b32_e32 v229, 0
	v_lshl_add_u64 v[232:233], s[2:3], 0, v[228:229]
	v_mov_b32_e32 v228, s9
	v_cmp_eq_u32_e32 vcc, 3, v230
	v_mul_i32_i24_e32 v234, 0x1600, v231
	v_ashrrev_i32_e32 v235, 31, v234
	v_cndmask_b32_e32 v233, v233, v228, vcc
	v_mov_b32_e32 v228, s8
	v_cndmask_b32_e32 v232, v232, v228, vcc
	v_lshl_add_u64 v[232:233], v[234:235], 2, v[232:233]
	s_lshl_b32 s26, s82, 7
	s_ashr_i32 s27, s26, 31
	v_lshl_add_u64 v[232:233], s[26:27], 2, v[232:233]
	v_and_b32_e32 v228, 63, v158
	v_lshlrev_b32_e32 v228, 3, v228
	v_mov_b32_e32 v229, 0
	v_lshl_add_u64 v[232:233], v[232:233], 0, v[228:229]
	global_load_dwordx2 v[226:227], v[232:233], off
	s_add_u32 s26, s6, 0xfff80080
	s_addc_u32 s27, s7, -1
	s_add_i32 s30, 0, 0x10000
	s_cmp_eq_u32 s25, 28
	s_cselect_b32 s59, s16, s27
	s_cselect_b32 s58, s17, s26
	v_add_u32_e32 v2, s30, v204
	s_cselect_b32 s45, s15, s24
	s_cselect_b32 s44, s18, s19
	s_add_i32 s31, 0, 0x14000
	ds_read_b128 v[132:135], v2
	ds_read_b128 v[136:139], v2 offset:1024
	ds_read_b128 v[140:143], v2 offset:2048
	ds_read_b128 v[144:147], v2 offset:3072
	v_add_u32_e32 v2, s31, v204
	ds_read_b128 v[148:151], v2
	ds_read_b128 v[152:155], v2 offset:1024
	ds_read_b128 v[174:177], v2 offset:2048
	ds_read_b128 v[178:181], v2 offset:3072
	v_lshl_add_u64 v[156:157], s[6:7], 0, v[170:171]
	s_add_i32 m0, s62, 0xc000
	ds_read_b128 v[182:185], v205
	ds_read_b128 v[186:189], v205 offset:1024
	ds_read_b128 v[190:193], v205 offset:2048
	ds_read_b128 v[194:197], v205 offset:3072
	ds_read_b128 v[206:209], v205 offset:4096
	ds_read_b128 v[210:213], v205 offset:5120
	ds_read_b128 v[214:217], v205 offset:6144
	ds_read_b128 v[218:221], v205 offset:7168
	global_load_lds_dwordx4 v[156:157], off
	v_lshl_add_u64 v[156:157], s[6:7], 0, v[172:173]
	s_add_i32 m0, s62, 0xe000
	s_nop 0
	global_load_lds_dwordx4 v[156:157], off
	s_waitcnt vmcnt(8)
	s_waitcnt lgkmcnt(0)
	s_barrier
	s_setprio 1
	s_waitcnt lgkmcnt(0)
	v_mfma_f32_16x16x32_bf16 v[116:119], v[132:135], v[182:185], 0
	v_mfma_f32_16x16x32_bf16 v[116:119], v[136:139], v[186:189], v[116:119]
	v_mfma_f32_16x16x32_bf16 v[100:103], v[140:143], v[182:185], 0
	v_mfma_f32_16x16x32_bf16 v[100:103], v[144:147], v[186:189], v[100:103]
	v_mfma_f32_16x16x32_bf16 v[108:111], v[132:135], v[190:193], 0
	v_mfma_f32_16x16x32_bf16 v[108:111], v[136:139], v[194:197], v[108:111]
	v_mfma_f32_16x16x32_bf16 v[96:99], v[140:143], v[190:193], 0
	v_mfma_f32_16x16x32_bf16 v[96:99], v[144:147], v[194:197], v[96:99]
	v_mfma_f32_16x16x32_bf16 v[88:91], v[132:135], v[206:209], 0
	v_mfma_f32_16x16x32_bf16 v[88:91], v[136:139], v[210:213], v[88:91]
	v_mfma_f32_16x16x32_bf16 v[84:87], v[140:143], v[206:209], 0
	v_mfma_f32_16x16x32_bf16 v[84:87], v[144:147], v[210:213], v[84:87]
	v_mfma_f32_16x16x32_bf16 v[72:75], v[132:135], v[214:217], 0
	v_mfma_f32_16x16x32_bf16 v[72:75], v[136:139], v[218:221], v[72:75]
	v_mfma_f32_16x16x32_bf16 v[80:83], v[140:143], v[214:217], 0
	v_mfma_f32_16x16x32_bf16 v[80:83], v[144:147], v[218:221], v[80:83]
	s_setprio 0
	s_setprio 1
	v_mfma_f32_16x16x32_bf16 v[128:131], v[148:151], v[182:185], 0
	v_mfma_f32_16x16x32_bf16 v[128:131], v[152:155], v[186:189], v[128:131]
	v_mfma_f32_16x16x32_bf16 v[44:47], v[174:177], v[182:185], 0
	v_mfma_f32_16x16x32_bf16 v[44:47], v[178:181], v[186:189], v[44:47]
	v_mfma_f32_16x16x32_bf16 v[124:127], v[148:151], v[190:193], 0
	v_mfma_f32_16x16x32_bf16 v[124:127], v[152:155], v[194:197], v[124:127]
	v_mfma_f32_16x16x32_bf16 v[36:39], v[174:177], v[190:193], 0
	v_mfma_f32_16x16x32_bf16 v[36:39], v[178:181], v[194:197], v[36:39]
	v_mfma_f32_16x16x32_bf16 v[120:123], v[148:151], v[206:209], 0
	v_mfma_f32_16x16x32_bf16 v[120:123], v[152:155], v[210:213], v[120:123]
	v_mfma_f32_16x16x32_bf16 v[32:35], v[174:177], v[206:209], 0
	v_mfma_f32_16x16x32_bf16 v[32:35], v[178:181], v[210:213], v[32:35]
	v_mfma_f32_16x16x32_bf16 v[112:115], v[148:151], v[214:217], 0
	v_mfma_f32_16x16x32_bf16 v[112:115], v[152:155], v[218:221], v[112:115]
	s_setprio 2
	s_barrier
	v_mfma_f32_16x16x32_bf16 v[28:31], v[174:177], v[214:217], 0
	v_mfma_f32_16x16x32_bf16 v[28:31], v[178:181], v[218:221], v[28:31]
	s_setprio 0
	s_add_i32 s26, s30, s61
	v_lshl_add_u64 v[156:157], s[44:45], 0, v[166:167]
	s_mov_b32 m0, s26
	s_nop 0
	global_load_lds_dwordx4 v[156:157], off
	s_add_i32 m0, s26, 0x2000
	s_add_u32 s26, s44, 0x80000
	v_lshl_add_u64 v[160:161], s[44:45], 0, v[0:1]
	s_addc_u32 s27, s45, 0
	s_add_i32 s30, s31, s61
	global_load_lds_dwordx4 v[160:161], off
	v_lshl_add_u64 v[162:163], s[26:27], 0, v[166:167]
	s_mov_b32 m0, s30
	v_lshl_add_u64 v[222:223], s[58:59], 0, v[164:165]
	global_load_lds_dwordx4 v[162:163], off
	v_lshl_add_u64 v[162:163], s[26:27], 0, v[0:1]
	s_add_i32 m0, s30, 0x2000
	s_nop 0
	global_load_lds_dwordx4 v[162:163], off
	v_lshl_add_u64 v[162:163], s[58:59], 0, v[168:169]
	s_mov_b32 m0, s62
	s_nop 0
	global_load_lds_dwordx4 v[162:163], off
	s_mov_b32 m0, s63
	s_nop 0
	global_load_lds_dwordx4 v[222:223], off
	ds_read_b128 v[182:185], v205 offset:16384
	ds_read_b128 v[186:189], v205 offset:17408
	ds_read_b128 v[190:193], v205 offset:18432
	ds_read_b128 v[194:197], v205 offset:19456
	ds_read_b128 v[206:209], v205 offset:20480
	ds_read_b128 v[210:213], v205 offset:21504
	ds_read_b128 v[214:217], v205 offset:22528
	ds_read_b128 v[218:221], v205 offset:23552
	s_waitcnt vmcnt(8)
	s_waitcnt lgkmcnt(0)
	s_barrier
; #define PG8_STAGE(bufoff, gbase, voff) do { _Pragma("unroll") for (int _i = 0; _i < 2; ++_i) \
;         __builtin_amdgcn_global_load_lds((const unsigned*)((const char*)(gbase) + (voff)[_i]), (LAS unsigned*)(lds + (bufoff) + ldsw + _i * 8192), 16, 0, 0); } while (0)
; #define PG8_LDA(dst, b, h) do { _Pragma("unroll") for (int m = 0; m < 4; ++m) _Pragma("unroll") for (int k = 0; k < 2; ++k) dst[m][k] = *(const LAS bf16x8*)(lds + PG8_SA(b, h) + aoff + m * 2048 + k * 1024); } while (0)
; #define PG8_LDB(dst, b, h) do { _Pragma("unroll") for (int n = 0; n < 2; ++n) _Pragma("unroll") for (int k = 0; k < 2; ++k) dst[n][k] = *(const LAS bf16x8*)(lds + PG8_SB(b, h) + boff + n * 2048 + k * 1024); } while (0)
; #define PG8_MMA(ai, bj, At, Bt) do { __builtin_amdgcn_s_setprio(1); _Pragma("unroll") for (int m = 0; m < 4; ++m) _Pragma("unroll") for (int n = 0; n < 2; ++n) _Pragma("unroll") for (int k = 0; k < 2; ++k) \
;         acc[ai][bj][m][n] = __builtin_amdgcn_mfma_f32_16x16x32_bf16(Bt[n][k], At[m][k], acc[ai][bj][m][n], 0, 0, 0); __builtin_amdgcn_s_setprio(0); } while (0)
; #define PG8_WAIT_V(n) asm volatile("s_waitcnt vmcnt(" #n ")" ::: "memory")
; #define PG8_WAIT_L(n) asm volatile("s_waitcnt lgkmcnt(" #n ")" ::: "memory")
; #define PG8_BAR __builtin_amdgcn_s_barrier()
; #define PG8_SCHED __builtin_amdgcn_sched_barrier(0)
; template <class Epi, class Sched, bool ALIGN_EPI = true>
; __device__ __forceinline__ void gemm_phase(LAS unsigned char* lds, const Gemm g, const Sched& S, const Epi& E) {
;     ...
;             PG8_WAIT_V(8); PG8_WAIT_L(0); PG8_BAR; PG8_MMA(1, 0, At, B0); PG8_MMA(1, 1, At, B1); PG8_BAR; PG8_SCHED;
;             PG8_LDB(B0, 1, 0); PG8_LDB(B1, 1, 1); PG8_SCHED; PG8_LDA(At, 1, 0); PG8_STAGE(PG8_SA(0, 1), a2 + hA, voffA);
;             PG8_WAIT_V(8); PG8_WAIT_L(0); PG8_BAR; PG8_MMA(0, 0, At, B0); PG8_MMA(0, 1, At, B1); PG8_BAR; PG8_SCHED;
	s_setprio 1
	s_waitcnt lgkmcnt(0)
	v_mfma_f32_16x16x32_bf16 v[60:63], v[132:135], v[182:185], 0
	v_mfma_f32_16x16x32_bf16 v[60:63], v[136:139], v[186:189], v[60:63]
	v_mfma_f32_16x16x32_bf16 v[68:71], v[140:143], v[182:185], 0
	v_mfma_f32_16x16x32_bf16 v[68:71], v[144:147], v[186:189], v[68:71]
	v_mfma_f32_16x16x32_bf16 v[40:43], v[132:135], v[190:193], 0
	v_mfma_f32_16x16x32_bf16 v[40:43], v[136:139], v[194:197], v[40:43]
	v_mfma_f32_16x16x32_bf16 v[64:67], v[140:143], v[190:193], 0
	v_mfma_f32_16x16x32_bf16 v[64:67], v[144:147], v[194:197], v[64:67]
	v_mfma_f32_16x16x32_bf16 v[24:27], v[132:135], v[206:209], 0
	v_mfma_f32_16x16x32_bf16 v[24:27], v[136:139], v[210:213], v[24:27]
	v_mfma_f32_16x16x32_bf16 v[56:59], v[140:143], v[206:209], 0
	v_mfma_f32_16x16x32_bf16 v[56:59], v[144:147], v[210:213], v[56:59]
	v_mfma_f32_16x16x32_bf16 v[12:15], v[132:135], v[214:217], 0
	v_mfma_f32_16x16x32_bf16 v[12:15], v[136:139], v[218:221], v[12:15]
	v_mfma_f32_16x16x32_bf16 v[48:51], v[140:143], v[214:217], 0
	v_mfma_f32_16x16x32_bf16 v[48:51], v[144:147], v[218:221], v[48:51]
	s_setprio 0
	s_setprio 1
	v_mfma_f32_16x16x32_bf16 v[104:107], v[148:151], v[182:185], 0
	v_mfma_f32_16x16x32_bf16 v[104:107], v[152:155], v[186:189], v[104:107]
	v_mfma_f32_16x16x32_bf16 v[20:23], v[174:177], v[182:185], 0
	v_mfma_f32_16x16x32_bf16 v[20:23], v[178:181], v[186:189], v[20:23]
	v_mfma_f32_16x16x32_bf16 v[92:95], v[148:151], v[190:193], 0
	v_mfma_f32_16x16x32_bf16 v[92:95], v[152:155], v[194:197], v[92:95]
	v_mfma_f32_16x16x32_bf16 v[16:19], v[174:177], v[190:193], 0
	v_mfma_f32_16x16x32_bf16 v[16:19], v[178:181], v[194:197], v[16:19]
	v_mfma_f32_16x16x32_bf16 v[76:79], v[148:151], v[206:209], 0
	v_mfma_f32_16x16x32_bf16 v[76:79], v[152:155], v[210:213], v[76:79]
	v_mfma_f32_16x16x32_bf16 v[8:11], v[174:177], v[206:209], 0
	v_mfma_f32_16x16x32_bf16 v[8:11], v[178:181], v[210:213], v[8:11]
	v_mfma_f32_16x16x32_bf16 v[52:55], v[148:151], v[214:217], 0
	v_mfma_f32_16x16x32_bf16 v[52:55], v[152:155], v[218:221], v[52:55]
	s_setprio 2
	s_barrier
	v_mfma_f32_16x16x32_bf16 v[4:7], v[174:177], v[214:217], 0
	v_mfma_f32_16x16x32_bf16 v[4:7], v[178:181], v[218:221], v[4:7]
	s_setprio 0
	s_add_i32 s30, 0, 0x18000
	v_add_u32_e32 v2, s30, v204
	s_add_i32 s31, 0, 0x1c000
	ds_read_b128 v[132:135], v2
	ds_read_b128 v[136:139], v2 offset:1024
	ds_read_b128 v[140:143], v2 offset:2048
	ds_read_b128 v[144:147], v2 offset:3072
	v_add_u32_e32 v2, s31, v204
	ds_read_b128 v[148:151], v2
	ds_read_b128 v[152:155], v2 offset:1024
	ds_read_b128 v[174:177], v2 offset:2048
	ds_read_b128 v[178:181], v2 offset:3072
	s_add_u32 s26, s58, 0x80000
	s_addc_u32 s27, s59, 0
	s_mov_b32 m0, s64
	v_lshl_add_u64 v[224:225], s[26:27], 0, v[168:169]
	ds_read_b128 v[182:185], v205 offset:32768
	ds_read_b128 v[186:189], v205 offset:33792
	ds_read_b128 v[190:193], v205 offset:34816
	ds_read_b128 v[194:197], v205 offset:35840
	ds_read_b128 v[206:209], v205 offset:36864
	ds_read_b128 v[210:213], v205 offset:37888
	ds_read_b128 v[214:217], v205 offset:38912
	ds_read_b128 v[218:221], v205 offset:39936
	global_load_lds_dwordx4 v[224:225], off
	v_lshl_add_u64 v[224:225], s[26:27], 0, v[164:165]
	s_mov_b32 m0, s65
	s_nop 0
	global_load_lds_dwordx4 v[224:225], off
	s_waitcnt vmcnt(8)
	s_waitcnt lgkmcnt(0)
	s_barrier
	s_setprio 1
	s_waitcnt lgkmcnt(0)
	v_mfma_f32_16x16x32_bf16 v[116:119], v[132:135], v[182:185], v[116:119]
	v_mfma_f32_16x16x32_bf16 v[116:119], v[136:139], v[186:189], v[116:119]
	v_mfma_f32_16x16x32_bf16 v[100:103], v[140:143], v[182:185], v[100:103]
	v_mfma_f32_16x16x32_bf16 v[100:103], v[144:147], v[186:189], v[100:103]
	v_mfma_f32_16x16x32_bf16 v[108:111], v[132:135], v[190:193], v[108:111]
	v_mfma_f32_16x16x32_bf16 v[108:111], v[136:139], v[194:197], v[108:111]
	v_mfma_f32_16x16x32_bf16 v[96:99], v[140:143], v[190:193], v[96:99]
	v_mfma_f32_16x16x32_bf16 v[96:99], v[144:147], v[194:197], v[96:99]
	v_mfma_f32_16x16x32_bf16 v[88:91], v[132:135], v[206:209], v[88:91]
	v_mfma_f32_16x16x32_bf16 v[88:91], v[136:139], v[210:213], v[88:91]
	v_mfma_f32_16x16x32_bf16 v[84:87], v[140:143], v[206:209], v[84:87]
	v_mfma_f32_16x16x32_bf16 v[84:87], v[144:147], v[210:213], v[84:87]
	v_mfma_f32_16x16x32_bf16 v[72:75], v[132:135], v[214:217], v[72:75]
	v_mfma_f32_16x16x32_bf16 v[72:75], v[136:139], v[218:221], v[72:75]
	v_mfma_f32_16x16x32_bf16 v[80:83], v[140:143], v[214:217], v[80:83]
	v_mfma_f32_16x16x32_bf16 v[80:83], v[144:147], v[218:221], v[80:83]
	s_setprio 0
	s_setprio 1
	v_mfma_f32_16x16x32_bf16 v[128:131], v[148:151], v[182:185], v[128:131]
	v_mfma_f32_16x16x32_bf16 v[128:131], v[152:155], v[186:189], v[128:131]
	v_mfma_f32_16x16x32_bf16 v[44:47], v[174:177], v[182:185], v[44:47]
	v_mfma_f32_16x16x32_bf16 v[44:47], v[178:181], v[186:189], v[44:47]
	v_mfma_f32_16x16x32_bf16 v[124:127], v[148:151], v[190:193], v[124:127]
	v_mfma_f32_16x16x32_bf16 v[124:127], v[152:155], v[194:197], v[124:127]
	v_mfma_f32_16x16x32_bf16 v[36:39], v[174:177], v[190:193], v[36:39]
	v_mfma_f32_16x16x32_bf16 v[36:39], v[178:181], v[194:197], v[36:39]
	v_mfma_f32_16x16x32_bf16 v[120:123], v[148:151], v[206:209], v[120:123]
	v_mfma_f32_16x16x32_bf16 v[120:123], v[152:155], v[210:213], v[120:123]
	v_mfma_f32_16x16x32_bf16 v[32:35], v[174:177], v[206:209], v[32:35]
	v_mfma_f32_16x16x32_bf16 v[32:35], v[178:181], v[210:213], v[32:35]
	v_mfma_f32_16x16x32_bf16 v[112:115], v[148:151], v[214:217], v[112:115]
	v_mfma_f32_16x16x32_bf16 v[112:115], v[152:155], v[218:221], v[112:115]
	s_setprio 2
	s_barrier
; #define PG8_STAGE(bufoff, gbase, voff) do { _Pragma("unroll") for (int _i = 0; _i < 2; ++_i) \
;         __builtin_amdgcn_global_load_lds((const unsigned*)((const char*)(gbase) + (voff)[_i]), (LAS unsigned*)(lds + (bufoff) + ldsw + _i * 8192), 16, 0, 0); } while (0)
; #define PG8_LDA(dst, b, h) do { _Pragma("unroll") for (int m = 0; m < 4; ++m) _Pragma("unroll") for (int k = 0; k < 2; ++k) dst[m][k] = *(const LAS bf16x8*)(lds + PG8_SA(b, h) + aoff + m * 2048 + k * 1024); } while (0)
; #define PG8_LDB(dst, b, h) do { _Pragma("unroll") for (int n = 0; n < 2; ++n) _Pragma("unroll") for (int k = 0; k < 2; ++k) dst[n][k] = *(const LAS bf16x8*)(lds + PG8_SB(b, h) + boff + n * 2048 + k * 1024); } while (0)
; #define PG8_WAIT_V(n) asm volatile("s_waitcnt vmcnt(" #n ")" ::: "memory")
; #define PG8_BAR __builtin_amdgcn_s_barrier()
; template <class Epi, class Sched, bool ALIGN_EPI = true>
; __device__ __forceinline__ void gemm_phase(LAS unsigned char* lds, const Gemm g, const Sched& S, const Epi& E) {
;     ...
;         for (int t = 0; t < nt; t += 2) {
;             const bool last = (t == nt - 2);
;             const char* a1 = cA + (size_t)(t + 1) * kstep;
;             const char* a2 = last ? nA : cA + (size_t)(t + 2) * kstep; const char* b2 = last ? nB : cB + (size_t)(t + 2) * kstep;
;             const char* a3 = a2 + kstep; const char* b3 = b2 + kstep;
;             PG8_LDB(B0, 0, 0); PG8_LDB(B1, 0, 1); PG8_SCHED; PG8_LDA(At, 0, 0); PG8_STAGE(PG8_SA(1, 1), a1 + hA, voffA);
;             PG8_WAIT_V(8); PG8_WAIT_L(0); PG8_BAR; PG8_MMA(0, 0, At, B0); PG8_MMA(0, 1, At, B1); PG8_BAR; PG8_SCHED;
;             PG8_LDA(At, 0, 1); PG8_STAGE(PG8_SB(0, 0), b2, voffB); PG8_STAGE(PG8_SB(0, 1), b2 + hB, voffB); PG8_STAGE(PG8_SA(0, 0), a2, voffA);
;             PG8_WAIT_V(8); PG8_WAIT_L(0); PG8_BAR; PG8_MMA(1, 0, At, B0); PG8_MMA(1, 1, At, B1); PG8_BAR; PG8_SCHED;
;             PG8_LDB(B0, 1, 0); PG8_LDB(B1, 1, 1); PG8_SCHED; PG8_LDA(At, 1, 0); PG8_STAGE(PG8_SA(0, 1), a2 + hA, voffA);
;             PG8_WAIT_V(8); PG8_WAIT_L(0); PG8_BAR; PG8_MMA(0, 0, At, B0); PG8_MMA(0, 1, At, B1); PG8_BAR; PG8_SCHED;
;             PG8_LDA(At, 1, 1); PG8_STAGE(PG8_SB(1, 0), b3, voffB); PG8_STAGE(PG8_SB(1, 1), b3 + hB, voffB); PG8_STAGE(PG8_SA(1, 0), a3, voffA);
;             PG8_WAIT_V(8); PG8_WAIT_L(0); PG8_BAR; PG8_MMA(1, 0, At, B0); PG8_MMA(1, 1, At, B1); PG8_BAR; PG8_SCHED;
	v_mfma_f32_16x16x32_bf16 v[28:31], v[174:177], v[214:217], v[28:31]
	v_mfma_f32_16x16x32_bf16 v[28:31], v[178:181], v[218:221], v[28:31]
	s_setprio 0
	s_add_i32 s26, s30, s61
	v_lshl_add_u64 v[156:157], v[156:157], 0, s[86:87]
	s_mov_b32 m0, s26
	s_nop 0
	global_load_lds_dwordx4 v[156:157], off
	s_add_i32 m0, s26, 0x2000
	s_add_u32 s26, s44, 0x80080
	v_lshl_add_u64 v[156:157], v[160:161], 0, s[86:87]
	s_addc_u32 s27, s45, 0
	s_add_i32 s30, s31, s61
	global_load_lds_dwordx4 v[156:157], off
	v_lshl_add_u64 v[156:157], s[26:27], 0, v[166:167]
	s_mov_b32 m0, s30
	s_nop 0
	global_load_lds_dwordx4 v[156:157], off
	v_lshl_add_u64 v[156:157], s[26:27], 0, v[0:1]
	s_add_i32 m0, s30, 0x2000
	s_nop 0
	global_load_lds_dwordx4 v[156:157], off
	v_lshl_add_u64 v[156:157], v[162:163], 0, s[86:87]
	s_mov_b32 m0, s75
	s_nop 0
	global_load_lds_dwordx4 v[156:157], off
	v_lshl_add_u64 v[156:157], v[222:223], 0, s[86:87]
	s_mov_b32 m0, s76
	s_nop 0
	global_load_lds_dwordx4 v[156:157], off
	ds_read_b128 v[182:185], v205 offset:49152
	ds_read_b128 v[186:189], v205 offset:50176
	ds_read_b128 v[190:193], v205 offset:51200
	ds_read_b128 v[194:197], v205 offset:52224
	ds_read_b128 v[206:209], v205 offset:53248
	ds_read_b128 v[210:213], v205 offset:54272
	ds_read_b128 v[214:217], v205 offset:55296
	ds_read_b128 v[218:221], v205 offset:56320
	s_waitcnt vmcnt(8)
	s_waitcnt lgkmcnt(0)
	s_barrier
	s_setprio 1
	s_waitcnt lgkmcnt(0)
	v_mfma_f32_16x16x32_bf16 v[60:63], v[132:135], v[182:185], v[60:63]
	v_mfma_f32_16x16x32_bf16 v[60:63], v[136:139], v[186:189], v[60:63]
	v_mfma_f32_16x16x32_bf16 v[68:71], v[140:143], v[182:185], v[68:71]
	v_mfma_f32_16x16x32_bf16 v[68:71], v[144:147], v[186:189], v[68:71]
	v_mfma_f32_16x16x32_bf16 v[40:43], v[132:135], v[190:193], v[40:43]
	v_mfma_f32_16x16x32_bf16 v[40:43], v[136:139], v[194:197], v[40:43]
	v_mfma_f32_16x16x32_bf16 v[64:67], v[140:143], v[190:193], v[64:67]
	v_mfma_f32_16x16x32_bf16 v[64:67], v[144:147], v[194:197], v[64:67]
	v_mfma_f32_16x16x32_bf16 v[24:27], v[132:135], v[206:209], v[24:27]
	v_mfma_f32_16x16x32_bf16 v[24:27], v[136:139], v[210:213], v[24:27]
	v_mfma_f32_16x16x32_bf16 v[56:59], v[140:143], v[206:209], v[56:59]
	v_mfma_f32_16x16x32_bf16 v[56:59], v[144:147], v[210:213], v[56:59]
	v_mfma_f32_16x16x32_bf16 v[12:15], v[132:135], v[214:217], v[12:15]
	v_mfma_f32_16x16x32_bf16 v[12:15], v[136:139], v[218:221], v[12:15]
	v_mfma_f32_16x16x32_bf16 v[48:51], v[140:143], v[214:217], v[48:51]
	v_mfma_f32_16x16x32_bf16 v[48:51], v[144:147], v[218:221], v[48:51]
	s_setprio 0
	s_setprio 1
	v_mfma_f32_16x16x32_bf16 v[104:107], v[148:151], v[182:185], v[104:107]
	v_mfma_f32_16x16x32_bf16 v[104:107], v[152:155], v[186:189], v[104:107]
	v_mfma_f32_16x16x32_bf16 v[20:23], v[174:177], v[182:185], v[20:23]
	v_mfma_f32_16x16x32_bf16 v[20:23], v[178:181], v[186:189], v[20:23]
	v_mfma_f32_16x16x32_bf16 v[92:95], v[148:151], v[190:193], v[92:95]
	v_mfma_f32_16x16x32_bf16 v[92:95], v[152:155], v[194:197], v[92:95]
	v_mfma_f32_16x16x32_bf16 v[16:19], v[174:177], v[190:193], v[16:19]
	v_mfma_f32_16x16x32_bf16 v[16:19], v[178:181], v[194:197], v[16:19]
	v_mfma_f32_16x16x32_bf16 v[76:79], v[148:151], v[206:209], v[76:79]
	v_mfma_f32_16x16x32_bf16 v[76:79], v[152:155], v[210:213], v[76:79]
	v_mfma_f32_16x16x32_bf16 v[8:11], v[174:177], v[206:209], v[8:11]
	v_mfma_f32_16x16x32_bf16 v[8:11], v[178:181], v[210:213], v[8:11]
	v_mfma_f32_16x16x32_bf16 v[52:55], v[148:151], v[214:217], v[52:55]
	v_mfma_f32_16x16x32_bf16 v[52:55], v[152:155], v[218:221], v[52:55]
	s_setprio 2
	s_barrier
	v_mfma_f32_16x16x32_bf16 v[4:7], v[174:177], v[214:217], v[4:7]
	v_mfma_f32_16x16x32_bf16 v[4:7], v[178:181], v[218:221], v[4:7]
	s_setprio 0
	s_add_i32 s25, s25, 2
	s_add_u32 s6, s6, 0x100
	s_addc_u32 s7, s7, 0
	s_add_u32 s19, s19, 0x100
	s_addc_u32 s24, s24, 0
	s_cmp_gt_u32 s25, 29
	s_cbranch_scc1 .Lpeel_exit_828
.LBB0_828:
	s_add_u32 s26, s6, 0xfff80080
	s_addc_u32 s27, s7, -1
	s_add_i32 s30, 0, 0x10000
	s_cmp_eq_u32 s25, 28
	s_cselect_b32 s59, s16, s27
	s_cselect_b32 s58, s17, s26
	v_add_u32_e32 v2, s30, v204
	s_cselect_b32 s45, s15, s24
	s_cselect_b32 s44, s18, s19
	s_add_i32 s31, 0, 0x14000
	ds_read_b128 v[132:135], v2
	ds_read_b128 v[136:139], v2 offset:1024
	ds_read_b128 v[140:143], v2 offset:2048
	ds_read_b128 v[144:147], v2 offset:3072
	v_add_u32_e32 v2, s31, v204
	ds_read_b128 v[148:151], v2
	ds_read_b128 v[152:155], v2 offset:1024
	ds_read_b128 v[174:177], v2 offset:2048
	ds_read_b128 v[178:181], v2 offset:3072
	v_lshl_add_u64 v[156:157], s[6:7], 0, v[170:171]
	s_add_i32 m0, s62, 0xc000
	ds_read_b128 v[182:185], v205
	ds_read_b128 v[186:189], v205 offset:1024
	ds_read_b128 v[190:193], v205 offset:2048
	ds_read_b128 v[194:197], v205 offset:3072
	ds_read_b128 v[206:209], v205 offset:4096
	ds_read_b128 v[210:213], v205 offset:5120
	ds_read_b128 v[214:217], v205 offset:6144
	ds_read_b128 v[218:221], v205 offset:7168
	global_load_lds_dwordx4 v[156:157], off
	v_lshl_add_u64 v[156:157], s[6:7], 0, v[172:173]
	s_add_i32 m0, s62, 0xe000
	s_nop 0
	global_load_lds_dwordx4 v[156:157], off
	s_waitcnt vmcnt(8)
	s_waitcnt lgkmcnt(0)
	s_barrier
; #define PG8_STAGE(bufoff, gbase, voff) do { _Pragma("unroll") for (int _i = 0; _i < 2; ++_i) \
;         __builtin_amdgcn_global_load_lds((const unsigned*)((const char*)(gbase) + (voff)[_i]), (LAS unsigned*)(lds + (bufoff) + ldsw + _i * 8192), 16, 0, 0); } while (0)
; #define PG8_LDA(dst, b, h) do { _Pragma("unroll") for (int m = 0; m < 4; ++m) _Pragma("unroll") for (int k = 0; k < 2; ++k) dst[m][k] = *(const LAS bf16x8*)(lds + PG8_SA(b, h) + aoff + m * 2048 + k * 1024); } while (0)
; #define PG8_MMA(ai, bj, At, Bt) do { __builtin_amdgcn_s_setprio(1); _Pragma("unroll") for (int m = 0; m < 4; ++m) _Pragma("unroll") for (int n = 0; n < 2; ++n) _Pragma("unroll") for (int k = 0; k < 2; ++k) \
;         acc[ai][bj][m][n] = __builtin_amdgcn_mfma_f32_16x16x32_bf16(Bt[n][k], At[m][k], acc[ai][bj][m][n], 0, 0, 0); __builtin_amdgcn_s_setprio(0); } while (0)
; #define PG8_WAIT_V(n) asm volatile("s_waitcnt vmcnt(" #n ")" ::: "memory")
; #define PG8_WAIT_L(n) asm volatile("s_waitcnt lgkmcnt(" #n ")" ::: "memory")
; #define PG8_BAR __builtin_amdgcn_s_barrier()
; #define PG8_SCHED __builtin_amdgcn_sched_barrier(0)
; template <class Epi, class Sched, bool ALIGN_EPI = true>
; __device__ __forceinline__ void gemm_phase(LAS unsigned char* lds, const Gemm g, const Sched& S, const Epi& E) {
;     ...
;             PG8_WAIT_V(8); PG8_WAIT_L(0); PG8_BAR; PG8_MMA(0, 0, At, B0); PG8_MMA(0, 1, At, B1); PG8_BAR; PG8_SCHED;
;             PG8_LDA(At, 0, 1); PG8_STAGE(PG8_SB(0, 0), b2, voffB); PG8_STAGE(PG8_SB(0, 1), b2 + hB, voffB); PG8_STAGE(PG8_SA(0, 0), a2, voffA);
;             PG8_WAIT_V(8); PG8_WAIT_L(0); PG8_BAR; PG8_MMA(1, 0, At, B0); PG8_MMA(1, 1, At, B1); PG8_BAR; PG8_SCHED;
	s_setprio 1
	s_waitcnt lgkmcnt(0)
	v_mfma_f32_16x16x32_bf16 v[116:119], v[132:135], v[182:185], v[116:119]
	v_mfma_f32_16x16x32_bf16 v[116:119], v[136:139], v[186:189], v[116:119]
	v_mfma_f32_16x16x32_bf16 v[100:103], v[140:143], v[182:185], v[100:103]
	v_mfma_f32_16x16x32_bf16 v[100:103], v[144:147], v[186:189], v[100:103]
	v_mfma_f32_16x16x32_bf16 v[108:111], v[132:135], v[190:193], v[108:111]
	v_mfma_f32_16x16x32_bf16 v[108:111], v[136:139], v[194:197], v[108:111]
	v_mfma_f32_16x16x32_bf16 v[96:99], v[140:143], v[190:193], v[96:99]
	v_mfma_f32_16x16x32_bf16 v[96:99], v[144:147], v[194:197], v[96:99]
	v_mfma_f32_16x16x32_bf16 v[88:91], v[132:135], v[206:209], v[88:91]
	v_mfma_f32_16x16x32_bf16 v[88:91], v[136:139], v[210:213], v[88:91]
	v_mfma_f32_16x16x32_bf16 v[84:87], v[140:143], v[206:209], v[84:87]
	v_mfma_f32_16x16x32_bf16 v[84:87], v[144:147], v[210:213], v[84:87]
	v_mfma_f32_16x16x32_bf16 v[72:75], v[132:135], v[214:217], v[72:75]
	v_mfma_f32_16x16x32_bf16 v[72:75], v[136:139], v[218:221], v[72:75]
	v_mfma_f32_16x16x32_bf16 v[80:83], v[140:143], v[214:217], v[80:83]
	v_mfma_f32_16x16x32_bf16 v[80:83], v[144:147], v[218:221], v[80:83]
	s_setprio 0
	s_setprio 1
	v_mfma_f32_16x16x32_bf16 v[128:131], v[148:151], v[182:185], v[128:131]
	v_mfma_f32_16x16x32_bf16 v[128:131], v[152:155], v[186:189], v[128:131]
	v_mfma_f32_16x16x32_bf16 v[44:47], v[174:177], v[182:185], v[44:47]
	v_mfma_f32_16x16x32_bf16 v[44:47], v[178:181], v[186:189], v[44:47]
	v_mfma_f32_16x16x32_bf16 v[124:127], v[148:151], v[190:193], v[124:127]
	v_mfma_f32_16x16x32_bf16 v[124:127], v[152:155], v[194:197], v[124:127]
	v_mfma_f32_16x16x32_bf16 v[36:39], v[174:177], v[190:193], v[36:39]
	v_mfma_f32_16x16x32_bf16 v[36:39], v[178:181], v[194:197], v[36:39]
	v_mfma_f32_16x16x32_bf16 v[120:123], v[148:151], v[206:209], v[120:123]
	v_mfma_f32_16x16x32_bf16 v[120:123], v[152:155], v[210:213], v[120:123]
	v_mfma_f32_16x16x32_bf16 v[32:35], v[174:177], v[206:209], v[32:35]
	v_mfma_f32_16x16x32_bf16 v[32:35], v[178:181], v[210:213], v[32:35]
	v_mfma_f32_16x16x32_bf16 v[112:115], v[148:151], v[214:217], v[112:115]
	v_mfma_f32_16x16x32_bf16 v[112:115], v[152:155], v[218:221], v[112:115]
	s_setprio 2
	s_barrier
	v_mfma_f32_16x16x32_bf16 v[28:31], v[174:177], v[214:217], v[28:31]
	v_mfma_f32_16x16x32_bf16 v[28:31], v[178:181], v[218:221], v[28:31]
	s_setprio 0
	s_add_i32 s26, s30, s61
	v_lshl_add_u64 v[156:157], s[44:45], 0, v[166:167]
	s_mov_b32 m0, s26
	s_nop 0
	global_load_lds_dwordx4 v[156:157], off
	s_add_i32 m0, s26, 0x2000
	s_add_u32 s26, s44, 0x80000
	v_lshl_add_u64 v[160:161], s[44:45], 0, v[0:1]
	s_addc_u32 s27, s45, 0
	s_add_i32 s30, s31, s61
	global_load_lds_dwordx4 v[160:161], off
	v_lshl_add_u64 v[162:163], s[26:27], 0, v[166:167]
	s_mov_b32 m0, s30
	v_lshl_add_u64 v[222:223], s[58:59], 0, v[164:165]
	global_load_lds_dwordx4 v[162:163], off
	v_lshl_add_u64 v[162:163], s[26:27], 0, v[0:1]
	s_add_i32 m0, s30, 0x2000
	s_nop 0
	global_load_lds_dwordx4 v[162:163], off
	v_lshl_add_u64 v[162:163], s[58:59], 0, v[168:169]
	s_mov_b32 m0, s62
	s_nop 0
	global_load_lds_dwordx4 v[162:163], off
	s_mov_b32 m0, s63
	s_nop 0
	global_load_lds_dwordx4 v[222:223], off
	ds_read_b128 v[182:185], v205 offset:16384
	ds_read_b128 v[186:189], v205 offset:17408
	ds_read_b128 v[190:193], v205 offset:18432
	ds_read_b128 v[194:197], v205 offset:19456
	ds_read_b128 v[206:209], v205 offset:20480
	ds_read_b128 v[210:213], v205 offset:21504
	ds_read_b128 v[214:217], v205 offset:22528
	ds_read_b128 v[218:221], v205 offset:23552
	s_waitcnt vmcnt(8)
	s_waitcnt lgkmcnt(0)
	s_barrier
	s_setprio 1
	s_waitcnt lgkmcnt(0)
	v_mfma_f32_16x16x32_bf16 v[60:63], v[132:135], v[182:185], v[60:63]
	v_mfma_f32_16x16x32_bf16 v[60:63], v[136:139], v[186:189], v[60:63]
	v_mfma_f32_16x16x32_bf16 v[68:71], v[140:143], v[182:185], v[68:71]
	v_mfma_f32_16x16x32_bf16 v[68:71], v[144:147], v[186:189], v[68:71]
	v_mfma_f32_16x16x32_bf16 v[40:43], v[132:135], v[190:193], v[40:43]
	v_mfma_f32_16x16x32_bf16 v[40:43], v[136:139], v[194:197], v[40:43]
	v_mfma_f32_16x16x32_bf16 v[64:67], v[140:143], v[190:193], v[64:67]
	v_mfma_f32_16x16x32_bf16 v[64:67], v[144:147], v[194:197], v[64:67]
	v_mfma_f32_16x16x32_bf16 v[24:27], v[132:135], v[206:209], v[24:27]
	v_mfma_f32_16x16x32_bf16 v[24:27], v[136:139], v[210:213], v[24:27]
	v_mfma_f32_16x16x32_bf16 v[56:59], v[140:143], v[206:209], v[56:59]
	v_mfma_f32_16x16x32_bf16 v[56:59], v[144:147], v[210:213], v[56:59]
	v_mfma_f32_16x16x32_bf16 v[12:15], v[132:135], v[214:217], v[12:15]
	v_mfma_f32_16x16x32_bf16 v[12:15], v[136:139], v[218:221], v[12:15]
	v_mfma_f32_16x16x32_bf16 v[48:51], v[140:143], v[214:217], v[48:51]
	v_mfma_f32_16x16x32_bf16 v[48:51], v[144:147], v[218:221], v[48:51]
	s_setprio 0
	s_setprio 1
	v_mfma_f32_16x16x32_bf16 v[104:107], v[148:151], v[182:185], v[104:107]
	v_mfma_f32_16x16x32_bf16 v[104:107], v[152:155], v[186:189], v[104:107]
	v_mfma_f32_16x16x32_bf16 v[20:23], v[174:177], v[182:185], v[20:23]
	v_mfma_f32_16x16x32_bf16 v[20:23], v[178:181], v[186:189], v[20:23]
	v_mfma_f32_16x16x32_bf16 v[92:95], v[148:151], v[190:193], v[92:95]
	v_mfma_f32_16x16x32_bf16 v[92:95], v[152:155], v[194:197], v[92:95]
	v_mfma_f32_16x16x32_bf16 v[16:19], v[174:177], v[190:193], v[16:19]
	v_mfma_f32_16x16x32_bf16 v[16:19], v[178:181], v[194:197], v[16:19]
	v_mfma_f32_16x16x32_bf16 v[76:79], v[148:151], v[206:209], v[76:79]
	v_mfma_f32_16x16x32_bf16 v[76:79], v[152:155], v[210:213], v[76:79]
	v_mfma_f32_16x16x32_bf16 v[8:11], v[174:177], v[206:209], v[8:11]
	v_mfma_f32_16x16x32_bf16 v[8:11], v[178:181], v[210:213], v[8:11]
	v_mfma_f32_16x16x32_bf16 v[52:55], v[148:151], v[214:217], v[52:55]
	v_mfma_f32_16x16x32_bf16 v[52:55], v[152:155], v[218:221], v[52:55]
	s_setprio 2
	s_barrier
; #define PG8_STAGE(bufoff, gbase, voff) do { _Pragma("unroll") for (int _i = 0; _i < 2; ++_i) \
;         __builtin_amdgcn_global_load_lds((const unsigned*)((const char*)(gbase) + (voff)[_i]), (LAS unsigned*)(lds + (bufoff) + ldsw + _i * 8192), 16, 0, 0); } while (0)
; #define PG8_LDA(dst, b, h) do { _Pragma("unroll") for (int m = 0; m < 4; ++m) _Pragma("unroll") for (int k = 0; k < 2; ++k) dst[m][k] = *(const LAS bf16x8*)(lds + PG8_SA(b, h) + aoff + m * 2048 + k * 1024); } while (0)
; #define PG8_LDB(dst, b, h) do { _Pragma("unroll") for (int n = 0; n < 2; ++n) _Pragma("unroll") for (int k = 0; k < 2; ++k) dst[n][k] = *(const LAS bf16x8*)(lds + PG8_SB(b, h) + boff + n * 2048 + k * 1024); } while (0)
; #define PG8_MMA(ai, bj, At, Bt) do { __builtin_amdgcn_s_setprio(1); _Pragma("unroll") for (int m = 0; m < 4; ++m) _Pragma("unroll") for (int n = 0; n < 2; ++n) _Pragma("unroll") for (int k = 0; k < 2; ++k) \
;         acc[ai][bj][m][n] = __builtin_amdgcn_mfma_f32_16x16x32_bf16(Bt[n][k], At[m][k], acc[ai][bj][m][n], 0, 0, 0); __builtin_amdgcn_s_setprio(0); } while (0)
; #define PG8_WAIT_V(n) asm volatile("s_waitcnt vmcnt(" #n ")" ::: "memory")
; #define PG8_WAIT_L(n) asm volatile("s_waitcnt lgkmcnt(" #n ")" ::: "memory")
; #define PG8_BAR __builtin_amdgcn_s_barrier()
; #define PG8_SCHED __builtin_amdgcn_sched_barrier(0)
; template <class Epi, class Sched, bool ALIGN_EPI = true>
; __device__ __forceinline__ void gemm_phase(LAS unsigned char* lds, const Gemm g, const Sched& S, const Epi& E) {
;     ...
;             PG8_WAIT_V(8); PG8_WAIT_L(0); PG8_BAR; PG8_MMA(1, 0, At, B0); PG8_MMA(1, 1, At, B1); PG8_BAR; PG8_SCHED;
;             PG8_LDB(B0, 1, 0); PG8_LDB(B1, 1, 1); PG8_SCHED; PG8_LDA(At, 1, 0); PG8_STAGE(PG8_SA(0, 1), a2 + hA, voffA);
;             PG8_WAIT_V(8); PG8_WAIT_L(0); PG8_BAR; PG8_MMA(0, 0, At, B0); PG8_MMA(0, 1, At, B1); PG8_BAR; PG8_SCHED;
	v_mfma_f32_16x16x32_bf16 v[4:7], v[174:177], v[214:217], v[4:7]
	v_mfma_f32_16x16x32_bf16 v[4:7], v[178:181], v[218:221], v[4:7]
	s_setprio 0
	s_add_i32 s30, 0, 0x18000
	v_add_u32_e32 v2, s30, v204
	s_add_i32 s31, 0, 0x1c000
	ds_read_b128 v[132:135], v2
	ds_read_b128 v[136:139], v2 offset:1024
	ds_read_b128 v[140:143], v2 offset:2048
	ds_read_b128 v[144:147], v2 offset:3072
	v_add_u32_e32 v2, s31, v204
	ds_read_b128 v[148:151], v2
	ds_read_b128 v[152:155], v2 offset:1024
	ds_read_b128 v[174:177], v2 offset:2048
	ds_read_b128 v[178:181], v2 offset:3072
	s_add_u32 s26, s58, 0x80000
	s_addc_u32 s27, s59, 0
	s_mov_b32 m0, s64
	v_lshl_add_u64 v[224:225], s[26:27], 0, v[168:169]
	ds_read_b128 v[182:185], v205 offset:32768
	ds_read_b128 v[186:189], v205 offset:33792
	ds_read_b128 v[190:193], v205 offset:34816
	ds_read_b128 v[194:197], v205 offset:35840
	ds_read_b128 v[206:209], v205 offset:36864
	ds_read_b128 v[210:213], v205 offset:37888
	ds_read_b128 v[214:217], v205 offset:38912
	ds_read_b128 v[218:221], v205 offset:39936
	global_load_lds_dwordx4 v[224:225], off
	v_lshl_add_u64 v[224:225], s[26:27], 0, v[164:165]
	s_mov_b32 m0, s65
	s_nop 0
	global_load_lds_dwordx4 v[224:225], off
	s_waitcnt vmcnt(8)
	s_waitcnt lgkmcnt(0)
	s_barrier
	s_setprio 1
	s_waitcnt lgkmcnt(0)
	v_mfma_f32_16x16x32_bf16 v[116:119], v[132:135], v[182:185], v[116:119]
	v_mfma_f32_16x16x32_bf16 v[116:119], v[136:139], v[186:189], v[116:119]
	v_mfma_f32_16x16x32_bf16 v[100:103], v[140:143], v[182:185], v[100:103]
	v_mfma_f32_16x16x32_bf16 v[100:103], v[144:147], v[186:189], v[100:103]
	v_mfma_f32_16x16x32_bf16 v[108:111], v[132:135], v[190:193], v[108:111]
	v_mfma_f32_16x16x32_bf16 v[108:111], v[136:139], v[194:197], v[108:111]
	v_mfma_f32_16x16x32_bf16 v[96:99], v[140:143], v[190:193], v[96:99]
	v_mfma_f32_16x16x32_bf16 v[96:99], v[144:147], v[194:197], v[96:99]
	v_mfma_f32_16x16x32_bf16 v[88:91], v[132:135], v[206:209], v[88:91]
	v_mfma_f32_16x16x32_bf16 v[88:91], v[136:139], v[210:213], v[88:91]
	v_mfma_f32_16x16x32_bf16 v[84:87], v[140:143], v[206:209], v[84:87]
	v_mfma_f32_16x16x32_bf16 v[84:87], v[144:147], v[210:213], v[84:87]
	v_mfma_f32_16x16x32_bf16 v[72:75], v[132:135], v[214:217], v[72:75]
	v_mfma_f32_16x16x32_bf16 v[72:75], v[136:139], v[218:221], v[72:75]
	v_mfma_f32_16x16x32_bf16 v[80:83], v[140:143], v[214:217], v[80:83]
	v_mfma_f32_16x16x32_bf16 v[80:83], v[144:147], v[218:221], v[80:83]
	s_setprio 0
	s_setprio 1
	v_mfma_f32_16x16x32_bf16 v[128:131], v[148:151], v[182:185], v[128:131]
	v_mfma_f32_16x16x32_bf16 v[128:131], v[152:155], v[186:189], v[128:131]
	v_mfma_f32_16x16x32_bf16 v[44:47], v[174:177], v[182:185], v[44:47]
	v_mfma_f32_16x16x32_bf16 v[44:47], v[178:181], v[186:189], v[44:47]
	v_mfma_f32_16x16x32_bf16 v[124:127], v[148:151], v[190:193], v[124:127]
	v_mfma_f32_16x16x32_bf16 v[124:127], v[152:155], v[194:197], v[124:127]
	v_mfma_f32_16x16x32_bf16 v[36:39], v[174:177], v[190:193], v[36:39]
	v_mfma_f32_16x16x32_bf16 v[36:39], v[178:181], v[194:197], v[36:39]
	v_mfma_f32_16x16x32_bf16 v[120:123], v[148:151], v[206:209], v[120:123]
	v_mfma_f32_16x16x32_bf16 v[120:123], v[152:155], v[210:213], v[120:123]
	v_mfma_f32_16x16x32_bf16 v[32:35], v[174:177], v[206:209], v[32:35]
	v_mfma_f32_16x16x32_bf16 v[32:35], v[178:181], v[210:213], v[32:35]
	v_mfma_f32_16x16x32_bf16 v[112:115], v[148:151], v[214:217], v[112:115]
	v_mfma_f32_16x16x32_bf16 v[112:115], v[152:155], v[218:221], v[112:115]
	s_setprio 2
	s_barrier
; #define PG8_STAGE(bufoff, gbase, voff) do { _Pragma("unroll") for (int _i = 0; _i < 2; ++_i) \
;         __builtin_amdgcn_global_load_lds((const unsigned*)((const char*)(gbase) + (voff)[_i]), (LAS unsigned*)(lds + (bufoff) + ldsw + _i * 8192), 16, 0, 0); } while (0)
; #define PG8_LDA(dst, b, h) do { _Pragma("unroll") for (int m = 0; m < 4; ++m) _Pragma("unroll") for (int k = 0; k < 2; ++k) dst[m][k] = *(const LAS bf16x8*)(lds + PG8_SA(b, h) + aoff + m * 2048 + k * 1024); } while (0)
; #define PG8_LDB(dst, b, h) do { _Pragma("unroll") for (int n = 0; n < 2; ++n) _Pragma("unroll") for (int k = 0; k < 2; ++k) dst[n][k] = *(const LAS bf16x8*)(lds + PG8_SB(b, h) + boff + n * 2048 + k * 1024); } while (0)
; #define PG8_WAIT_V(n) asm volatile("s_waitcnt vmcnt(" #n ")" ::: "memory")
; #define PG8_BAR __builtin_amdgcn_s_barrier()
; template <class Epi, class Sched, bool ALIGN_EPI = true>
; __device__ __forceinline__ void gemm_phase(LAS unsigned char* lds, const Gemm g, const Sched& S, const Epi& E) {
;     ...
;         for (int t = 0; t < nt; t += 2) {
;             const bool last = (t == nt - 2);
;             const char* a1 = cA + (size_t)(t + 1) * kstep;
;             const char* a2 = last ? nA : cA + (size_t)(t + 2) * kstep; const char* b2 = last ? nB : cB + (size_t)(t + 2) * kstep;
;             const char* a3 = a2 + kstep; const char* b3 = b2 + kstep;
;             PG8_LDB(B0, 0, 0); PG8_LDB(B1, 0, 1); PG8_SCHED; PG8_LDA(At, 0, 0); PG8_STAGE(PG8_SA(1, 1), a1 + hA, voffA);
;             PG8_WAIT_V(8); PG8_WAIT_L(0); PG8_BAR; PG8_MMA(0, 0, At, B0); PG8_MMA(0, 1, At, B1); PG8_BAR; PG8_SCHED;
;             PG8_LDA(At, 0, 1); PG8_STAGE(PG8_SB(0, 0), b2, voffB); PG8_STAGE(PG8_SB(0, 1), b2 + hB, voffB); PG8_STAGE(PG8_SA(0, 0), a2, voffA);
;             PG8_WAIT_V(8); PG8_WAIT_L(0); PG8_BAR; PG8_MMA(1, 0, At, B0); PG8_MMA(1, 1, At, B1); PG8_BAR; PG8_SCHED;
;             PG8_LDB(B0, 1, 0); PG8_LDB(B1, 1, 1); PG8_SCHED; PG8_LDA(At, 1, 0); PG8_STAGE(PG8_SA(0, 1), a2 + hA, voffA);
;             PG8_WAIT_V(8); PG8_WAIT_L(0); PG8_BAR; PG8_MMA(0, 0, At, B0); PG8_MMA(0, 1, At, B1); PG8_BAR; PG8_SCHED;
;             PG8_LDA(At, 1, 1); PG8_STAGE(PG8_SB(1, 0), b3, voffB); PG8_STAGE(PG8_SB(1, 1), b3 + hB, voffB); PG8_STAGE(PG8_SA(1, 0), a3, voffA);
;             PG8_WAIT_V(8); PG8_WAIT_L(0); PG8_BAR; PG8_MMA(1, 0, At, B0); PG8_MMA(1, 1, At, B1); PG8_BAR; PG8_SCHED;
	v_mfma_f32_16x16x32_bf16 v[28:31], v[174:177], v[214:217], v[28:31]
	v_mfma_f32_16x16x32_bf16 v[28:31], v[178:181], v[218:221], v[28:31]
	s_setprio 0
	s_add_i32 s26, s30, s61
	v_lshl_add_u64 v[156:157], v[156:157], 0, s[86:87]
	s_mov_b32 m0, s26
	s_nop 0
	global_load_lds_dwordx4 v[156:157], off
	s_add_i32 m0, s26, 0x2000
	s_add_u32 s26, s44, 0x80080
	v_lshl_add_u64 v[156:157], v[160:161], 0, s[86:87]
	s_addc_u32 s27, s45, 0
	s_add_i32 s30, s31, s61
	global_load_lds_dwordx4 v[156:157], off
	v_lshl_add_u64 v[156:157], s[26:27], 0, v[166:167]
	s_mov_b32 m0, s30
	s_nop 0
	global_load_lds_dwordx4 v[156:157], off
	v_lshl_add_u64 v[156:157], s[26:27], 0, v[0:1]
	s_add_i32 m0, s30, 0x2000
	s_nop 0
	global_load_lds_dwordx4 v[156:157], off
	v_lshl_add_u64 v[156:157], v[162:163], 0, s[86:87]
	s_mov_b32 m0, s75
	s_nop 0
	global_load_lds_dwordx4 v[156:157], off
	v_lshl_add_u64 v[156:157], v[222:223], 0, s[86:87]
	s_mov_b32 m0, s76
	s_nop 0
	global_load_lds_dwordx4 v[156:157], off
	ds_read_b128 v[182:185], v205 offset:49152
	ds_read_b128 v[186:189], v205 offset:50176
	ds_read_b128 v[190:193], v205 offset:51200
	ds_read_b128 v[194:197], v205 offset:52224
	ds_read_b128 v[206:209], v205 offset:53248
	ds_read_b128 v[210:213], v205 offset:54272
	ds_read_b128 v[214:217], v205 offset:55296
	ds_read_b128 v[218:221], v205 offset:56320
	s_waitcnt vmcnt(8)
	s_waitcnt lgkmcnt(0)
	s_barrier
	s_setprio 1
	s_waitcnt lgkmcnt(0)
	v_mfma_f32_16x16x32_bf16 v[60:63], v[132:135], v[182:185], v[60:63]
	v_mfma_f32_16x16x32_bf16 v[60:63], v[136:139], v[186:189], v[60:63]
	v_mfma_f32_16x16x32_bf16 v[68:71], v[140:143], v[182:185], v[68:71]
	v_mfma_f32_16x16x32_bf16 v[68:71], v[144:147], v[186:189], v[68:71]
	v_mfma_f32_16x16x32_bf16 v[40:43], v[132:135], v[190:193], v[40:43]
	v_mfma_f32_16x16x32_bf16 v[40:43], v[136:139], v[194:197], v[40:43]
	v_mfma_f32_16x16x32_bf16 v[64:67], v[140:143], v[190:193], v[64:67]
	v_mfma_f32_16x16x32_bf16 v[64:67], v[144:147], v[194:197], v[64:67]
	v_mfma_f32_16x16x32_bf16 v[24:27], v[132:135], v[206:209], v[24:27]
	v_mfma_f32_16x16x32_bf16 v[24:27], v[136:139], v[210:213], v[24:27]
	v_mfma_f32_16x16x32_bf16 v[56:59], v[140:143], v[206:209], v[56:59]
	v_mfma_f32_16x16x32_bf16 v[56:59], v[144:147], v[210:213], v[56:59]
	v_mfma_f32_16x16x32_bf16 v[12:15], v[132:135], v[214:217], v[12:15]
	v_mfma_f32_16x16x32_bf16 v[12:15], v[136:139], v[218:221], v[12:15]
	v_mfma_f32_16x16x32_bf16 v[48:51], v[140:143], v[214:217], v[48:51]
	v_mfma_f32_16x16x32_bf16 v[48:51], v[144:147], v[218:221], v[48:51]
	s_setprio 0
	s_setprio 1
	v_mfma_f32_16x16x32_bf16 v[104:107], v[148:151], v[182:185], v[104:107]
	v_mfma_f32_16x16x32_bf16 v[104:107], v[152:155], v[186:189], v[104:107]
	v_mfma_f32_16x16x32_bf16 v[20:23], v[174:177], v[182:185], v[20:23]
	v_mfma_f32_16x16x32_bf16 v[20:23], v[178:181], v[186:189], v[20:23]
	v_mfma_f32_16x16x32_bf16 v[92:95], v[148:151], v[190:193], v[92:95]
	v_mfma_f32_16x16x32_bf16 v[92:95], v[152:155], v[194:197], v[92:95]
	v_mfma_f32_16x16x32_bf16 v[16:19], v[174:177], v[190:193], v[16:19]
	v_mfma_f32_16x16x32_bf16 v[16:19], v[178:181], v[194:197], v[16:19]
	v_mfma_f32_16x16x32_bf16 v[76:79], v[148:151], v[206:209], v[76:79]
	v_mfma_f32_16x16x32_bf16 v[76:79], v[152:155], v[210:213], v[76:79]
	v_mfma_f32_16x16x32_bf16 v[8:11], v[174:177], v[206:209], v[8:11]
	v_mfma_f32_16x16x32_bf16 v[8:11], v[178:181], v[210:213], v[8:11]
	v_mfma_f32_16x16x32_bf16 v[52:55], v[148:151], v[214:217], v[52:55]
	v_mfma_f32_16x16x32_bf16 v[52:55], v[152:155], v[218:221], v[52:55]
	s_setprio 2
	s_barrier
	v_mfma_f32_16x16x32_bf16 v[4:7], v[174:177], v[214:217], v[4:7]
	v_mfma_f32_16x16x32_bf16 v[4:7], v[178:181], v[218:221], v[4:7]
	s_setprio 0
	s_add_i32 s25, s25, 2
	s_add_u32 s6, s6, 0x100
	s_addc_u32 s7, s7, 0
	s_add_u32 s19, s19, 0x100
	s_addc_u32 s24, s24, 0
	s_cmp_gt_u32 s25, 29
	s_cbranch_scc0 .LBB0_828

;     __device__ bool next(int i, Unit& u) const { if (i >= 2) return false; const int x = c & 7, j = c >> 3; u.pm = 32 * i + 4 * x + (j & 3); u.pn = j >> 2; return true; }
; #define PG8_STAGE(bufoff, gbase, voff) do { _Pragma("unroll") for (int _i = 0; _i < 2; ++_i) \
;         __builtin_amdgcn_global_load_lds((const unsigned*)((const char*)(gbase) + (voff)[_i]), (LAS unsigned*)(lds + (bufoff) + ldsw + _i * 8192), 16, 0, 0); } while (0)
; #define PG8_LDA(dst, b, h) do { _Pragma("unroll") for (int m = 0; m < 4; ++m) _Pragma("unroll") for (int k = 0; k < 2; ++k) dst[m][k] = *(const LAS bf16x8*)(lds + PG8_SA(b, h) + aoff + m * 2048 + k * 1024); } while (0)
; #define PG8_LDB(dst, b, h) do { _Pragma("unroll") for (int n = 0; n < 2; ++n) _Pragma("unroll") for (int k = 0; k < 2; ++k) dst[n][k] = *(const LAS bf16x8*)(lds + PG8_SB(b, h) + boff + n * 2048 + k * 1024); } while (0)
; #define PG8_WAIT_V(n) asm volatile("s_waitcnt vmcnt(" #n ")" ::: "memory")
; #define PG8_WAIT_L(n) asm volatile("s_waitcnt lgkmcnt(" #n ")" ::: "memory")
; #define PG8_BAR __builtin_amdgcn_s_barrier()
; template <class Epi, class Sched, bool ALIGN_EPI = true>
; __device__ __forceinline__ void gemm_phase(LAS unsigned char* lds, const Gemm g, const Sched& S, const Epi& E) {
;     ...
;         const bool has_next = S.next(ui + 1, nxt);
;         const char* nA = has_next ? (const char*)g.A + ((size_t)nxt.pm * BM * g.lda + (size_t)nxt.pn * g.a_pn_off) * 2 : cA; const char* nB = has_next ? (const char*)g.Bt + (size_t)nxt.pn * BM * g.ldb * 2 : cB;
;         for (int t = 0; t < nt; t += 2) {
;             const bool last = (t == nt - 2);
;             const char* a1 = cA + (size_t)(t + 1) * kstep;
;             const char* a2 = last ? nA : cA + (size_t)(t + 2) * kstep; const char* b2 = last ? nB : cB + (size_t)(t + 2) * kstep;
;             const char* a3 = a2 + kstep; const char* b3 = b2 + kstep;
;             PG8_LDB(B0, 0, 0); PG8_LDB(B1, 0, 1); PG8_SCHED; PG8_LDA(At, 0, 0); PG8_STAGE(PG8_SA(1, 1), a1 + hA, voffA);
;             PG8_WAIT_V(8); PG8_WAIT_L(0); PG8_BAR; PG8_MMA(0, 0, At, B0); PG8_MMA(0, 1, At, B1); PG8_BAR; PG8_SCHED;
;             PG8_LDA(At, 0, 1); PG8_STAGE(PG8_SB(0, 0), b2, voffB); PG8_STAGE(PG8_SB(0, 1), b2 + hB, voffB); PG8_STAGE(PG8_SA(0, 0), a2, voffA);
;             PG8_WAIT_V(8); PG8_WAIT_L(0); PG8_BAR; PG8_MMA(1, 0, At, B0); PG8_MMA(1, 1, At, B1); PG8_BAR; PG8_SCHED;
.LBB0_1110:
	s_add_u32 s16, s10, 0x100
	s_addc_u32 s17, s11, 0
	s_add_u32 s10, s10, 0x160080
	s_addc_u32 s11, s11, 0
	v_lshl_add_u64 v[132:133], s[10:11], 0, v[168:169]
	v_lshl_add_u64 v[134:135], s[10:11], 0, v[170:171]
	s_mov_b32 s18, -2
	s_mov_b64 s[10:11], 0
	s_add_u32 vcc_lo, s10, 0x100
	s_addc_u32 vcc_hi, s11, 0
	s_add_u32 s19, s16, s10
	s_addc_u32 s24, s17, s11
	s_add_i32 s25, 0, 0x10000
	s_cmpk_eq_i32 s18, 0x54
	s_cselect_b32 s65, s61, s24
	s_cselect_b32 s24, 0, vcc_lo
	s_cselect_b32 s64, s60, s19
	s_cselect_b32 s19, 0, vcc_hi
	s_add_u32 s62, s2, s24
	v_add_u32_e32 v160, s25, v188
	s_addc_u32 s63, s3, s19
	s_add_i32 s19, 0, 0x14000
	ds_read_b128 v[136:139], v160
	ds_read_b128 v[140:143], v160 offset:1024
	ds_read_b128 v[144:147], v160 offset:2048
	ds_read_b128 v[172:175], v160 offset:3072
	v_add_u32_e32 v160, s19, v188
	ds_read_b128 v[176:179], v160
	ds_read_b128 v[180:183], v160 offset:1024
	ds_read_b128 v[184:187], v160 offset:2048
	ds_read_b128 v[208:211], v160 offset:3072
	v_lshl_add_u64 v[160:161], v[132:133], 0, s[10:11]
	s_add_i32 m0, s67, 0xc000
	ds_read_b128 v[212:215], v197
	ds_read_b128 v[216:219], v197 offset:1024
	ds_read_b128 v[220:223], v197 offset:2048
	ds_read_b128 v[224:227], v197 offset:3072
	ds_read_b128 v[228:231], v197 offset:4096
	ds_read_b128 v[232:235], v197 offset:5120
	ds_read_b128 v[236:239], v197 offset:6144
	ds_read_b128 v[240:243], v197 offset:7168
	global_load_lds_dwordx4 v[160:161], off
	v_lshl_add_u64 v[160:161], v[134:135], 0, s[10:11]
	s_add_i32 m0, s67, 0xe000
	s_nop 0
	global_load_lds_dwordx4 v[160:161], off
	s_waitcnt vmcnt(8)
	s_waitcnt lgkmcnt(0)
	s_barrier
	s_setprio 1
	s_waitcnt lgkmcnt(0)
	v_mfma_f32_16x16x32_bf16 v[16:19], v[136:139], v[212:215], 0
	v_mfma_f32_16x16x32_bf16 v[16:19], v[140:143], v[216:219], v[16:19]
	v_mfma_f32_16x16x32_bf16 v[12:15], v[144:147], v[212:215], 0
	v_mfma_f32_16x16x32_bf16 v[12:15], v[172:175], v[216:219], v[12:15]
	v_mfma_f32_16x16x32_bf16 v[56:59], v[136:139], v[220:223], 0
	v_mfma_f32_16x16x32_bf16 v[56:59], v[140:143], v[224:227], v[56:59]
	v_mfma_f32_16x16x32_bf16 v[52:55], v[144:147], v[220:223], 0
	v_mfma_f32_16x16x32_bf16 v[52:55], v[172:175], v[224:227], v[52:55]
	v_mfma_f32_16x16x32_bf16 v[88:91], v[136:139], v[228:231], 0
	v_mfma_f32_16x16x32_bf16 v[88:91], v[140:143], v[232:235], v[88:91]
	v_mfma_f32_16x16x32_bf16 v[76:79], v[144:147], v[228:231], 0
	v_mfma_f32_16x16x32_bf16 v[76:79], v[172:175], v[232:235], v[76:79]
	v_mfma_f32_16x16x32_bf16 v[112:115], v[136:139], v[236:239], 0
	v_mfma_f32_16x16x32_bf16 v[112:115], v[140:143], v[240:243], v[112:115]
	v_mfma_f32_16x16x32_bf16 v[108:111], v[144:147], v[236:239], 0
	v_mfma_f32_16x16x32_bf16 v[108:111], v[172:175], v[240:243], v[108:111]
	s_setprio 0
	s_setprio 1
	v_mfma_f32_16x16x32_bf16 v[8:11], v[176:179], v[212:215], 0
	v_mfma_f32_16x16x32_bf16 v[8:11], v[180:183], v[216:219], v[8:11]
	v_mfma_f32_16x16x32_bf16 v[4:7], v[184:187], v[212:215], 0
	v_mfma_f32_16x16x32_bf16 v[4:7], v[208:211], v[216:219], v[4:7]
	v_mfma_f32_16x16x32_bf16 v[40:43], v[176:179], v[220:223], 0
	v_mfma_f32_16x16x32_bf16 v[40:43], v[180:183], v[224:227], v[40:43]
	v_mfma_f32_16x16x32_bf16 v[36:39], v[184:187], v[220:223], 0
	v_mfma_f32_16x16x32_bf16 v[36:39], v[208:211], v[224:227], v[36:39]
	v_mfma_f32_16x16x32_bf16 v[64:67], v[176:179], v[228:231], 0
	v_mfma_f32_16x16x32_bf16 v[64:67], v[180:183], v[232:235], v[64:67]
	v_mfma_f32_16x16x32_bf16 v[60:63], v[184:187], v[228:231], 0
	v_mfma_f32_16x16x32_bf16 v[60:63], v[208:211], v[232:235], v[60:63]
	v_mfma_f32_16x16x32_bf16 v[96:99], v[176:179], v[236:239], 0
	v_mfma_f32_16x16x32_bf16 v[96:99], v[180:183], v[240:243], v[96:99]
	s_setprio 2
	s_barrier
	v_mfma_f32_16x16x32_bf16 v[92:95], v[184:187], v[236:239], 0
	v_mfma_f32_16x16x32_bf16 v[92:95], v[208:211], v[240:243], v[92:95]
	s_setprio 0
	s_add_i32 s10, s25, s66
	v_lshl_add_u64 v[160:161], s[62:63], 0, v[2:3]
	s_mov_b32 m0, s10
	s_nop 0
	global_load_lds_dwordx4 v[160:161], off
	s_add_i32 m0, s10, 0x2000
	s_add_u32 s10, s62, 0x160000
	v_lshl_add_u64 v[162:163], s[62:63], 0, v[150:151]
	s_addc_u32 s11, s63, 0
	s_add_i32 s19, s19, s66
	global_load_lds_dwordx4 v[162:163], off
	v_lshl_add_u64 v[244:245], s[10:11], 0, v[2:3]
	s_mov_b32 m0, s19
	v_lshl_add_u64 v[246:247], s[64:65], 0, v[148:149]
	global_load_lds_dwordx4 v[244:245], off
	v_lshl_add_u64 v[244:245], s[10:11], 0, v[150:151]
	s_add_i32 m0, s19, 0x2000
	s_nop 0
	global_load_lds_dwordx4 v[244:245], off
	v_lshl_add_u64 v[244:245], s[64:65], 0, v[0:1]
	s_mov_b32 m0, s67
	s_nop 0
	global_load_lds_dwordx4 v[244:245], off
	s_mov_b32 m0, s75
	s_nop 0
	global_load_lds_dwordx4 v[246:247], off
	ds_read_b128 v[212:215], v197 offset:16384
	ds_read_b128 v[216:219], v197 offset:17408
	ds_read_b128 v[220:223], v197 offset:18432
	ds_read_b128 v[224:227], v197 offset:19456
	ds_read_b128 v[228:231], v197 offset:20480
	ds_read_b128 v[232:235], v197 offset:21504
	ds_read_b128 v[236:239], v197 offset:22528
	ds_read_b128 v[240:243], v197 offset:23552
	s_waitcnt vmcnt(8)
	s_waitcnt lgkmcnt(0)
	s_barrier
; #define PG8_STAGE(bufoff, gbase, voff) do { _Pragma("unroll") for (int _i = 0; _i < 2; ++_i) \
;         __builtin_amdgcn_global_load_lds((const unsigned*)((const char*)(gbase) + (voff)[_i]), (LAS unsigned*)(lds + (bufoff) + ldsw + _i * 8192), 16, 0, 0); } while (0)
; #define PG8_LDA(dst, b, h) do { _Pragma("unroll") for (int m = 0; m < 4; ++m) _Pragma("unroll") for (int k = 0; k < 2; ++k) dst[m][k] = *(const LAS bf16x8*)(lds + PG8_SA(b, h) + aoff + m * 2048 + k * 1024); } while (0)
; #define PG8_LDB(dst, b, h) do { _Pragma("unroll") for (int n = 0; n < 2; ++n) _Pragma("unroll") for (int k = 0; k < 2; ++k) dst[n][k] = *(const LAS bf16x8*)(lds + PG8_SB(b, h) + boff + n * 2048 + k * 1024); } while (0)
; #define PG8_MMA(ai, bj, At, Bt) do { __builtin_amdgcn_s_setprio(1); _Pragma("unroll") for (int m = 0; m < 4; ++m) _Pragma("unroll") for (int n = 0; n < 2; ++n) _Pragma("unroll") for (int k = 0; k < 2; ++k) \
;         acc[ai][bj][m][n] = __builtin_amdgcn_mfma_f32_16x16x32_bf16(Bt[n][k], At[m][k], acc[ai][bj][m][n], 0, 0, 0); __builtin_amdgcn_s_setprio(0); } while (0)
; #define PG8_WAIT_V(n) asm volatile("s_waitcnt vmcnt(" #n ")" ::: "memory")
; #define PG8_WAIT_L(n) asm volatile("s_waitcnt lgkmcnt(" #n ")" ::: "memory")
; #define PG8_BAR __builtin_amdgcn_s_barrier()
; #define PG8_SCHED __builtin_amdgcn_sched_barrier(0)
; template <class Epi, class Sched, bool ALIGN_EPI = true>
; __device__ __forceinline__ void gemm_phase(LAS unsigned char* lds, const Gemm g, const Sched& S, const Epi& E) {
;     ...
;             PG8_WAIT_V(8); PG8_WAIT_L(0); PG8_BAR; PG8_MMA(1, 0, At, B0); PG8_MMA(1, 1, At, B1); PG8_BAR; PG8_SCHED;
;             PG8_LDB(B0, 1, 0); PG8_LDB(B1, 1, 1); PG8_SCHED; PG8_LDA(At, 1, 0); PG8_STAGE(PG8_SA(0, 1), a2 + hA, voffA);
;             PG8_WAIT_V(8); PG8_WAIT_L(0); PG8_BAR; PG8_MMA(0, 0, At, B0); PG8_MMA(0, 1, At, B1); PG8_BAR; PG8_SCHED;
	s_setprio 1
	s_waitcnt lgkmcnt(0)
	v_mfma_f32_16x16x32_bf16 v[128:131], v[136:139], v[212:215], 0
	v_mfma_f32_16x16x32_bf16 v[128:131], v[140:143], v[216:219], v[128:131]
	v_mfma_f32_16x16x32_bf16 v[124:127], v[144:147], v[212:215], 0
	v_mfma_f32_16x16x32_bf16 v[124:127], v[172:175], v[216:219], v[124:127]
	v_mfma_f32_16x16x32_bf16 v[104:107], v[136:139], v[220:223], 0
	v_mfma_f32_16x16x32_bf16 v[104:107], v[140:143], v[224:227], v[104:107]
	v_mfma_f32_16x16x32_bf16 v[100:103], v[144:147], v[220:223], 0
	v_mfma_f32_16x16x32_bf16 v[100:103], v[172:175], v[224:227], v[100:103]
	v_mfma_f32_16x16x32_bf16 v[72:75], v[136:139], v[228:231], 0
	v_mfma_f32_16x16x32_bf16 v[72:75], v[140:143], v[232:235], v[72:75]
	v_mfma_f32_16x16x32_bf16 v[68:71], v[144:147], v[228:231], 0
	v_mfma_f32_16x16x32_bf16 v[68:71], v[172:175], v[232:235], v[68:71]
	v_mfma_f32_16x16x32_bf16 v[32:35], v[136:139], v[236:239], 0
	v_mfma_f32_16x16x32_bf16 v[32:35], v[140:143], v[240:243], v[32:35]
	v_mfma_f32_16x16x32_bf16 v[28:31], v[144:147], v[236:239], 0
	v_mfma_f32_16x16x32_bf16 v[28:31], v[172:175], v[240:243], v[28:31]
	s_setprio 0
	s_setprio 1
	v_mfma_f32_16x16x32_bf16 v[120:123], v[176:179], v[212:215], 0
	v_mfma_f32_16x16x32_bf16 v[120:123], v[180:183], v[216:219], v[120:123]
	v_mfma_f32_16x16x32_bf16 v[116:119], v[184:187], v[212:215], 0
	v_mfma_f32_16x16x32_bf16 v[116:119], v[208:211], v[216:219], v[116:119]
	v_mfma_f32_16x16x32_bf16 v[84:87], v[176:179], v[220:223], 0
	v_mfma_f32_16x16x32_bf16 v[84:87], v[180:183], v[224:227], v[84:87]
	v_mfma_f32_16x16x32_bf16 v[80:83], v[184:187], v[220:223], 0
	v_mfma_f32_16x16x32_bf16 v[80:83], v[208:211], v[224:227], v[80:83]
	v_mfma_f32_16x16x32_bf16 v[48:51], v[176:179], v[228:231], 0
	v_mfma_f32_16x16x32_bf16 v[48:51], v[180:183], v[232:235], v[48:51]
	v_mfma_f32_16x16x32_bf16 v[44:47], v[184:187], v[228:231], 0
	v_mfma_f32_16x16x32_bf16 v[44:47], v[208:211], v[232:235], v[44:47]
	v_mfma_f32_16x16x32_bf16 v[24:27], v[176:179], v[236:239], 0
	v_mfma_f32_16x16x32_bf16 v[24:27], v[180:183], v[240:243], v[24:27]
	s_setprio 2
	s_barrier
	v_mfma_f32_16x16x32_bf16 v[20:23], v[184:187], v[236:239], 0
	v_mfma_f32_16x16x32_bf16 v[20:23], v[208:211], v[240:243], v[20:23]
	s_setprio 0
	s_add_i32 s19, 0, 0x18000
	s_add_i32 s24, 0, 0x1c000
	v_add_u32_e32 v172, s19, v188
	v_add_u32_e32 v207, s24, v188
	ds_read_b128 v[136:139], v172
	ds_read_b128 v[140:143], v172 offset:1024
	ds_read_b128 v[144:147], v172 offset:2048
	ds_read_b128 v[172:175], v172 offset:3072
	ds_read_b128 v[176:179], v207
	ds_read_b128 v[180:183], v207 offset:1024
	ds_read_b128 v[184:187], v207 offset:2048
	ds_read_b128 v[208:211], v207 offset:3072
	s_add_u32 s10, s64, 0x160000
	s_addc_u32 s11, s65, 0
	s_mov_b32 m0, s76
	v_lshl_add_u64 v[248:249], s[10:11], 0, v[0:1]
	ds_read_b128 v[212:215], v197 offset:32768
	ds_read_b128 v[216:219], v197 offset:33792
	ds_read_b128 v[220:223], v197 offset:34816
	ds_read_b128 v[224:227], v197 offset:35840
	ds_read_b128 v[228:231], v197 offset:36864
	ds_read_b128 v[232:235], v197 offset:37888
	ds_read_b128 v[236:239], v197 offset:38912
	ds_read_b128 v[240:243], v197 offset:39936
	global_load_lds_dwordx4 v[248:249], off
	v_lshl_add_u64 v[248:249], s[10:11], 0, v[148:149]
	s_mov_b32 m0, s77
	s_nop 0
	global_load_lds_dwordx4 v[248:249], off
	s_waitcnt vmcnt(8)
	s_waitcnt lgkmcnt(0)
	s_barrier
	s_setprio 1
	s_waitcnt lgkmcnt(0)
	v_mfma_f32_16x16x32_bf16 v[16:19], v[136:139], v[212:215], v[16:19]
	v_mfma_f32_16x16x32_bf16 v[16:19], v[140:143], v[216:219], v[16:19]
	v_mfma_f32_16x16x32_bf16 v[12:15], v[144:147], v[212:215], v[12:15]
	v_mfma_f32_16x16x32_bf16 v[12:15], v[172:175], v[216:219], v[12:15]
	v_mfma_f32_16x16x32_bf16 v[56:59], v[136:139], v[220:223], v[56:59]
	v_mfma_f32_16x16x32_bf16 v[56:59], v[140:143], v[224:227], v[56:59]
	v_mfma_f32_16x16x32_bf16 v[52:55], v[144:147], v[220:223], v[52:55]
	v_mfma_f32_16x16x32_bf16 v[52:55], v[172:175], v[224:227], v[52:55]
	v_mfma_f32_16x16x32_bf16 v[88:91], v[136:139], v[228:231], v[88:91]
	v_mfma_f32_16x16x32_bf16 v[88:91], v[140:143], v[232:235], v[88:91]
	v_mfma_f32_16x16x32_bf16 v[76:79], v[144:147], v[228:231], v[76:79]
	v_mfma_f32_16x16x32_bf16 v[76:79], v[172:175], v[232:235], v[76:79]
	v_mfma_f32_16x16x32_bf16 v[112:115], v[136:139], v[236:239], v[112:115]
	v_mfma_f32_16x16x32_bf16 v[112:115], v[140:143], v[240:243], v[112:115]
	v_mfma_f32_16x16x32_bf16 v[108:111], v[144:147], v[236:239], v[108:111]
	v_mfma_f32_16x16x32_bf16 v[108:111], v[172:175], v[240:243], v[108:111]
	s_setprio 0
	s_setprio 1
	v_mfma_f32_16x16x32_bf16 v[8:11], v[176:179], v[212:215], v[8:11]
	v_mfma_f32_16x16x32_bf16 v[8:11], v[180:183], v[216:219], v[8:11]
	v_mfma_f32_16x16x32_bf16 v[4:7], v[184:187], v[212:215], v[4:7]
	v_mfma_f32_16x16x32_bf16 v[4:7], v[208:211], v[216:219], v[4:7]
	v_mfma_f32_16x16x32_bf16 v[40:43], v[176:179], v[220:223], v[40:43]
	v_mfma_f32_16x16x32_bf16 v[40:43], v[180:183], v[224:227], v[40:43]
	v_mfma_f32_16x16x32_bf16 v[36:39], v[184:187], v[220:223], v[36:39]
	v_mfma_f32_16x16x32_bf16 v[36:39], v[208:211], v[224:227], v[36:39]
	v_mfma_f32_16x16x32_bf16 v[64:67], v[176:179], v[228:231], v[64:67]
	v_mfma_f32_16x16x32_bf16 v[64:67], v[180:183], v[232:235], v[64:67]
	v_mfma_f32_16x16x32_bf16 v[60:63], v[184:187], v[228:231], v[60:63]
	v_mfma_f32_16x16x32_bf16 v[60:63], v[208:211], v[232:235], v[60:63]
	v_mfma_f32_16x16x32_bf16 v[96:99], v[176:179], v[236:239], v[96:99]
	v_mfma_f32_16x16x32_bf16 v[96:99], v[180:183], v[240:243], v[96:99]
	s_setprio 2
	s_barrier
; #define PG8_STAGE(bufoff, gbase, voff) do { _Pragma("unroll") for (int _i = 0; _i < 2; ++_i) \
;         __builtin_amdgcn_global_load_lds((const unsigned*)((const char*)(gbase) + (voff)[_i]), (LAS unsigned*)(lds + (bufoff) + ldsw + _i * 8192), 16, 0, 0); } while (0)
; #define PG8_LDA(dst, b, h) do { _Pragma("unroll") for (int m = 0; m < 4; ++m) _Pragma("unroll") for (int k = 0; k < 2; ++k) dst[m][k] = *(const LAS bf16x8*)(lds + PG8_SA(b, h) + aoff + m * 2048 + k * 1024); } while (0)
; #define PG8_LDB(dst, b, h) do { _Pragma("unroll") for (int n = 0; n < 2; ++n) _Pragma("unroll") for (int k = 0; k < 2; ++k) dst[n][k] = *(const LAS bf16x8*)(lds + PG8_SB(b, h) + boff + n * 2048 + k * 1024); } while (0)
; #define PG8_WAIT_V(n) asm volatile("s_waitcnt vmcnt(" #n ")" ::: "memory")
; #define PG8_BAR __builtin_amdgcn_s_barrier()
; template <class Epi, class Sched, bool ALIGN_EPI = true>
; __device__ __forceinline__ void gemm_phase(LAS unsigned char* lds, const Gemm g, const Sched& S, const Epi& E) {
;     ...
;         for (int t = 0; t < nt; t += 2) {
;             const bool last = (t == nt - 2);
;             const char* a1 = cA + (size_t)(t + 1) * kstep;
;             const char* a2 = last ? nA : cA + (size_t)(t + 2) * kstep; const char* b2 = last ? nB : cB + (size_t)(t + 2) * kstep;
;             const char* a3 = a2 + kstep; const char* b3 = b2 + kstep;
;             PG8_LDB(B0, 0, 0); PG8_LDB(B1, 0, 1); PG8_SCHED; PG8_LDA(At, 0, 0); PG8_STAGE(PG8_SA(1, 1), a1 + hA, voffA);
;             PG8_WAIT_V(8); PG8_WAIT_L(0); PG8_BAR; PG8_MMA(0, 0, At, B0); PG8_MMA(0, 1, At, B1); PG8_BAR; PG8_SCHED;
;             PG8_LDA(At, 0, 1); PG8_STAGE(PG8_SB(0, 0), b2, voffB); PG8_STAGE(PG8_SB(0, 1), b2 + hB, voffB); PG8_STAGE(PG8_SA(0, 0), a2, voffA);
;             PG8_WAIT_V(8); PG8_WAIT_L(0); PG8_BAR; PG8_MMA(1, 0, At, B0); PG8_MMA(1, 1, At, B1); PG8_BAR; PG8_SCHED;
;             PG8_LDB(B0, 1, 0); PG8_LDB(B1, 1, 1); PG8_SCHED; PG8_LDA(At, 1, 0); PG8_STAGE(PG8_SA(0, 1), a2 + hA, voffA);
;             PG8_WAIT_V(8); PG8_WAIT_L(0); PG8_BAR; PG8_MMA(0, 0, At, B0); PG8_MMA(0, 1, At, B1); PG8_BAR; PG8_SCHED;
;             PG8_LDA(At, 1, 1); PG8_STAGE(PG8_SB(1, 0), b3, voffB); PG8_STAGE(PG8_SB(1, 1), b3 + hB, voffB); PG8_STAGE(PG8_SA(1, 0), a3, voffA);
;             PG8_WAIT_V(8); PG8_WAIT_L(0); PG8_BAR; PG8_MMA(1, 0, At, B0); PG8_MMA(1, 1, At, B1); PG8_BAR; PG8_SCHED;
	v_mfma_f32_16x16x32_bf16 v[92:95], v[184:187], v[236:239], v[92:95]
	v_mfma_f32_16x16x32_bf16 v[92:95], v[208:211], v[240:243], v[92:95]
	s_setprio 0
	s_add_i32 s10, s19, s66
	v_lshl_add_u64 v[160:161], v[160:161], 0, s[86:87]
	s_mov_b32 m0, s10
	s_nop 0
	global_load_lds_dwordx4 v[160:161], off
	s_add_i32 m0, s10, 0x2000
	s_add_u32 s10, s62, 0x160080
	v_lshl_add_u64 v[160:161], v[162:163], 0, s[86:87]
	s_addc_u32 s11, s63, 0
	s_add_i32 s19, s24, s66
	global_load_lds_dwordx4 v[160:161], off
	v_lshl_add_u64 v[160:161], s[10:11], 0, v[2:3]
	s_mov_b32 m0, s19
	s_nop 0
	global_load_lds_dwordx4 v[160:161], off
	v_lshl_add_u64 v[160:161], s[10:11], 0, v[150:151]
	s_add_i32 m0, s19, 0x2000
	s_nop 0
	global_load_lds_dwordx4 v[160:161], off
	v_lshl_add_u64 v[160:161], v[244:245], 0, s[86:87]
	s_mov_b32 m0, s80
	s_nop 0
	global_load_lds_dwordx4 v[160:161], off
	v_lshl_add_u64 v[160:161], v[246:247], 0, s[86:87]
	s_mov_b32 m0, s81
	s_nop 0
	global_load_lds_dwordx4 v[160:161], off
	ds_read_b128 v[212:215], v197 offset:49152
	ds_read_b128 v[216:219], v197 offset:50176
	ds_read_b128 v[220:223], v197 offset:51200
	ds_read_b128 v[224:227], v197 offset:52224
	ds_read_b128 v[228:231], v197 offset:53248
	ds_read_b128 v[232:235], v197 offset:54272
	ds_read_b128 v[236:239], v197 offset:55296
	ds_read_b128 v[240:243], v197 offset:56320
	s_waitcnt vmcnt(8)
	s_waitcnt lgkmcnt(0)
	s_barrier
	s_setprio 1
	s_waitcnt lgkmcnt(0)
	v_mfma_f32_16x16x32_bf16 v[128:131], v[136:139], v[212:215], v[128:131]
	v_mfma_f32_16x16x32_bf16 v[128:131], v[140:143], v[216:219], v[128:131]
	v_mfma_f32_16x16x32_bf16 v[124:127], v[144:147], v[212:215], v[124:127]
	v_mfma_f32_16x16x32_bf16 v[124:127], v[172:175], v[216:219], v[124:127]
	v_mfma_f32_16x16x32_bf16 v[104:107], v[136:139], v[220:223], v[104:107]
	v_mfma_f32_16x16x32_bf16 v[104:107], v[140:143], v[224:227], v[104:107]
	v_mfma_f32_16x16x32_bf16 v[100:103], v[144:147], v[220:223], v[100:103]
	v_mfma_f32_16x16x32_bf16 v[100:103], v[172:175], v[224:227], v[100:103]
	v_mfma_f32_16x16x32_bf16 v[72:75], v[136:139], v[228:231], v[72:75]
	v_mfma_f32_16x16x32_bf16 v[72:75], v[140:143], v[232:235], v[72:75]
	v_mfma_f32_16x16x32_bf16 v[68:71], v[144:147], v[228:231], v[68:71]
	v_mfma_f32_16x16x32_bf16 v[68:71], v[172:175], v[232:235], v[68:71]
	v_mfma_f32_16x16x32_bf16 v[32:35], v[136:139], v[236:239], v[32:35]
	v_mfma_f32_16x16x32_bf16 v[32:35], v[140:143], v[240:243], v[32:35]
	v_mfma_f32_16x16x32_bf16 v[28:31], v[144:147], v[236:239], v[28:31]
	v_mfma_f32_16x16x32_bf16 v[28:31], v[172:175], v[240:243], v[28:31]
	s_setprio 0
	s_setprio 1
	v_mfma_f32_16x16x32_bf16 v[120:123], v[176:179], v[212:215], v[120:123]
	v_mfma_f32_16x16x32_bf16 v[120:123], v[180:183], v[216:219], v[120:123]
	v_mfma_f32_16x16x32_bf16 v[116:119], v[184:187], v[212:215], v[116:119]
	v_mfma_f32_16x16x32_bf16 v[116:119], v[208:211], v[216:219], v[116:119]
	v_mfma_f32_16x16x32_bf16 v[84:87], v[176:179], v[220:223], v[84:87]
	v_mfma_f32_16x16x32_bf16 v[84:87], v[180:183], v[224:227], v[84:87]
	v_mfma_f32_16x16x32_bf16 v[80:83], v[184:187], v[220:223], v[80:83]
	v_mfma_f32_16x16x32_bf16 v[80:83], v[208:211], v[224:227], v[80:83]
	v_mfma_f32_16x16x32_bf16 v[48:51], v[176:179], v[228:231], v[48:51]
	v_mfma_f32_16x16x32_bf16 v[48:51], v[180:183], v[232:235], v[48:51]
	v_mfma_f32_16x16x32_bf16 v[44:47], v[184:187], v[228:231], v[44:47]
	v_mfma_f32_16x16x32_bf16 v[44:47], v[208:211], v[232:235], v[44:47]
	v_mfma_f32_16x16x32_bf16 v[24:27], v[176:179], v[236:239], v[24:27]
	v_mfma_f32_16x16x32_bf16 v[24:27], v[180:183], v[240:243], v[24:27]
	s_setprio 2
	s_barrier
	v_mfma_f32_16x16x32_bf16 v[20:23], v[184:187], v[236:239], v[20:23]
	v_mfma_f32_16x16x32_bf16 v[20:23], v[208:211], v[240:243], v[20:23]
	s_setprio 0
	s_add_i32 s18, s18, 2
	s_cmpk_gt_u32 s18, 0x55
	s_mov_b64 s[10:11], vcc
	s_cbranch_scc1 .Lpeel_exit_1111
.LBB0_1111:
	s_add_u32 vcc_lo, s10, 0x100
	s_addc_u32 vcc_hi, s11, 0
	s_add_u32 s19, s16, s10
	s_addc_u32 s24, s17, s11
	s_add_i32 s25, 0, 0x10000
	s_cmpk_eq_i32 s18, 0x54
	s_cselect_b32 s65, s61, s24
	s_cselect_b32 s24, 0, vcc_lo
	s_cselect_b32 s64, s60, s19
	s_cselect_b32 s19, 0, vcc_hi
	s_add_u32 s62, s2, s24
	v_add_u32_e32 v160, s25, v188
	s_addc_u32 s63, s3, s19
	s_add_i32 s19, 0, 0x14000
	ds_read_b128 v[136:139], v160
	ds_read_b128 v[140:143], v160 offset:1024
	ds_read_b128 v[144:147], v160 offset:2048
	ds_read_b128 v[172:175], v160 offset:3072
	v_add_u32_e32 v160, s19, v188
	ds_read_b128 v[176:179], v160
	ds_read_b128 v[180:183], v160 offset:1024
	ds_read_b128 v[184:187], v160 offset:2048
	ds_read_b128 v[208:211], v160 offset:3072
	v_lshl_add_u64 v[160:161], v[132:133], 0, s[10:11]
	s_add_i32 m0, s67, 0xc000
	ds_read_b128 v[212:215], v197
	ds_read_b128 v[216:219], v197 offset:1024
	ds_read_b128 v[220:223], v197 offset:2048
	ds_read_b128 v[224:227], v197 offset:3072
	ds_read_b128 v[228:231], v197 offset:4096
	ds_read_b128 v[232:235], v197 offset:5120
	ds_read_b128 v[236:239], v197 offset:6144
	ds_read_b128 v[240:243], v197 offset:7168
	global_load_lds_dwordx4 v[160:161], off
	v_lshl_add_u64 v[160:161], v[134:135], 0, s[10:11]
	s_add_i32 m0, s67, 0xe000
	s_nop 0
	global_load_lds_dwordx4 v[160:161], off
	s_waitcnt vmcnt(8)
	s_waitcnt lgkmcnt(0)
	s_barrier
; #define PG8_STAGE(bufoff, gbase, voff) do { _Pragma("unroll") for (int _i = 0; _i < 2; ++_i) \
;         __builtin_amdgcn_global_load_lds((const unsigned*)((const char*)(gbase) + (voff)[_i]), (LAS unsigned*)(lds + (bufoff) + ldsw + _i * 8192), 16, 0, 0); } while (0)
; #define PG8_LDA(dst, b, h) do { _Pragma("unroll") for (int m = 0; m < 4; ++m) _Pragma("unroll") for (int k = 0; k < 2; ++k) dst[m][k] = *(const LAS bf16x8*)(lds + PG8_SA(b, h) + aoff + m * 2048 + k * 1024); } while (0)
; #define PG8_MMA(ai, bj, At, Bt) do { __builtin_amdgcn_s_setprio(1); _Pragma("unroll") for (int m = 0; m < 4; ++m) _Pragma("unroll") for (int n = 0; n < 2; ++n) _Pragma("unroll") for (int k = 0; k < 2; ++k) \
;         acc[ai][bj][m][n] = __builtin_amdgcn_mfma_f32_16x16x32_bf16(Bt[n][k], At[m][k], acc[ai][bj][m][n], 0, 0, 0); __builtin_amdgcn_s_setprio(0); } while (0)
; #define PG8_WAIT_V(n) asm volatile("s_waitcnt vmcnt(" #n ")" ::: "memory")
; #define PG8_WAIT_L(n) asm volatile("s_waitcnt lgkmcnt(" #n ")" ::: "memory")
; #define PG8_BAR __builtin_amdgcn_s_barrier()
; #define PG8_SCHED __builtin_amdgcn_sched_barrier(0)
; template <class Epi, class Sched, bool ALIGN_EPI = true>
; __device__ __forceinline__ void gemm_phase(LAS unsigned char* lds, const Gemm g, const Sched& S, const Epi& E) {
;     ...
;             PG8_WAIT_V(8); PG8_WAIT_L(0); PG8_BAR; PG8_MMA(0, 0, At, B0); PG8_MMA(0, 1, At, B1); PG8_BAR; PG8_SCHED;
;             PG8_LDA(At, 0, 1); PG8_STAGE(PG8_SB(0, 0), b2, voffB); PG8_STAGE(PG8_SB(0, 1), b2 + hB, voffB); PG8_STAGE(PG8_SA(0, 0), a2, voffA);
;             PG8_WAIT_V(8); PG8_WAIT_L(0); PG8_BAR; PG8_MMA(1, 0, At, B0); PG8_MMA(1, 1, At, B1); PG8_BAR; PG8_SCHED;
	s_setprio 1
	s_waitcnt lgkmcnt(0)
	v_mfma_f32_16x16x32_bf16 v[16:19], v[136:139], v[212:215], v[16:19]
	v_mfma_f32_16x16x32_bf16 v[16:19], v[140:143], v[216:219], v[16:19]
	v_mfma_f32_16x16x32_bf16 v[12:15], v[144:147], v[212:215], v[12:15]
	v_mfma_f32_16x16x32_bf16 v[12:15], v[172:175], v[216:219], v[12:15]
	v_mfma_f32_16x16x32_bf16 v[56:59], v[136:139], v[220:223], v[56:59]
	v_mfma_f32_16x16x32_bf16 v[56:59], v[140:143], v[224:227], v[56:59]
	v_mfma_f32_16x16x32_bf16 v[52:55], v[144:147], v[220:223], v[52:55]
	v_mfma_f32_16x16x32_bf16 v[52:55], v[172:175], v[224:227], v[52:55]
	v_mfma_f32_16x16x32_bf16 v[88:91], v[136:139], v[228:231], v[88:91]
	v_mfma_f32_16x16x32_bf16 v[88:91], v[140:143], v[232:235], v[88:91]
	v_mfma_f32_16x16x32_bf16 v[76:79], v[144:147], v[228:231], v[76:79]
	v_mfma_f32_16x16x32_bf16 v[76:79], v[172:175], v[232:235], v[76:79]
	v_mfma_f32_16x16x32_bf16 v[112:115], v[136:139], v[236:239], v[112:115]
	v_mfma_f32_16x16x32_bf16 v[112:115], v[140:143], v[240:243], v[112:115]
	v_mfma_f32_16x16x32_bf16 v[108:111], v[144:147], v[236:239], v[108:111]
	v_mfma_f32_16x16x32_bf16 v[108:111], v[172:175], v[240:243], v[108:111]
	s_setprio 0
	s_setprio 1
	v_mfma_f32_16x16x32_bf16 v[8:11], v[176:179], v[212:215], v[8:11]
	v_mfma_f32_16x16x32_bf16 v[8:11], v[180:183], v[216:219], v[8:11]
	v_mfma_f32_16x16x32_bf16 v[4:7], v[184:187], v[212:215], v[4:7]
	v_mfma_f32_16x16x32_bf16 v[4:7], v[208:211], v[216:219], v[4:7]
	v_mfma_f32_16x16x32_bf16 v[40:43], v[176:179], v[220:223], v[40:43]
	v_mfma_f32_16x16x32_bf16 v[40:43], v[180:183], v[224:227], v[40:43]
	v_mfma_f32_16x16x32_bf16 v[36:39], v[184:187], v[220:223], v[36:39]
	v_mfma_f32_16x16x32_bf16 v[36:39], v[208:211], v[224:227], v[36:39]
	v_mfma_f32_16x16x32_bf16 v[64:67], v[176:179], v[228:231], v[64:67]
	v_mfma_f32_16x16x32_bf16 v[64:67], v[180:183], v[232:235], v[64:67]
	v_mfma_f32_16x16x32_bf16 v[60:63], v[184:187], v[228:231], v[60:63]
	v_mfma_f32_16x16x32_bf16 v[60:63], v[208:211], v[232:235], v[60:63]
	v_mfma_f32_16x16x32_bf16 v[96:99], v[176:179], v[236:239], v[96:99]
	v_mfma_f32_16x16x32_bf16 v[96:99], v[180:183], v[240:243], v[96:99]
	s_setprio 2
	s_barrier
	v_mfma_f32_16x16x32_bf16 v[92:95], v[184:187], v[236:239], v[92:95]
	v_mfma_f32_16x16x32_bf16 v[92:95], v[208:211], v[240:243], v[92:95]
	s_setprio 0
	s_add_i32 s10, s25, s66
	v_lshl_add_u64 v[160:161], s[62:63], 0, v[2:3]
	s_mov_b32 m0, s10
	s_nop 0
	global_load_lds_dwordx4 v[160:161], off
	s_add_i32 m0, s10, 0x2000
	s_add_u32 s10, s62, 0x160000
	v_lshl_add_u64 v[162:163], s[62:63], 0, v[150:151]
	s_addc_u32 s11, s63, 0
	s_add_i32 s19, s19, s66
	global_load_lds_dwordx4 v[162:163], off
	v_lshl_add_u64 v[244:245], s[10:11], 0, v[2:3]
	s_mov_b32 m0, s19
	v_lshl_add_u64 v[246:247], s[64:65], 0, v[148:149]
	global_load_lds_dwordx4 v[244:245], off
	v_lshl_add_u64 v[244:245], s[10:11], 0, v[150:151]
	s_add_i32 m0, s19, 0x2000
	s_nop 0
	global_load_lds_dwordx4 v[244:245], off
	v_lshl_add_u64 v[244:245], s[64:65], 0, v[0:1]
	s_mov_b32 m0, s67
	s_nop 0
	global_load_lds_dwordx4 v[244:245], off
	s_mov_b32 m0, s75
	s_nop 0
	global_load_lds_dwordx4 v[246:247], off
	ds_read_b128 v[212:215], v197 offset:16384
	ds_read_b128 v[216:219], v197 offset:17408
	ds_read_b128 v[220:223], v197 offset:18432
	ds_read_b128 v[224:227], v197 offset:19456
	ds_read_b128 v[228:231], v197 offset:20480
	ds_read_b128 v[232:235], v197 offset:21504
	ds_read_b128 v[236:239], v197 offset:22528
	ds_read_b128 v[240:243], v197 offset:23552
	s_waitcnt vmcnt(8)
	s_waitcnt lgkmcnt(0)
	s_barrier
	s_setprio 1
	s_waitcnt lgkmcnt(0)
	v_mfma_f32_16x16x32_bf16 v[128:131], v[136:139], v[212:215], v[128:131]
	v_mfma_f32_16x16x32_bf16 v[128:131], v[140:143], v[216:219], v[128:131]
	v_mfma_f32_16x16x32_bf16 v[124:127], v[144:147], v[212:215], v[124:127]
	v_mfma_f32_16x16x32_bf16 v[124:127], v[172:175], v[216:219], v[124:127]
	v_mfma_f32_16x16x32_bf16 v[104:107], v[136:139], v[220:223], v[104:107]
	v_mfma_f32_16x16x32_bf16 v[104:107], v[140:143], v[224:227], v[104:107]
	v_mfma_f32_16x16x32_bf16 v[100:103], v[144:147], v[220:223], v[100:103]
	v_mfma_f32_16x16x32_bf16 v[100:103], v[172:175], v[224:227], v[100:103]
	v_mfma_f32_16x16x32_bf16 v[72:75], v[136:139], v[228:231], v[72:75]
	v_mfma_f32_16x16x32_bf16 v[72:75], v[140:143], v[232:235], v[72:75]
	v_mfma_f32_16x16x32_bf16 v[68:71], v[144:147], v[228:231], v[68:71]
	v_mfma_f32_16x16x32_bf16 v[68:71], v[172:175], v[232:235], v[68:71]
	v_mfma_f32_16x16x32_bf16 v[32:35], v[136:139], v[236:239], v[32:35]
	v_mfma_f32_16x16x32_bf16 v[32:35], v[140:143], v[240:243], v[32:35]
	v_mfma_f32_16x16x32_bf16 v[28:31], v[144:147], v[236:239], v[28:31]
	v_mfma_f32_16x16x32_bf16 v[28:31], v[172:175], v[240:243], v[28:31]
	s_setprio 0
	s_setprio 1
	v_mfma_f32_16x16x32_bf16 v[120:123], v[176:179], v[212:215], v[120:123]
	v_mfma_f32_16x16x32_bf16 v[120:123], v[180:183], v[216:219], v[120:123]
	v_mfma_f32_16x16x32_bf16 v[116:119], v[184:187], v[212:215], v[116:119]
	v_mfma_f32_16x16x32_bf16 v[116:119], v[208:211], v[216:219], v[116:119]
	v_mfma_f32_16x16x32_bf16 v[84:87], v[176:179], v[220:223], v[84:87]
	v_mfma_f32_16x16x32_bf16 v[84:87], v[180:183], v[224:227], v[84:87]
	v_mfma_f32_16x16x32_bf16 v[80:83], v[184:187], v[220:223], v[80:83]
	v_mfma_f32_16x16x32_bf16 v[80:83], v[208:211], v[224:227], v[80:83]
	v_mfma_f32_16x16x32_bf16 v[48:51], v[176:179], v[228:231], v[48:51]
	v_mfma_f32_16x16x32_bf16 v[48:51], v[180:183], v[232:235], v[48:51]
	v_mfma_f32_16x16x32_bf16 v[44:47], v[184:187], v[228:231], v[44:47]
	v_mfma_f32_16x16x32_bf16 v[44:47], v[208:211], v[232:235], v[44:47]
	v_mfma_f32_16x16x32_bf16 v[24:27], v[176:179], v[236:239], v[24:27]
	v_mfma_f32_16x16x32_bf16 v[24:27], v[180:183], v[240:243], v[24:27]
	s_setprio 2
	s_barrier
; #define PG8_STAGE(bufoff, gbase, voff) do { _Pragma("unroll") for (int _i = 0; _i < 2; ++_i) \
;         __builtin_amdgcn_global_load_lds((const unsigned*)((const char*)(gbase) + (voff)[_i]), (LAS unsigned*)(lds + (bufoff) + ldsw + _i * 8192), 16, 0, 0); } while (0)
; #define PG8_LDA(dst, b, h) do { _Pragma("unroll") for (int m = 0; m < 4; ++m) _Pragma("unroll") for (int k = 0; k < 2; ++k) dst[m][k] = *(const LAS bf16x8*)(lds + PG8_SA(b, h) + aoff + m * 2048 + k * 1024); } while (0)
; #define PG8_LDB(dst, b, h) do { _Pragma("unroll") for (int n = 0; n < 2; ++n) _Pragma("unroll") for (int k = 0; k < 2; ++k) dst[n][k] = *(const LAS bf16x8*)(lds + PG8_SB(b, h) + boff + n * 2048 + k * 1024); } while (0)
; #define PG8_MMA(ai, bj, At, Bt) do { __builtin_amdgcn_s_setprio(1); _Pragma("unroll") for (int m = 0; m < 4; ++m) _Pragma("unroll") for (int n = 0; n < 2; ++n) _Pragma("unroll") for (int k = 0; k < 2; ++k) \
;         acc[ai][bj][m][n] = __builtin_amdgcn_mfma_f32_16x16x32_bf16(Bt[n][k], At[m][k], acc[ai][bj][m][n], 0, 0, 0); __builtin_amdgcn_s_setprio(0); } while (0)
; #define PG8_WAIT_V(n) asm volatile("s_waitcnt vmcnt(" #n ")" ::: "memory")
; #define PG8_WAIT_L(n) asm volatile("s_waitcnt lgkmcnt(" #n ")" ::: "memory")
; #define PG8_BAR __builtin_amdgcn_s_barrier()
; #define PG8_SCHED __builtin_amdgcn_sched_barrier(0)
; template <class Epi, class Sched, bool ALIGN_EPI = true>
; __device__ __forceinline__ void gemm_phase(LAS unsigned char* lds, const Gemm g, const Sched& S, const Epi& E) {
;     ...
;             PG8_WAIT_V(8); PG8_WAIT_L(0); PG8_BAR; PG8_MMA(1, 0, At, B0); PG8_MMA(1, 1, At, B1); PG8_BAR; PG8_SCHED;
;             PG8_LDB(B0, 1, 0); PG8_LDB(B1, 1, 1); PG8_SCHED; PG8_LDA(At, 1, 0); PG8_STAGE(PG8_SA(0, 1), a2 + hA, voffA);
;             PG8_WAIT_V(8); PG8_WAIT_L(0); PG8_BAR; PG8_MMA(0, 0, At, B0); PG8_MMA(0, 1, At, B1); PG8_BAR; PG8_SCHED;
	v_mfma_f32_16x16x32_bf16 v[20:23], v[184:187], v[236:239], v[20:23]
	v_mfma_f32_16x16x32_bf16 v[20:23], v[208:211], v[240:243], v[20:23]
	s_setprio 0
	s_add_i32 s19, 0, 0x18000
	s_add_i32 s24, 0, 0x1c000
	v_add_u32_e32 v172, s19, v188
	v_add_u32_e32 v207, s24, v188
	ds_read_b128 v[136:139], v172
	ds_read_b128 v[140:143], v172 offset:1024
	ds_read_b128 v[144:147], v172 offset:2048
	ds_read_b128 v[172:175], v172 offset:3072
	ds_read_b128 v[176:179], v207
	ds_read_b128 v[180:183], v207 offset:1024
	ds_read_b128 v[184:187], v207 offset:2048
	ds_read_b128 v[208:211], v207 offset:3072
	s_add_u32 s10, s64, 0x160000
	s_addc_u32 s11, s65, 0
	s_mov_b32 m0, s76
	v_lshl_add_u64 v[248:249], s[10:11], 0, v[0:1]
	ds_read_b128 v[212:215], v197 offset:32768
	ds_read_b128 v[216:219], v197 offset:33792
	ds_read_b128 v[220:223], v197 offset:34816
	ds_read_b128 v[224:227], v197 offset:35840
	ds_read_b128 v[228:231], v197 offset:36864
	ds_read_b128 v[232:235], v197 offset:37888
	ds_read_b128 v[236:239], v197 offset:38912
	ds_read_b128 v[240:243], v197 offset:39936
	global_load_lds_dwordx4 v[248:249], off
	v_lshl_add_u64 v[248:249], s[10:11], 0, v[148:149]
	s_mov_b32 m0, s77
	s_nop 0
	global_load_lds_dwordx4 v[248:249], off
	s_waitcnt vmcnt(8)
	s_waitcnt lgkmcnt(0)
	s_barrier
	s_setprio 1
	s_waitcnt lgkmcnt(0)
	v_mfma_f32_16x16x32_bf16 v[16:19], v[136:139], v[212:215], v[16:19]
	v_mfma_f32_16x16x32_bf16 v[16:19], v[140:143], v[216:219], v[16:19]
	v_mfma_f32_16x16x32_bf16 v[12:15], v[144:147], v[212:215], v[12:15]
	v_mfma_f32_16x16x32_bf16 v[12:15], v[172:175], v[216:219], v[12:15]
	v_mfma_f32_16x16x32_bf16 v[56:59], v[136:139], v[220:223], v[56:59]
	v_mfma_f32_16x16x32_bf16 v[56:59], v[140:143], v[224:227], v[56:59]
	v_mfma_f32_16x16x32_bf16 v[52:55], v[144:147], v[220:223], v[52:55]
	v_mfma_f32_16x16x32_bf16 v[52:55], v[172:175], v[224:227], v[52:55]
	v_mfma_f32_16x16x32_bf16 v[88:91], v[136:139], v[228:231], v[88:91]
	v_mfma_f32_16x16x32_bf16 v[88:91], v[140:143], v[232:235], v[88:91]
	v_mfma_f32_16x16x32_bf16 v[76:79], v[144:147], v[228:231], v[76:79]
	v_mfma_f32_16x16x32_bf16 v[76:79], v[172:175], v[232:235], v[76:79]
	v_mfma_f32_16x16x32_bf16 v[112:115], v[136:139], v[236:239], v[112:115]
	v_mfma_f32_16x16x32_bf16 v[112:115], v[140:143], v[240:243], v[112:115]
	v_mfma_f32_16x16x32_bf16 v[108:111], v[144:147], v[236:239], v[108:111]
	v_mfma_f32_16x16x32_bf16 v[108:111], v[172:175], v[240:243], v[108:111]
	s_setprio 0
	s_setprio 1
	v_mfma_f32_16x16x32_bf16 v[8:11], v[176:179], v[212:215], v[8:11]
	v_mfma_f32_16x16x32_bf16 v[8:11], v[180:183], v[216:219], v[8:11]
	v_mfma_f32_16x16x32_bf16 v[4:7], v[184:187], v[212:215], v[4:7]
	v_mfma_f32_16x16x32_bf16 v[4:7], v[208:211], v[216:219], v[4:7]
	v_mfma_f32_16x16x32_bf16 v[40:43], v[176:179], v[220:223], v[40:43]
	v_mfma_f32_16x16x32_bf16 v[40:43], v[180:183], v[224:227], v[40:43]
	v_mfma_f32_16x16x32_bf16 v[36:39], v[184:187], v[220:223], v[36:39]
	v_mfma_f32_16x16x32_bf16 v[36:39], v[208:211], v[224:227], v[36:39]
	v_mfma_f32_16x16x32_bf16 v[64:67], v[176:179], v[228:231], v[64:67]
	v_mfma_f32_16x16x32_bf16 v[64:67], v[180:183], v[232:235], v[64:67]
	v_mfma_f32_16x16x32_bf16 v[60:63], v[184:187], v[228:231], v[60:63]
	v_mfma_f32_16x16x32_bf16 v[60:63], v[208:211], v[232:235], v[60:63]
	v_mfma_f32_16x16x32_bf16 v[96:99], v[176:179], v[236:239], v[96:99]
	v_mfma_f32_16x16x32_bf16 v[96:99], v[180:183], v[240:243], v[96:99]
	s_setprio 2
	s_barrier
; #define PG8_STAGE(bufoff, gbase, voff) do { _Pragma("unroll") for (int _i = 0; _i < 2; ++_i) \
;         __builtin_amdgcn_global_load_lds((const unsigned*)((const char*)(gbase) + (voff)[_i]), (LAS unsigned*)(lds + (bufoff) + ldsw + _i * 8192), 16, 0, 0); } while (0)
; #define PG8_LDA(dst, b, h) do { _Pragma("unroll") for (int m = 0; m < 4; ++m) _Pragma("unroll") for (int k = 0; k < 2; ++k) dst[m][k] = *(const LAS bf16x8*)(lds + PG8_SA(b, h) + aoff + m * 2048 + k * 1024); } while (0)
; #define PG8_LDB(dst, b, h) do { _Pragma("unroll") for (int n = 0; n < 2; ++n) _Pragma("unroll") for (int k = 0; k < 2; ++k) dst[n][k] = *(const LAS bf16x8*)(lds + PG8_SB(b, h) + boff + n * 2048 + k * 1024); } while (0)
; #define PG8_WAIT_V(n) asm volatile("s_waitcnt vmcnt(" #n ")" ::: "memory")
; #define PG8_BAR __builtin_amdgcn_s_barrier()
; template <class Epi, class Sched, bool ALIGN_EPI = true>
; __device__ __forceinline__ void gemm_phase(LAS unsigned char* lds, const Gemm g, const Sched& S, const Epi& E) {
;     ...
;         for (int t = 0; t < nt; t += 2) {
;             const bool last = (t == nt - 2);
;             const char* a1 = cA + (size_t)(t + 1) * kstep;
;             const char* a2 = last ? nA : cA + (size_t)(t + 2) * kstep; const char* b2 = last ? nB : cB + (size_t)(t + 2) * kstep;
;             const char* a3 = a2 + kstep; const char* b3 = b2 + kstep;
;             PG8_LDB(B0, 0, 0); PG8_LDB(B1, 0, 1); PG8_SCHED; PG8_LDA(At, 0, 0); PG8_STAGE(PG8_SA(1, 1), a1 + hA, voffA);
;             PG8_WAIT_V(8); PG8_WAIT_L(0); PG8_BAR; PG8_MMA(0, 0, At, B0); PG8_MMA(0, 1, At, B1); PG8_BAR; PG8_SCHED;
;             PG8_LDA(At, 0, 1); PG8_STAGE(PG8_SB(0, 0), b2, voffB); PG8_STAGE(PG8_SB(0, 1), b2 + hB, voffB); PG8_STAGE(PG8_SA(0, 0), a2, voffA);
;             PG8_WAIT_V(8); PG8_WAIT_L(0); PG8_BAR; PG8_MMA(1, 0, At, B0); PG8_MMA(1, 1, At, B1); PG8_BAR; PG8_SCHED;
;             PG8_LDB(B0, 1, 0); PG8_LDB(B1, 1, 1); PG8_SCHED; PG8_LDA(At, 1, 0); PG8_STAGE(PG8_SA(0, 1), a2 + hA, voffA);
;             PG8_WAIT_V(8); PG8_WAIT_L(0); PG8_BAR; PG8_MMA(0, 0, At, B0); PG8_MMA(0, 1, At, B1); PG8_BAR; PG8_SCHED;
;             PG8_LDA(At, 1, 1); PG8_STAGE(PG8_SB(1, 0), b3, voffB); PG8_STAGE(PG8_SB(1, 1), b3 + hB, voffB); PG8_STAGE(PG8_SA(1, 0), a3, voffA);
;             PG8_WAIT_V(8); PG8_WAIT_L(0); PG8_BAR; PG8_MMA(1, 0, At, B0); PG8_MMA(1, 1, At, B1); PG8_BAR; PG8_SCHED;
	v_mfma_f32_16x16x32_bf16 v[92:95], v[184:187], v[236:239], v[92:95]
	v_mfma_f32_16x16x32_bf16 v[92:95], v[208:211], v[240:243], v[92:95]
	s_setprio 0
	s_add_i32 s10, s19, s66
	v_lshl_add_u64 v[160:161], v[160:161], 0, s[86:87]
	s_mov_b32 m0, s10
	s_nop 0
	global_load_lds_dwordx4 v[160:161], off
	s_add_i32 m0, s10, 0x2000
	s_add_u32 s10, s62, 0x160080
	v_lshl_add_u64 v[160:161], v[162:163], 0, s[86:87]
	s_addc_u32 s11, s63, 0
	s_add_i32 s19, s24, s66
	global_load_lds_dwordx4 v[160:161], off
	v_lshl_add_u64 v[160:161], s[10:11], 0, v[2:3]
	s_mov_b32 m0, s19
	s_nop 0
	global_load_lds_dwordx4 v[160:161], off
	v_lshl_add_u64 v[160:161], s[10:11], 0, v[150:151]
	s_add_i32 m0, s19, 0x2000
	s_nop 0
	global_load_lds_dwordx4 v[160:161], off
	v_lshl_add_u64 v[160:161], v[244:245], 0, s[86:87]
	s_mov_b32 m0, s80
	s_nop 0
	global_load_lds_dwordx4 v[160:161], off
	v_lshl_add_u64 v[160:161], v[246:247], 0, s[86:87]
	s_mov_b32 m0, s81
	s_nop 0
	global_load_lds_dwordx4 v[160:161], off
	ds_read_b128 v[212:215], v197 offset:49152
	ds_read_b128 v[216:219], v197 offset:50176
	ds_read_b128 v[220:223], v197 offset:51200
	ds_read_b128 v[224:227], v197 offset:52224
	ds_read_b128 v[228:231], v197 offset:53248
	ds_read_b128 v[232:235], v197 offset:54272
	ds_read_b128 v[236:239], v197 offset:55296
	ds_read_b128 v[240:243], v197 offset:56320
	s_waitcnt vmcnt(8)
	s_waitcnt lgkmcnt(0)
	s_barrier
	s_setprio 1
	s_waitcnt lgkmcnt(0)
	v_mfma_f32_16x16x32_bf16 v[128:131], v[136:139], v[212:215], v[128:131]
	v_mfma_f32_16x16x32_bf16 v[128:131], v[140:143], v[216:219], v[128:131]
	v_mfma_f32_16x16x32_bf16 v[124:127], v[144:147], v[212:215], v[124:127]
	v_mfma_f32_16x16x32_bf16 v[124:127], v[172:175], v[216:219], v[124:127]
	v_mfma_f32_16x16x32_bf16 v[104:107], v[136:139], v[220:223], v[104:107]
	v_mfma_f32_16x16x32_bf16 v[104:107], v[140:143], v[224:227], v[104:107]
	v_mfma_f32_16x16x32_bf16 v[100:103], v[144:147], v[220:223], v[100:103]
	v_mfma_f32_16x16x32_bf16 v[100:103], v[172:175], v[224:227], v[100:103]
	v_mfma_f32_16x16x32_bf16 v[72:75], v[136:139], v[228:231], v[72:75]
	v_mfma_f32_16x16x32_bf16 v[72:75], v[140:143], v[232:235], v[72:75]
	v_mfma_f32_16x16x32_bf16 v[68:71], v[144:147], v[228:231], v[68:71]
	v_mfma_f32_16x16x32_bf16 v[68:71], v[172:175], v[232:235], v[68:71]
	v_mfma_f32_16x16x32_bf16 v[32:35], v[136:139], v[236:239], v[32:35]
	v_mfma_f32_16x16x32_bf16 v[32:35], v[140:143], v[240:243], v[32:35]
	v_mfma_f32_16x16x32_bf16 v[28:31], v[144:147], v[236:239], v[28:31]
	v_mfma_f32_16x16x32_bf16 v[28:31], v[172:175], v[240:243], v[28:31]
	s_setprio 0
	s_setprio 1
	v_mfma_f32_16x16x32_bf16 v[120:123], v[176:179], v[212:215], v[120:123]
	v_mfma_f32_16x16x32_bf16 v[120:123], v[180:183], v[216:219], v[120:123]
	v_mfma_f32_16x16x32_bf16 v[116:119], v[184:187], v[212:215], v[116:119]
	v_mfma_f32_16x16x32_bf16 v[116:119], v[208:211], v[216:219], v[116:119]
	v_mfma_f32_16x16x32_bf16 v[84:87], v[176:179], v[220:223], v[84:87]
	v_mfma_f32_16x16x32_bf16 v[84:87], v[180:183], v[224:227], v[84:87]
	v_mfma_f32_16x16x32_bf16 v[80:83], v[184:187], v[220:223], v[80:83]
	v_mfma_f32_16x16x32_bf16 v[80:83], v[208:211], v[224:227], v[80:83]
	v_mfma_f32_16x16x32_bf16 v[48:51], v[176:179], v[228:231], v[48:51]
	v_mfma_f32_16x16x32_bf16 v[48:51], v[180:183], v[232:235], v[48:51]
	v_mfma_f32_16x16x32_bf16 v[44:47], v[184:187], v[228:231], v[44:47]
	v_mfma_f32_16x16x32_bf16 v[44:47], v[208:211], v[232:235], v[44:47]
	v_mfma_f32_16x16x32_bf16 v[24:27], v[176:179], v[236:239], v[24:27]
	v_mfma_f32_16x16x32_bf16 v[24:27], v[180:183], v[240:243], v[24:27]
	s_setprio 2
	s_barrier
	v_mfma_f32_16x16x32_bf16 v[20:23], v[184:187], v[236:239], v[20:23]
	v_mfma_f32_16x16x32_bf16 v[20:23], v[208:211], v[240:243], v[20:23]
	s_setprio 0
	s_add_i32 s18, s18, 2
	s_cmpk_gt_u32 s18, 0x55
	s_mov_b64 s[10:11], vcc
	s_cbranch_scc0 .LBB0_1111
